# GEMM main loops: two of the six LDS-DMA issues of the second super-phase moved into the following load segment (4+4 instead of 2+6), counted wait adjusted
# speedup vs baseline: 1.0109x; 1.0109x over previous
.LBB0_472:
	ds_read_b128 v[152:155], v148
	ds_read_b128 v[156:159], v148 offset:1024
	ds_read_b128 v[166:169], v148 offset:2048
	ds_read_b128 v[170:173], v148 offset:3072
	ds_read_b128 v[174:177], v149
	ds_read_b128 v[178:181], v149 offset:1024
	ds_read_b128 v[182:185], v149 offset:2048
	ds_read_b128 v[186:189], v149 offset:3072
	s_add_u32 s44, s54, 0xfff00080
	s_addc_u32 s56, s55, -1
	s_cmp_eq_u32 s72, 60
	s_cselect_b32 s59, s17, s56
	s_cselect_b32 s58, s68, s44
	s_cselect_b32 s57, s15, s71
	s_cselect_b32 s56, s69, s70
	v_lshl_add_u64 v[160:161], s[54:55], 0, v[138:139]
	s_add_i32 m0, s41, 0xc000
	ds_read_b128 v[190:193], v150
	ds_read_b128 v[194:197], v150 offset:1024
	ds_read_b128 v[198:201], v150 offset:2048
	ds_read_b128 v[202:205], v150 offset:3072
	ds_read_b128 v[206:209], v150 offset:4096
	ds_read_b128 v[210:213], v150 offset:5120
	ds_read_b128 v[214:217], v150 offset:6144
	ds_read_b128 v[218:221], v150 offset:7168
	global_load_lds_dwordx4 v[160:161], off
	v_lshl_add_u64 v[160:161], s[54:55], 0, v[140:141]
	s_add_i32 m0, s41, 0xe000
	s_nop 0
	global_load_lds_dwordx4 v[160:161], off
	s_waitcnt vmcnt(8)
	s_waitcnt lgkmcnt(0)
	s_barrier
	s_setprio 1
	s_waitcnt lgkmcnt(0)
	v_mfma_f32_16x16x32_bf16 v[126:129], v[152:155], v[190:193], v[126:129]
	v_mfma_f32_16x16x32_bf16 v[122:125], v[166:169], v[190:193], v[122:125]
	v_mfma_f32_16x16x32_bf16 v[118:121], v[152:155], v[198:201], v[118:121]
	v_mfma_f32_16x16x32_bf16 v[110:113], v[166:169], v[198:201], v[110:113]
	v_mfma_f32_16x16x32_bf16 v[102:105], v[152:155], v[206:209], v[102:105]
	v_mfma_f32_16x16x32_bf16 v[94:97], v[166:169], v[206:209], v[94:97]
	v_mfma_f32_16x16x32_bf16 v[86:89], v[152:155], v[214:217], v[86:89]
	v_mfma_f32_16x16x32_bf16 v[78:81], v[166:169], v[214:217], v[78:81]
	v_mfma_f32_16x16x32_bf16 v[126:129], v[156:159], v[194:197], v[126:129]
	v_mfma_f32_16x16x32_bf16 v[122:125], v[170:173], v[194:197], v[122:125]
	v_mfma_f32_16x16x32_bf16 v[118:121], v[156:159], v[202:205], v[118:121]
	v_mfma_f32_16x16x32_bf16 v[110:113], v[170:173], v[202:205], v[110:113]
	v_mfma_f32_16x16x32_bf16 v[102:105], v[156:159], v[210:213], v[102:105]
	v_mfma_f32_16x16x32_bf16 v[94:97], v[170:173], v[210:213], v[94:97]
	v_mfma_f32_16x16x32_bf16 v[86:89], v[156:159], v[218:221], v[86:89]
	v_mfma_f32_16x16x32_bf16 v[78:81], v[170:173], v[218:221], v[78:81]
	s_setprio 0
	s_setprio 1
	v_mfma_f32_16x16x32_bf16 v[114:117], v[174:177], v[190:193], v[114:117]
	v_mfma_f32_16x16x32_bf16 v[106:109], v[182:185], v[190:193], v[106:109]
	v_mfma_f32_16x16x32_bf16 v[98:101], v[174:177], v[198:201], v[98:101]
	v_mfma_f32_16x16x32_bf16 v[90:93], v[182:185], v[198:201], v[90:93]
	v_mfma_f32_16x16x32_bf16 v[82:85], v[174:177], v[206:209], v[82:85]
	v_mfma_f32_16x16x32_bf16 v[74:77], v[182:185], v[206:209], v[74:77]
	v_mfma_f32_16x16x32_bf16 v[70:73], v[174:177], v[214:217], v[70:73]
	v_mfma_f32_16x16x32_bf16 v[66:69], v[182:185], v[214:217], v[66:69]
	v_mfma_f32_16x16x32_bf16 v[114:117], v[178:181], v[194:197], v[114:117]
	v_mfma_f32_16x16x32_bf16 v[106:109], v[186:189], v[194:197], v[106:109]
	v_mfma_f32_16x16x32_bf16 v[98:101], v[178:181], v[202:205], v[98:101]
	v_mfma_f32_16x16x32_bf16 v[90:93], v[186:189], v[202:205], v[90:93]
	v_mfma_f32_16x16x32_bf16 v[82:85], v[178:181], v[210:213], v[82:85]
	v_mfma_f32_16x16x32_bf16 v[74:77], v[186:189], v[210:213], v[74:77]
	v_mfma_f32_16x16x32_bf16 v[70:73], v[178:181], v[218:221], v[70:73]
	v_mfma_f32_16x16x32_bf16 v[66:69], v[186:189], v[218:221], v[66:69]
	s_setprio 0
	s_barrier
	s_add_i32 s44, s64, s27
	v_lshl_add_u64 v[160:161], s[56:57], 0, v[134:135]
	s_mov_b32 m0, s44
	ds_read_b128 v[190:193], v150 offset:16384
	ds_read_b128 v[194:197], v150 offset:17408
	ds_read_b128 v[198:201], v150 offset:18432
	ds_read_b128 v[202:205], v150 offset:19456
	ds_read_b128 v[206:209], v150 offset:20480
	ds_read_b128 v[210:213], v150 offset:21504
	ds_read_b128 v[214:217], v150 offset:22528
	ds_read_b128 v[218:221], v150 offset:23552
	global_load_lds_dwordx4 v[160:161], off
	s_add_i32 m0, s44, 0x2000
	s_add_u32 s74, s56, 0x100000
	v_lshl_add_u64 v[222:223], s[56:57], 0, v[130:131]
	s_addc_u32 s75, s57, 0
	s_add_i32 s44, s65, s27
	global_load_lds_dwordx4 v[222:223], off
	v_lshl_add_u64 v[224:225], s[74:75], 0, v[134:135]
	s_mov_b32 m0, s44
	v_lshl_add_u64 v[226:227], s[58:59], 0, v[132:133]
	global_load_lds_dwordx4 v[224:225], off
	v_lshl_add_u64 v[224:225], s[74:75], 0, v[130:131]
	s_add_i32 m0, s44, 0x2000
	s_nop 0
	global_load_lds_dwordx4 v[224:225], off
	s_waitcnt vmcnt(6)
	s_waitcnt lgkmcnt(0)
	s_barrier
	s_setprio 1
	s_waitcnt lgkmcnt(0)
	v_mfma_f32_16x16x32_bf16 v[62:65], v[152:155], v[190:193], v[62:65]
	v_mfma_f32_16x16x32_bf16 v[58:61], v[166:169], v[190:193], v[58:61]
	v_mfma_f32_16x16x32_bf16 v[54:57], v[152:155], v[198:201], v[54:57]
	v_mfma_f32_16x16x32_bf16 v[46:49], v[166:169], v[198:201], v[46:49]
	v_mfma_f32_16x16x32_bf16 v[38:41], v[152:155], v[206:209], v[38:41]
	v_mfma_f32_16x16x32_bf16 v[30:33], v[166:169], v[206:209], v[30:33]
	v_mfma_f32_16x16x32_bf16 v[22:25], v[152:155], v[214:217], v[22:25]
	v_mfma_f32_16x16x32_bf16 v[14:17], v[166:169], v[214:217], v[14:17]
	v_mfma_f32_16x16x32_bf16 v[62:65], v[156:159], v[194:197], v[62:65]
	v_mfma_f32_16x16x32_bf16 v[58:61], v[170:173], v[194:197], v[58:61]
	v_mfma_f32_16x16x32_bf16 v[54:57], v[156:159], v[202:205], v[54:57]
	v_mfma_f32_16x16x32_bf16 v[46:49], v[170:173], v[202:205], v[46:49]
	v_mfma_f32_16x16x32_bf16 v[38:41], v[156:159], v[210:213], v[38:41]
	v_mfma_f32_16x16x32_bf16 v[30:33], v[170:173], v[210:213], v[30:33]
	v_mfma_f32_16x16x32_bf16 v[22:25], v[156:159], v[218:221], v[22:25]
	v_mfma_f32_16x16x32_bf16 v[14:17], v[170:173], v[218:221], v[14:17]
	s_setprio 0
	s_setprio 1
	v_mfma_f32_16x16x32_bf16 v[50:53], v[174:177], v[190:193], v[50:53]
	v_mfma_f32_16x16x32_bf16 v[42:45], v[182:185], v[190:193], v[42:45]
	v_mfma_f32_16x16x32_bf16 v[34:37], v[174:177], v[198:201], v[34:37]
	v_mfma_f32_16x16x32_bf16 v[26:29], v[182:185], v[198:201], v[26:29]
	v_mfma_f32_16x16x32_bf16 v[18:21], v[174:177], v[206:209], v[18:21]
	v_mfma_f32_16x16x32_bf16 v[10:13], v[182:185], v[206:209], v[10:13]
	v_mfma_f32_16x16x32_bf16 v[6:9], v[174:177], v[214:217], v[6:9]
	v_mfma_f32_16x16x32_bf16 v[2:5], v[182:185], v[214:217], v[2:5]
	v_mfma_f32_16x16x32_bf16 v[50:53], v[178:181], v[194:197], v[50:53]
	v_mfma_f32_16x16x32_bf16 v[42:45], v[186:189], v[194:197], v[42:45]
	v_mfma_f32_16x16x32_bf16 v[34:37], v[178:181], v[202:205], v[34:37]
	v_mfma_f32_16x16x32_bf16 v[26:29], v[186:189], v[202:205], v[26:29]
	v_mfma_f32_16x16x32_bf16 v[18:21], v[178:181], v[210:213], v[18:21]
	v_mfma_f32_16x16x32_bf16 v[10:13], v[186:189], v[210:213], v[10:13]
	v_mfma_f32_16x16x32_bf16 v[6:9], v[178:181], v[218:221], v[6:9]
	v_mfma_f32_16x16x32_bf16 v[2:5], v[186:189], v[218:221], v[2:5]
	s_setprio 0
	s_barrier
	s_add_i32 s44, 0, 0x18000
	v_add_u32_e32 v151, s44, v146
	s_add_i32 s73, 0, 0x1c000
	ds_read_b128 v[152:155], v151
	ds_read_b128 v[156:159], v151 offset:1024
	ds_read_b128 v[166:169], v151 offset:2048
	ds_read_b128 v[170:173], v151 offset:3072
	v_add_u32_e32 v151, s73, v146
	ds_read_b128 v[174:177], v151
	ds_read_b128 v[178:181], v151 offset:1024
	ds_read_b128 v[182:185], v151 offset:2048
	ds_read_b128 v[186:189], v151 offset:3072
	v_lshl_add_u64 v[224:225], s[58:59], 0, v[136:137]
	s_mov_b32 m0, s41
	s_nop 0
	global_load_lds_dwordx4 v[224:225], off
	s_mov_b32 m0, s43
	s_nop 0
	global_load_lds_dwordx4 v[226:227], off
	s_add_u32 s58, s58, 0x100000
	s_addc_u32 s59, s59, 0
	s_mov_b32 m0, s45
	v_lshl_add_u64 v[228:229], s[58:59], 0, v[136:137]
	ds_read_b128 v[190:193], v150 offset:32768
	ds_read_b128 v[194:197], v150 offset:33792
	ds_read_b128 v[198:201], v150 offset:34816
	ds_read_b128 v[202:205], v150 offset:35840
	ds_read_b128 v[206:209], v150 offset:36864
	ds_read_b128 v[210:213], v150 offset:37888
	ds_read_b128 v[214:217], v150 offset:38912
	ds_read_b128 v[218:221], v150 offset:39936
	global_load_lds_dwordx4 v[228:229], off
	v_lshl_add_u64 v[228:229], s[58:59], 0, v[132:133]
	s_mov_b32 m0, s53
	s_nop 0
	global_load_lds_dwordx4 v[228:229], off
	s_waitcnt vmcnt(8)
	s_waitcnt lgkmcnt(0)
	s_barrier
	s_setprio 1
	s_waitcnt lgkmcnt(0)
	v_mfma_f32_16x16x32_bf16 v[126:129], v[152:155], v[190:193], v[126:129]
	v_mfma_f32_16x16x32_bf16 v[122:125], v[166:169], v[190:193], v[122:125]
	v_mfma_f32_16x16x32_bf16 v[118:121], v[152:155], v[198:201], v[118:121]
	v_mfma_f32_16x16x32_bf16 v[110:113], v[166:169], v[198:201], v[110:113]
	v_mfma_f32_16x16x32_bf16 v[102:105], v[152:155], v[206:209], v[102:105]
	v_mfma_f32_16x16x32_bf16 v[94:97], v[166:169], v[206:209], v[94:97]
	v_mfma_f32_16x16x32_bf16 v[86:89], v[152:155], v[214:217], v[86:89]
	v_mfma_f32_16x16x32_bf16 v[78:81], v[166:169], v[214:217], v[78:81]
	v_mfma_f32_16x16x32_bf16 v[126:129], v[156:159], v[194:197], v[126:129]
	v_mfma_f32_16x16x32_bf16 v[122:125], v[170:173], v[194:197], v[122:125]
	v_mfma_f32_16x16x32_bf16 v[118:121], v[156:159], v[202:205], v[118:121]
	v_mfma_f32_16x16x32_bf16 v[110:113], v[170:173], v[202:205], v[110:113]
	v_mfma_f32_16x16x32_bf16 v[102:105], v[156:159], v[210:213], v[102:105]
	v_mfma_f32_16x16x32_bf16 v[94:97], v[170:173], v[210:213], v[94:97]
	v_mfma_f32_16x16x32_bf16 v[86:89], v[156:159], v[218:221], v[86:89]
	v_mfma_f32_16x16x32_bf16 v[78:81], v[170:173], v[218:221], v[78:81]
	s_setprio 0
	s_setprio 1
	v_mfma_f32_16x16x32_bf16 v[114:117], v[174:177], v[190:193], v[114:117]
	v_mfma_f32_16x16x32_bf16 v[106:109], v[182:185], v[190:193], v[106:109]
	v_mfma_f32_16x16x32_bf16 v[98:101], v[174:177], v[198:201], v[98:101]
	v_mfma_f32_16x16x32_bf16 v[90:93], v[182:185], v[198:201], v[90:93]
	v_mfma_f32_16x16x32_bf16 v[82:85], v[174:177], v[206:209], v[82:85]
	v_mfma_f32_16x16x32_bf16 v[74:77], v[182:185], v[206:209], v[74:77]
	v_mfma_f32_16x16x32_bf16 v[70:73], v[174:177], v[214:217], v[70:73]
	v_mfma_f32_16x16x32_bf16 v[66:69], v[182:185], v[214:217], v[66:69]
	v_mfma_f32_16x16x32_bf16 v[114:117], v[178:181], v[194:197], v[114:117]
	v_mfma_f32_16x16x32_bf16 v[106:109], v[186:189], v[194:197], v[106:109]
	v_mfma_f32_16x16x32_bf16 v[98:101], v[178:181], v[202:205], v[98:101]
	v_mfma_f32_16x16x32_bf16 v[90:93], v[186:189], v[202:205], v[90:93]
	v_mfma_f32_16x16x32_bf16 v[82:85], v[178:181], v[210:213], v[82:85]
	v_mfma_f32_16x16x32_bf16 v[74:77], v[186:189], v[210:213], v[74:77]
	v_mfma_f32_16x16x32_bf16 v[70:73], v[178:181], v[218:221], v[70:73]
	v_mfma_f32_16x16x32_bf16 v[66:69], v[186:189], v[218:221], v[66:69]
	s_setprio 0
	s_barrier
	s_add_i32 s44, s44, s27
	v_lshl_add_u64 v[160:161], v[160:161], 0, s[10:11]
	s_mov_b32 m0, s44
	ds_read_b128 v[190:193], v150 offset:49152
	ds_read_b128 v[194:197], v150 offset:50176
	ds_read_b128 v[198:201], v150 offset:51200
	ds_read_b128 v[202:205], v150 offset:52224
	ds_read_b128 v[206:209], v150 offset:53248
	ds_read_b128 v[210:213], v150 offset:54272
	ds_read_b128 v[214:217], v150 offset:55296
	ds_read_b128 v[218:221], v150 offset:56320
	global_load_lds_dwordx4 v[160:161], off
	s_add_i32 m0, s44, 0x2000
	s_add_u32 s56, s56, 0x100080
	v_lshl_add_u64 v[160:161], v[222:223], 0, s[10:11]
	s_addc_u32 s57, s57, 0
	s_add_i32 s44, s73, s27
	global_load_lds_dwordx4 v[160:161], off
	v_lshl_add_u64 v[160:161], s[56:57], 0, v[134:135]
	s_mov_b32 m0, s44
	s_nop 0
	global_load_lds_dwordx4 v[160:161], off
	v_lshl_add_u64 v[160:161], s[56:57], 0, v[130:131]
	s_add_i32 m0, s44, 0x2000
	s_nop 0
	global_load_lds_dwordx4 v[160:161], off
	v_lshl_add_u64 v[160:161], v[224:225], 0, s[10:11]
	s_mov_b32 m0, s61
	s_nop 0
	global_load_lds_dwordx4 v[160:161], off
	v_lshl_add_u64 v[160:161], v[226:227], 0, s[10:11]
	s_mov_b32 m0, s62
	s_nop 0
	global_load_lds_dwordx4 v[160:161], off
	s_waitcnt vmcnt(8)
	s_waitcnt lgkmcnt(0)
	s_barrier
	s_setprio 1
	s_waitcnt lgkmcnt(0)
	v_mfma_f32_16x16x32_bf16 v[62:65], v[152:155], v[190:193], v[62:65]
	v_mfma_f32_16x16x32_bf16 v[58:61], v[166:169], v[190:193], v[58:61]
	v_mfma_f32_16x16x32_bf16 v[54:57], v[152:155], v[198:201], v[54:57]
	v_mfma_f32_16x16x32_bf16 v[46:49], v[166:169], v[198:201], v[46:49]
	v_mfma_f32_16x16x32_bf16 v[38:41], v[152:155], v[206:209], v[38:41]
	v_mfma_f32_16x16x32_bf16 v[30:33], v[166:169], v[206:209], v[30:33]
	v_mfma_f32_16x16x32_bf16 v[22:25], v[152:155], v[214:217], v[22:25]
	v_mfma_f32_16x16x32_bf16 v[14:17], v[166:169], v[214:217], v[14:17]
	v_mfma_f32_16x16x32_bf16 v[62:65], v[156:159], v[194:197], v[62:65]
	v_mfma_f32_16x16x32_bf16 v[58:61], v[170:173], v[194:197], v[58:61]
	v_mfma_f32_16x16x32_bf16 v[54:57], v[156:159], v[202:205], v[54:57]
	v_mfma_f32_16x16x32_bf16 v[46:49], v[170:173], v[202:205], v[46:49]
	v_mfma_f32_16x16x32_bf16 v[38:41], v[156:159], v[210:213], v[38:41]
	v_mfma_f32_16x16x32_bf16 v[30:33], v[170:173], v[210:213], v[30:33]
	v_mfma_f32_16x16x32_bf16 v[22:25], v[156:159], v[218:221], v[22:25]
	v_mfma_f32_16x16x32_bf16 v[14:17], v[170:173], v[218:221], v[14:17]
	s_setprio 0
	s_setprio 1
	v_mfma_f32_16x16x32_bf16 v[50:53], v[174:177], v[190:193], v[50:53]
	v_mfma_f32_16x16x32_bf16 v[42:45], v[182:185], v[190:193], v[42:45]
	v_mfma_f32_16x16x32_bf16 v[34:37], v[174:177], v[198:201], v[34:37]
	v_mfma_f32_16x16x32_bf16 v[26:29], v[182:185], v[198:201], v[26:29]
	v_mfma_f32_16x16x32_bf16 v[18:21], v[174:177], v[206:209], v[18:21]
	v_mfma_f32_16x16x32_bf16 v[10:13], v[182:185], v[206:209], v[10:13]
	v_mfma_f32_16x16x32_bf16 v[6:9], v[174:177], v[214:217], v[6:9]
	v_mfma_f32_16x16x32_bf16 v[2:5], v[182:185], v[214:217], v[2:5]
	v_mfma_f32_16x16x32_bf16 v[50:53], v[178:181], v[194:197], v[50:53]
	v_mfma_f32_16x16x32_bf16 v[42:45], v[186:189], v[194:197], v[42:45]
	v_mfma_f32_16x16x32_bf16 v[34:37], v[178:181], v[202:205], v[34:37]
	v_mfma_f32_16x16x32_bf16 v[26:29], v[186:189], v[202:205], v[26:29]
	v_mfma_f32_16x16x32_bf16 v[18:21], v[178:181], v[210:213], v[18:21]
	v_mfma_f32_16x16x32_bf16 v[10:13], v[186:189], v[210:213], v[10:13]
	v_mfma_f32_16x16x32_bf16 v[6:9], v[178:181], v[218:221], v[6:9]
	v_mfma_f32_16x16x32_bf16 v[2:5], v[186:189], v[218:221], v[2:5]
	s_setprio 0
	s_barrier
	s_add_i32 s72, s72, 2
	s_add_u32 s54, s54, 0x100
	s_addc_u32 s55, s55, 0
	s_add_u32 s70, s70, 0x100
	s_addc_u32 s71, s71, 0
	s_cmp_gt_u32 s72, 61
	s_cbranch_scc0 .LBB0_472
	s_and_b64 vcc, exec, s[12:13]
	s_cbranch_vccz .LBB0_475
	s_barrier

.LBB0_706:
	s_add_u32 s72, s60, s44
	s_addc_u32 s73, s61, 0
	s_add_u32 s68, s72, 0x100
	s_addc_u32 s69, s73, 0
	s_and_b64 s[66:67], s[64:65], exec
	s_cselect_b32 s69, s17, s69
	s_cselect_b32 s68, s86, s68
	s_add_u32 s44, s56, s44
	s_addc_u32 s66, s57, 0
	s_add_u32 s44, s44, 0x100
	s_addc_u32 s66, s66, 0
	s_and_b64 s[64:65], s[64:65], exec
	s_cselect_b32 s71, s15, s66
	s_cselect_b32 s70, s87, s44
	s_add_u32 s74, s72, 0x10080
	s_addc_u32 s75, s73, 0
	s_add_i32 vcc_hi, s82, s27
	ds_read_b128 v[150:153], v147
	ds_read_b128 v[154:157], v147 offset:1024
	ds_read_b128 v[158:161], v147 offset:2048
	ds_read_b128 v[166:169], v147 offset:3072
	ds_read_b128 v[170:173], v148
	ds_read_b128 v[174:177], v148 offset:1024
	ds_read_b128 v[178:181], v148 offset:2048
	ds_read_b128 v[182:185], v148 offset:3072
	s_add_i32 m0, s36, 0xc000
	s_add_i32 s45, s36, 0xe000
	s_add_i32 s96, vcc_hi, 0x2000
	s_add_u32 s72, s70, 0x10000
	s_addc_u32 s73, s71, 0
	s_add_i32 vcc_lo, s83, s27
	s_add_i32 s97, vcc_lo, 0x2000
	s_add_i32 s95, 0, 0x18000
	s_add_i32 s94, 0, 0x1c000
	s_add_u32 s66, s68, 0x10000
	s_addc_u32 s67, s69, 0
	s_add_i32 s93, s95, s27
	s_add_i32 s89, s93, 0x2000
	s_add_u32 s64, s70, 0x10080
	s_addc_u32 s65, s71, 0
	s_add_i32 s92, s94, s27
	s_add_i32 s44, s92, 0x2000
	v_lshl_add_u64 v[198:199], s[74:75], 0, v[130:131]
	ds_read_b128 v[186:189], v149
	ds_read_b128 v[190:193], v149 offset:1024
	ds_read_b128 v[194:197], v149 offset:2048
	ds_read_b128 v[202:205], v149 offset:3072
	ds_read_b128 v[206:209], v149 offset:4096
	ds_read_b128 v[210:213], v149 offset:5120
	ds_read_b128 v[214:217], v149 offset:6144
	ds_read_b128 v[218:221], v149 offset:7168
	global_load_lds_dwordx4 v[198:199], off
	v_lshl_add_u64 v[198:199], s[74:75], 0, v[134:135]
	s_mov_b32 m0, s45
	s_nop 0
	global_load_lds_dwordx4 v[198:199], off
	s_waitcnt vmcnt(8)
	s_waitcnt lgkmcnt(0)
	s_barrier
	s_setprio 1
	s_waitcnt lgkmcnt(0)
	v_mfma_f32_16x16x32_bf16 v[126:129], v[150:153], v[186:189], v[126:129]
	v_mfma_f32_16x16x32_bf16 v[122:125], v[158:161], v[186:189], v[122:125]
	v_mfma_f32_16x16x32_bf16 v[118:121], v[150:153], v[194:197], v[118:121]
	v_mfma_f32_16x16x32_bf16 v[110:113], v[158:161], v[194:197], v[110:113]
	v_mfma_f32_16x16x32_bf16 v[102:105], v[150:153], v[206:209], v[102:105]
	v_mfma_f32_16x16x32_bf16 v[94:97], v[158:161], v[206:209], v[94:97]
	v_mfma_f32_16x16x32_bf16 v[86:89], v[150:153], v[214:217], v[86:89]
	v_mfma_f32_16x16x32_bf16 v[78:81], v[158:161], v[214:217], v[78:81]
	v_mfma_f32_16x16x32_bf16 v[126:129], v[154:157], v[190:193], v[126:129]
	v_mfma_f32_16x16x32_bf16 v[122:125], v[166:169], v[190:193], v[122:125]
	v_mfma_f32_16x16x32_bf16 v[118:121], v[154:157], v[202:205], v[118:121]
	v_mfma_f32_16x16x32_bf16 v[110:113], v[166:169], v[202:205], v[110:113]
	v_mfma_f32_16x16x32_bf16 v[102:105], v[154:157], v[210:213], v[102:105]
	v_mfma_f32_16x16x32_bf16 v[94:97], v[166:169], v[210:213], v[94:97]
	v_mfma_f32_16x16x32_bf16 v[86:89], v[154:157], v[218:221], v[86:89]
	v_mfma_f32_16x16x32_bf16 v[78:81], v[166:169], v[218:221], v[78:81]
	s_setprio 0
	s_setprio 1
	v_mfma_f32_16x16x32_bf16 v[114:117], v[170:173], v[186:189], v[114:117]
	v_mfma_f32_16x16x32_bf16 v[106:109], v[178:181], v[186:189], v[106:109]
	v_mfma_f32_16x16x32_bf16 v[98:101], v[170:173], v[194:197], v[98:101]
	v_mfma_f32_16x16x32_bf16 v[90:93], v[178:181], v[194:197], v[90:93]
	v_mfma_f32_16x16x32_bf16 v[82:85], v[170:173], v[206:209], v[82:85]
	v_mfma_f32_16x16x32_bf16 v[74:77], v[178:181], v[206:209], v[74:77]
	v_mfma_f32_16x16x32_bf16 v[70:73], v[170:173], v[214:217], v[70:73]
	v_mfma_f32_16x16x32_bf16 v[66:69], v[178:181], v[214:217], v[66:69]
	v_mfma_f32_16x16x32_bf16 v[114:117], v[174:177], v[190:193], v[114:117]
	v_mfma_f32_16x16x32_bf16 v[106:109], v[182:185], v[190:193], v[106:109]
	v_mfma_f32_16x16x32_bf16 v[98:101], v[174:177], v[202:205], v[98:101]
	v_mfma_f32_16x16x32_bf16 v[90:93], v[182:185], v[202:205], v[90:93]
	v_mfma_f32_16x16x32_bf16 v[82:85], v[174:177], v[210:213], v[82:85]
	v_mfma_f32_16x16x32_bf16 v[74:77], v[182:185], v[210:213], v[74:77]
	v_mfma_f32_16x16x32_bf16 v[70:73], v[174:177], v[218:221], v[70:73]
	v_mfma_f32_16x16x32_bf16 v[66:69], v[182:185], v[218:221], v[66:69]
	s_setprio 0
	s_barrier
	s_mov_b32 m0, vcc_hi
	v_lshl_add_u64 v[198:199], s[70:71], 0, v[132:133]
	ds_read_b128 v[186:189], v149 offset:16384
	ds_read_b128 v[190:193], v149 offset:17408
	ds_read_b128 v[194:197], v149 offset:18432
	ds_read_b128 v[202:205], v149 offset:19456
	ds_read_b128 v[206:209], v149 offset:20480
	ds_read_b128 v[210:213], v149 offset:21504
	ds_read_b128 v[214:217], v149 offset:22528
	ds_read_b128 v[218:221], v149 offset:23552
	global_load_lds_dwordx4 v[198:199], off
	v_lshl_add_u64 v[222:223], s[70:71], 0, v[136:137]
	s_mov_b32 m0, s96
	v_lshl_add_u64 v[224:225], s[72:73], 0, v[132:133]
	global_load_lds_dwordx4 v[222:223], off
	s_mov_b32 m0, vcc_lo
	v_lshl_add_u64 v[226:227], s[68:69], 0, v[134:135]
	global_load_lds_dwordx4 v[224:225], off
	v_lshl_add_u64 v[224:225], s[72:73], 0, v[136:137]
	s_mov_b32 m0, s97
	s_nop 0
	global_load_lds_dwordx4 v[224:225], off
	s_waitcnt vmcnt(6)
	s_waitcnt lgkmcnt(0)
	s_barrier
	s_setprio 1
	s_waitcnt lgkmcnt(0)
	v_mfma_f32_16x16x32_bf16 v[62:65], v[150:153], v[186:189], v[62:65]
	v_mfma_f32_16x16x32_bf16 v[58:61], v[158:161], v[186:189], v[58:61]
	v_mfma_f32_16x16x32_bf16 v[54:57], v[150:153], v[194:197], v[54:57]
	v_mfma_f32_16x16x32_bf16 v[46:49], v[158:161], v[194:197], v[46:49]
	v_mfma_f32_16x16x32_bf16 v[38:41], v[150:153], v[206:209], v[38:41]
	v_mfma_f32_16x16x32_bf16 v[30:33], v[158:161], v[206:209], v[30:33]
	v_mfma_f32_16x16x32_bf16 v[22:25], v[150:153], v[214:217], v[22:25]
	v_mfma_f32_16x16x32_bf16 v[14:17], v[158:161], v[214:217], v[14:17]
	v_mfma_f32_16x16x32_bf16 v[62:65], v[154:157], v[190:193], v[62:65]
	v_mfma_f32_16x16x32_bf16 v[58:61], v[166:169], v[190:193], v[58:61]
	v_mfma_f32_16x16x32_bf16 v[54:57], v[154:157], v[202:205], v[54:57]
	v_mfma_f32_16x16x32_bf16 v[46:49], v[166:169], v[202:205], v[46:49]
	v_mfma_f32_16x16x32_bf16 v[38:41], v[154:157], v[210:213], v[38:41]
	v_mfma_f32_16x16x32_bf16 v[30:33], v[166:169], v[210:213], v[30:33]
	v_mfma_f32_16x16x32_bf16 v[22:25], v[154:157], v[218:221], v[22:25]
	v_mfma_f32_16x16x32_bf16 v[14:17], v[166:169], v[218:221], v[14:17]
	s_setprio 0
	s_setprio 1
	v_mfma_f32_16x16x32_bf16 v[50:53], v[170:173], v[186:189], v[50:53]
	v_mfma_f32_16x16x32_bf16 v[42:45], v[178:181], v[186:189], v[42:45]
	v_mfma_f32_16x16x32_bf16 v[34:37], v[170:173], v[194:197], v[34:37]
	v_mfma_f32_16x16x32_bf16 v[26:29], v[178:181], v[194:197], v[26:29]
	v_mfma_f32_16x16x32_bf16 v[18:21], v[170:173], v[206:209], v[18:21]
	v_mfma_f32_16x16x32_bf16 v[10:13], v[178:181], v[206:209], v[10:13]
	v_mfma_f32_16x16x32_bf16 v[6:9], v[170:173], v[214:217], v[6:9]
	v_mfma_f32_16x16x32_bf16 v[2:5], v[178:181], v[214:217], v[2:5]
	v_mfma_f32_16x16x32_bf16 v[50:53], v[174:177], v[190:193], v[50:53]
	v_mfma_f32_16x16x32_bf16 v[42:45], v[182:185], v[190:193], v[42:45]
	v_mfma_f32_16x16x32_bf16 v[34:37], v[174:177], v[202:205], v[34:37]
	v_mfma_f32_16x16x32_bf16 v[26:29], v[182:185], v[202:205], v[26:29]
	v_mfma_f32_16x16x32_bf16 v[18:21], v[174:177], v[210:213], v[18:21]
	v_mfma_f32_16x16x32_bf16 v[10:13], v[182:185], v[210:213], v[10:13]
	v_mfma_f32_16x16x32_bf16 v[6:9], v[174:177], v[218:221], v[6:9]
	v_mfma_f32_16x16x32_bf16 v[2:5], v[182:185], v[218:221], v[2:5]
	s_setprio 0
	s_barrier
	v_add_u32_e32 v166, s95, v145
	v_add_u32_e32 v182, s94, v145
	ds_read_b128 v[150:153], v166
	ds_read_b128 v[154:157], v166 offset:1024
	ds_read_b128 v[158:161], v166 offset:2048
	ds_read_b128 v[166:169], v166 offset:3072
	ds_read_b128 v[170:173], v182
	ds_read_b128 v[174:177], v182 offset:1024
	ds_read_b128 v[178:181], v182 offset:2048
	ds_read_b128 v[182:185], v182 offset:3072
	v_lshl_add_u64 v[224:225], s[68:69], 0, v[130:131]
	s_mov_b32 m0, s36
	s_nop 0
	global_load_lds_dwordx4 v[224:225], off
	s_mov_b32 m0, s55
	s_nop 0
	global_load_lds_dwordx4 v[226:227], off
	s_mov_b32 m0, s76
	v_lshl_add_u64 v[228:229], s[66:67], 0, v[130:131]
	ds_read_b128 v[186:189], v149 offset:32768
	ds_read_b128 v[190:193], v149 offset:33792
	ds_read_b128 v[194:197], v149 offset:34816
	ds_read_b128 v[202:205], v149 offset:35840
	ds_read_b128 v[206:209], v149 offset:36864
	ds_read_b128 v[210:213], v149 offset:37888
	ds_read_b128 v[214:217], v149 offset:38912
	ds_read_b128 v[218:221], v149 offset:39936
	global_load_lds_dwordx4 v[228:229], off
	v_lshl_add_u64 v[228:229], s[66:67], 0, v[134:135]
	s_mov_b32 m0, s77
	s_nop 0
	global_load_lds_dwordx4 v[228:229], off
	s_waitcnt vmcnt(8)
	s_waitcnt lgkmcnt(0)
	s_barrier
	s_setprio 1
	s_waitcnt lgkmcnt(0)
	v_mfma_f32_16x16x32_bf16 v[126:129], v[150:153], v[186:189], v[126:129]
	v_mfma_f32_16x16x32_bf16 v[122:125], v[158:161], v[186:189], v[122:125]
	v_mfma_f32_16x16x32_bf16 v[118:121], v[150:153], v[194:197], v[118:121]
	v_mfma_f32_16x16x32_bf16 v[110:113], v[158:161], v[194:197], v[110:113]
	v_mfma_f32_16x16x32_bf16 v[102:105], v[150:153], v[206:209], v[102:105]
	v_mfma_f32_16x16x32_bf16 v[94:97], v[158:161], v[206:209], v[94:97]
	v_mfma_f32_16x16x32_bf16 v[86:89], v[150:153], v[214:217], v[86:89]
	v_mfma_f32_16x16x32_bf16 v[78:81], v[158:161], v[214:217], v[78:81]
	v_mfma_f32_16x16x32_bf16 v[126:129], v[154:157], v[190:193], v[126:129]
	v_mfma_f32_16x16x32_bf16 v[122:125], v[166:169], v[190:193], v[122:125]
	v_mfma_f32_16x16x32_bf16 v[118:121], v[154:157], v[202:205], v[118:121]
	v_mfma_f32_16x16x32_bf16 v[110:113], v[166:169], v[202:205], v[110:113]
	v_mfma_f32_16x16x32_bf16 v[102:105], v[154:157], v[210:213], v[102:105]
	v_mfma_f32_16x16x32_bf16 v[94:97], v[166:169], v[210:213], v[94:97]
	v_mfma_f32_16x16x32_bf16 v[86:89], v[154:157], v[218:221], v[86:89]
	v_mfma_f32_16x16x32_bf16 v[78:81], v[166:169], v[218:221], v[78:81]
	s_setprio 0
	s_setprio 1
	v_mfma_f32_16x16x32_bf16 v[114:117], v[170:173], v[186:189], v[114:117]
	v_mfma_f32_16x16x32_bf16 v[106:109], v[178:181], v[186:189], v[106:109]
	v_mfma_f32_16x16x32_bf16 v[98:101], v[170:173], v[194:197], v[98:101]
	v_mfma_f32_16x16x32_bf16 v[90:93], v[178:181], v[194:197], v[90:93]
	v_mfma_f32_16x16x32_bf16 v[82:85], v[170:173], v[206:209], v[82:85]
	v_mfma_f32_16x16x32_bf16 v[74:77], v[178:181], v[206:209], v[74:77]
	v_mfma_f32_16x16x32_bf16 v[70:73], v[170:173], v[214:217], v[70:73]
	v_mfma_f32_16x16x32_bf16 v[66:69], v[178:181], v[214:217], v[66:69]
	v_mfma_f32_16x16x32_bf16 v[114:117], v[174:177], v[190:193], v[114:117]
	v_mfma_f32_16x16x32_bf16 v[106:109], v[182:185], v[190:193], v[106:109]
	v_mfma_f32_16x16x32_bf16 v[98:101], v[174:177], v[202:205], v[98:101]
	v_mfma_f32_16x16x32_bf16 v[90:93], v[182:185], v[202:205], v[90:93]
	v_mfma_f32_16x16x32_bf16 v[82:85], v[174:177], v[210:213], v[82:85]
	v_mfma_f32_16x16x32_bf16 v[74:77], v[182:185], v[210:213], v[74:77]
	v_mfma_f32_16x16x32_bf16 v[70:73], v[174:177], v[218:221], v[70:73]
	v_mfma_f32_16x16x32_bf16 v[66:69], v[182:185], v[218:221], v[66:69]
	s_setprio 0
	s_barrier
	s_mov_b32 m0, s93
	v_lshl_add_u64 v[198:199], v[198:199], 0, s[10:11]
	ds_read_b128 v[186:189], v149 offset:49152
	ds_read_b128 v[190:193], v149 offset:50176
	ds_read_b128 v[194:197], v149 offset:51200
	ds_read_b128 v[202:205], v149 offset:52224
	ds_read_b128 v[206:209], v149 offset:53248
	ds_read_b128 v[210:213], v149 offset:54272
	ds_read_b128 v[214:217], v149 offset:55296
	ds_read_b128 v[218:221], v149 offset:56320
	global_load_lds_dwordx4 v[198:199], off
	v_lshl_add_u64 v[198:199], v[222:223], 0, s[10:11]
	s_mov_b32 m0, s89
	s_nop 0
	global_load_lds_dwordx4 v[198:199], off
	v_lshl_add_u64 v[198:199], s[64:65], 0, v[132:133]
	s_mov_b32 m0, s92
	s_nop 0
	global_load_lds_dwordx4 v[198:199], off
	v_lshl_add_u64 v[198:199], s[64:65], 0, v[136:137]
	s_mov_b32 m0, s44
	s_nop 0
	global_load_lds_dwordx4 v[198:199], off
	v_lshl_add_u64 v[198:199], v[224:225], 0, s[10:11]
	s_mov_b32 m0, s79
	s_nop 0
	global_load_lds_dwordx4 v[198:199], off
	v_lshl_add_u64 v[198:199], v[226:227], 0, s[10:11]
	s_mov_b32 m0, s80
	s_nop 0
	global_load_lds_dwordx4 v[198:199], off
	s_waitcnt vmcnt(8)
	s_waitcnt lgkmcnt(0)
	s_barrier
	s_setprio 1
	s_waitcnt lgkmcnt(0)
	v_mfma_f32_16x16x32_bf16 v[62:65], v[150:153], v[186:189], v[62:65]
	v_mfma_f32_16x16x32_bf16 v[58:61], v[158:161], v[186:189], v[58:61]
	v_mfma_f32_16x16x32_bf16 v[54:57], v[150:153], v[194:197], v[54:57]
	v_mfma_f32_16x16x32_bf16 v[46:49], v[158:161], v[194:197], v[46:49]
	v_mfma_f32_16x16x32_bf16 v[38:41], v[150:153], v[206:209], v[38:41]
	v_mfma_f32_16x16x32_bf16 v[30:33], v[158:161], v[206:209], v[30:33]
	v_mfma_f32_16x16x32_bf16 v[22:25], v[150:153], v[214:217], v[22:25]
	v_mfma_f32_16x16x32_bf16 v[14:17], v[158:161], v[214:217], v[14:17]
	v_mfma_f32_16x16x32_bf16 v[62:65], v[154:157], v[190:193], v[62:65]
	v_mfma_f32_16x16x32_bf16 v[58:61], v[166:169], v[190:193], v[58:61]
	v_mfma_f32_16x16x32_bf16 v[54:57], v[154:157], v[202:205], v[54:57]
	v_mfma_f32_16x16x32_bf16 v[46:49], v[166:169], v[202:205], v[46:49]
	v_mfma_f32_16x16x32_bf16 v[38:41], v[154:157], v[210:213], v[38:41]
	v_mfma_f32_16x16x32_bf16 v[30:33], v[166:169], v[210:213], v[30:33]
	v_mfma_f32_16x16x32_bf16 v[22:25], v[154:157], v[218:221], v[22:25]
	v_mfma_f32_16x16x32_bf16 v[14:17], v[166:169], v[218:221], v[14:17]
	s_setprio 0
	s_setprio 1
	v_mfma_f32_16x16x32_bf16 v[50:53], v[170:173], v[186:189], v[50:53]
	v_mfma_f32_16x16x32_bf16 v[42:45], v[178:181], v[186:189], v[42:45]
	v_mfma_f32_16x16x32_bf16 v[34:37], v[170:173], v[194:197], v[34:37]
	v_mfma_f32_16x16x32_bf16 v[26:29], v[178:181], v[194:197], v[26:29]
	v_mfma_f32_16x16x32_bf16 v[18:21], v[170:173], v[206:209], v[18:21]
	v_mfma_f32_16x16x32_bf16 v[10:13], v[178:181], v[206:209], v[10:13]
	v_mfma_f32_16x16x32_bf16 v[6:9], v[170:173], v[214:217], v[6:9]
	v_mfma_f32_16x16x32_bf16 v[2:5], v[178:181], v[214:217], v[2:5]
	v_mfma_f32_16x16x32_bf16 v[50:53], v[174:177], v[190:193], v[50:53]
	v_mfma_f32_16x16x32_bf16 v[42:45], v[182:185], v[190:193], v[42:45]
	v_mfma_f32_16x16x32_bf16 v[34:37], v[174:177], v[202:205], v[34:37]
	v_mfma_f32_16x16x32_bf16 v[26:29], v[182:185], v[202:205], v[26:29]
	v_mfma_f32_16x16x32_bf16 v[18:21], v[174:177], v[210:213], v[18:21]
	v_mfma_f32_16x16x32_bf16 v[10:13], v[182:185], v[210:213], v[10:13]
	v_mfma_f32_16x16x32_bf16 v[6:9], v[174:177], v[218:221], v[6:9]
	v_mfma_f32_16x16x32_bf16 v[2:5], v[182:185], v[218:221], v[2:5]
	s_setprio 0
	s_barrier
	s_movk_i32 s44, 0x100
	s_andn2_b64 vcc, exec, s[62:63]
	s_mov_b64 s[64:65], -1
	s_mov_b64 s[62:63], 0
	s_cbranch_vccz .LBB0_706
	s_and_b64 vcc, exec, s[12:13]
	s_cbranch_vccz .LBB0_709
	s_barrier

.LBB0_722:
	s_add_u32 s36, s56, s44
	s_addc_u32 s37, s57, 0
	s_add_u32 s66, s36, 0x100
	s_addc_u32 s67, s37, 0
	s_and_b64 s[64:65], s[62:63], exec
	s_cselect_b32 s67, s17, s67
	s_cselect_b32 s66, s83, s66
	s_add_u32 s44, s54, s44
	s_addc_u32 s64, s55, 0
	s_add_u32 s44, s44, 0x100
	s_addc_u32 s64, s64, 0
	s_and_b64 s[62:63], s[62:63], exec
	s_cselect_b32 s69, s15, s64
	s_cselect_b32 s68, s84, s44
	s_add_u32 s72, s36, 0x10080
	s_addc_u32 s73, s37, 0
	s_add_i32 s96, s79, s27
	ds_read_b128 v[148:151], v143
	ds_read_b128 v[152:155], v143 offset:1024
	ds_read_b128 v[156:159], v143 offset:2048
	ds_read_b128 v[166:169], v143 offset:3072
	ds_read_b128 v[170:173], v145
	ds_read_b128 v[174:177], v145 offset:1024
	ds_read_b128 v[178:181], v145 offset:2048
	ds_read_b128 v[182:185], v145 offset:3072
	s_add_i32 m0, s43, 0xc000
	s_add_i32 s97, s43, 0xe000
	s_add_i32 s93, s96, 0x2000
	s_add_u32 s70, s68, 0x10000
	s_addc_u32 s71, s69, 0
	s_add_i32 s95, s80, s27
	s_add_i32 s94, s95, 0x2000
	s_add_i32 s92, 0, 0x18000
	s_add_i32 s89, 0, 0x1c000
	s_add_u32 s64, s66, 0x10000
	s_addc_u32 s65, s67, 0
	s_add_i32 s87, s92, s27
	s_add_i32 s85, s87, 0x2000
	s_add_u32 s62, s68, 0x10080
	s_addc_u32 s63, s69, 0
	s_add_i32 s86, s89, s27
	s_add_i32 s44, s86, 0x2000
	v_lshl_add_u64 v[160:161], s[72:73], 0, v[130:131]
	ds_read_b128 v[186:189], v146
	ds_read_b128 v[190:193], v146 offset:1024
	ds_read_b128 v[194:197], v146 offset:2048
	ds_read_b128 v[202:205], v146 offset:3072
	ds_read_b128 v[206:209], v146 offset:4096
	ds_read_b128 v[210:213], v146 offset:5120
	ds_read_b128 v[214:217], v146 offset:6144
	ds_read_b128 v[218:221], v146 offset:7168
	global_load_lds_dwordx4 v[160:161], off
	v_lshl_add_u64 v[160:161], s[72:73], 0, v[134:135]
	s_mov_b32 m0, s97
	s_nop 0
	global_load_lds_dwordx4 v[160:161], off
	s_waitcnt vmcnt(8)
	s_waitcnt lgkmcnt(0)
	s_barrier
	s_setprio 1
	s_waitcnt lgkmcnt(0)
	v_mfma_f32_16x16x32_bf16 v[126:129], v[148:151], v[186:189], v[126:129]
	v_mfma_f32_16x16x32_bf16 v[122:125], v[156:159], v[186:189], v[122:125]
	v_mfma_f32_16x16x32_bf16 v[118:121], v[148:151], v[194:197], v[118:121]
	v_mfma_f32_16x16x32_bf16 v[110:113], v[156:159], v[194:197], v[110:113]
	v_mfma_f32_16x16x32_bf16 v[102:105], v[148:151], v[206:209], v[102:105]
	v_mfma_f32_16x16x32_bf16 v[94:97], v[156:159], v[206:209], v[94:97]
	v_mfma_f32_16x16x32_bf16 v[86:89], v[148:151], v[214:217], v[86:89]
	v_mfma_f32_16x16x32_bf16 v[78:81], v[156:159], v[214:217], v[78:81]
	v_mfma_f32_16x16x32_bf16 v[126:129], v[152:155], v[190:193], v[126:129]
	v_mfma_f32_16x16x32_bf16 v[122:125], v[166:169], v[190:193], v[122:125]
	v_mfma_f32_16x16x32_bf16 v[118:121], v[152:155], v[202:205], v[118:121]
	v_mfma_f32_16x16x32_bf16 v[110:113], v[166:169], v[202:205], v[110:113]
	v_mfma_f32_16x16x32_bf16 v[102:105], v[152:155], v[210:213], v[102:105]
	v_mfma_f32_16x16x32_bf16 v[94:97], v[166:169], v[210:213], v[94:97]
	v_mfma_f32_16x16x32_bf16 v[86:89], v[152:155], v[218:221], v[86:89]
	v_mfma_f32_16x16x32_bf16 v[78:81], v[166:169], v[218:221], v[78:81]
	s_setprio 0
	s_setprio 1
	v_mfma_f32_16x16x32_bf16 v[114:117], v[170:173], v[186:189], v[114:117]
	v_mfma_f32_16x16x32_bf16 v[106:109], v[178:181], v[186:189], v[106:109]
	v_mfma_f32_16x16x32_bf16 v[98:101], v[170:173], v[194:197], v[98:101]
	v_mfma_f32_16x16x32_bf16 v[90:93], v[178:181], v[194:197], v[90:93]
	v_mfma_f32_16x16x32_bf16 v[82:85], v[170:173], v[206:209], v[82:85]
	v_mfma_f32_16x16x32_bf16 v[74:77], v[178:181], v[206:209], v[74:77]
	v_mfma_f32_16x16x32_bf16 v[70:73], v[170:173], v[214:217], v[70:73]
	v_mfma_f32_16x16x32_bf16 v[66:69], v[178:181], v[214:217], v[66:69]
	v_mfma_f32_16x16x32_bf16 v[114:117], v[174:177], v[190:193], v[114:117]
	v_mfma_f32_16x16x32_bf16 v[106:109], v[182:185], v[190:193], v[106:109]
	v_mfma_f32_16x16x32_bf16 v[98:101], v[174:177], v[202:205], v[98:101]
	v_mfma_f32_16x16x32_bf16 v[90:93], v[182:185], v[202:205], v[90:93]
	v_mfma_f32_16x16x32_bf16 v[82:85], v[174:177], v[210:213], v[82:85]
	v_mfma_f32_16x16x32_bf16 v[74:77], v[182:185], v[210:213], v[74:77]
	v_mfma_f32_16x16x32_bf16 v[70:73], v[174:177], v[218:221], v[70:73]
	v_mfma_f32_16x16x32_bf16 v[66:69], v[182:185], v[218:221], v[66:69]
	s_setprio 0
	s_barrier
	s_mov_b32 m0, s96
	v_lshl_add_u64 v[160:161], s[68:69], 0, v[132:133]
	ds_read_b128 v[186:189], v146 offset:16384
	ds_read_b128 v[190:193], v146 offset:17408
	ds_read_b128 v[194:197], v146 offset:18432
	ds_read_b128 v[202:205], v146 offset:19456
	ds_read_b128 v[206:209], v146 offset:20480
	ds_read_b128 v[210:213], v146 offset:21504
	ds_read_b128 v[214:217], v146 offset:22528
	ds_read_b128 v[218:221], v146 offset:23552
	global_load_lds_dwordx4 v[160:161], off
	v_lshl_add_u64 v[198:199], s[68:69], 0, v[136:137]
	s_mov_b32 m0, s93
	v_lshl_add_u64 v[222:223], s[70:71], 0, v[132:133]
	global_load_lds_dwordx4 v[198:199], off
	s_mov_b32 m0, s95
	v_lshl_add_u64 v[224:225], s[66:67], 0, v[134:135]
	global_load_lds_dwordx4 v[222:223], off
	v_lshl_add_u64 v[222:223], s[70:71], 0, v[136:137]
	s_mov_b32 m0, s94
	s_nop 0
	global_load_lds_dwordx4 v[222:223], off
	s_waitcnt vmcnt(6)
	s_waitcnt lgkmcnt(0)
	s_barrier
	s_setprio 1
	s_waitcnt lgkmcnt(0)
	v_mfma_f32_16x16x32_bf16 v[62:65], v[148:151], v[186:189], v[62:65]
	v_mfma_f32_16x16x32_bf16 v[58:61], v[156:159], v[186:189], v[58:61]
	v_mfma_f32_16x16x32_bf16 v[54:57], v[148:151], v[194:197], v[54:57]
	v_mfma_f32_16x16x32_bf16 v[46:49], v[156:159], v[194:197], v[46:49]
	v_mfma_f32_16x16x32_bf16 v[38:41], v[148:151], v[206:209], v[38:41]
	v_mfma_f32_16x16x32_bf16 v[30:33], v[156:159], v[206:209], v[30:33]
	v_mfma_f32_16x16x32_bf16 v[22:25], v[148:151], v[214:217], v[22:25]
	v_mfma_f32_16x16x32_bf16 v[14:17], v[156:159], v[214:217], v[14:17]
	v_mfma_f32_16x16x32_bf16 v[62:65], v[152:155], v[190:193], v[62:65]
	v_mfma_f32_16x16x32_bf16 v[58:61], v[166:169], v[190:193], v[58:61]
	v_mfma_f32_16x16x32_bf16 v[54:57], v[152:155], v[202:205], v[54:57]
	v_mfma_f32_16x16x32_bf16 v[46:49], v[166:169], v[202:205], v[46:49]
	v_mfma_f32_16x16x32_bf16 v[38:41], v[152:155], v[210:213], v[38:41]
	v_mfma_f32_16x16x32_bf16 v[30:33], v[166:169], v[210:213], v[30:33]
	v_mfma_f32_16x16x32_bf16 v[22:25], v[152:155], v[218:221], v[22:25]
	v_mfma_f32_16x16x32_bf16 v[14:17], v[166:169], v[218:221], v[14:17]
	s_setprio 0
	s_setprio 1
	v_mfma_f32_16x16x32_bf16 v[50:53], v[170:173], v[186:189], v[50:53]
	v_mfma_f32_16x16x32_bf16 v[42:45], v[178:181], v[186:189], v[42:45]
	v_mfma_f32_16x16x32_bf16 v[34:37], v[170:173], v[194:197], v[34:37]
	v_mfma_f32_16x16x32_bf16 v[26:29], v[178:181], v[194:197], v[26:29]
	v_mfma_f32_16x16x32_bf16 v[18:21], v[170:173], v[206:209], v[18:21]
	v_mfma_f32_16x16x32_bf16 v[10:13], v[178:181], v[206:209], v[10:13]
	v_mfma_f32_16x16x32_bf16 v[6:9], v[170:173], v[214:217], v[6:9]
	v_mfma_f32_16x16x32_bf16 v[2:5], v[178:181], v[214:217], v[2:5]
	v_mfma_f32_16x16x32_bf16 v[50:53], v[174:177], v[190:193], v[50:53]
	v_mfma_f32_16x16x32_bf16 v[42:45], v[182:185], v[190:193], v[42:45]
	v_mfma_f32_16x16x32_bf16 v[34:37], v[174:177], v[202:205], v[34:37]
	v_mfma_f32_16x16x32_bf16 v[26:29], v[182:185], v[202:205], v[26:29]
	v_mfma_f32_16x16x32_bf16 v[18:21], v[174:177], v[210:213], v[18:21]
	v_mfma_f32_16x16x32_bf16 v[10:13], v[182:185], v[210:213], v[10:13]
	v_mfma_f32_16x16x32_bf16 v[6:9], v[174:177], v[218:221], v[6:9]
	v_mfma_f32_16x16x32_bf16 v[2:5], v[182:185], v[218:221], v[2:5]
	s_setprio 0
	s_barrier
	v_add_u32_e32 v147, s92, v142
	ds_read_b128 v[148:151], v147
	ds_read_b128 v[152:155], v147 offset:1024
	ds_read_b128 v[156:159], v147 offset:2048
	ds_read_b128 v[166:169], v147 offset:3072
	v_add_u32_e32 v147, s89, v142
	ds_read_b128 v[170:173], v147
	ds_read_b128 v[174:177], v147 offset:1024
	ds_read_b128 v[178:181], v147 offset:2048
	ds_read_b128 v[182:185], v147 offset:3072
	v_lshl_add_u64 v[222:223], s[66:67], 0, v[130:131]
	s_mov_b32 m0, s43
	s_nop 0
	global_load_lds_dwordx4 v[222:223], off
	s_mov_b32 m0, s45
	s_nop 0
	global_load_lds_dwordx4 v[224:225], off
	s_mov_b32 m0, s49
	v_lshl_add_u64 v[226:227], s[64:65], 0, v[130:131]
	ds_read_b128 v[186:189], v146 offset:32768
	ds_read_b128 v[190:193], v146 offset:33792
	ds_read_b128 v[194:197], v146 offset:34816
	ds_read_b128 v[202:205], v146 offset:35840
	ds_read_b128 v[206:209], v146 offset:36864
	ds_read_b128 v[210:213], v146 offset:37888
	ds_read_b128 v[214:217], v146 offset:38912
	ds_read_b128 v[218:221], v146 offset:39936
	global_load_lds_dwordx4 v[226:227], off
	v_lshl_add_u64 v[226:227], s[64:65], 0, v[134:135]
	s_mov_b32 m0, s74
	s_nop 0
	global_load_lds_dwordx4 v[226:227], off
	s_waitcnt vmcnt(8)
	s_waitcnt lgkmcnt(0)
	s_barrier
	s_setprio 1
	s_waitcnt lgkmcnt(0)
	v_mfma_f32_16x16x32_bf16 v[126:129], v[148:151], v[186:189], v[126:129]
	v_mfma_f32_16x16x32_bf16 v[122:125], v[156:159], v[186:189], v[122:125]
	v_mfma_f32_16x16x32_bf16 v[118:121], v[148:151], v[194:197], v[118:121]
	v_mfma_f32_16x16x32_bf16 v[110:113], v[156:159], v[194:197], v[110:113]
	v_mfma_f32_16x16x32_bf16 v[102:105], v[148:151], v[206:209], v[102:105]
	v_mfma_f32_16x16x32_bf16 v[94:97], v[156:159], v[206:209], v[94:97]
	v_mfma_f32_16x16x32_bf16 v[86:89], v[148:151], v[214:217], v[86:89]
	v_mfma_f32_16x16x32_bf16 v[78:81], v[156:159], v[214:217], v[78:81]
	v_mfma_f32_16x16x32_bf16 v[126:129], v[152:155], v[190:193], v[126:129]
	v_mfma_f32_16x16x32_bf16 v[122:125], v[166:169], v[190:193], v[122:125]
	v_mfma_f32_16x16x32_bf16 v[118:121], v[152:155], v[202:205], v[118:121]
	v_mfma_f32_16x16x32_bf16 v[110:113], v[166:169], v[202:205], v[110:113]
	v_mfma_f32_16x16x32_bf16 v[102:105], v[152:155], v[210:213], v[102:105]
	v_mfma_f32_16x16x32_bf16 v[94:97], v[166:169], v[210:213], v[94:97]
	v_mfma_f32_16x16x32_bf16 v[86:89], v[152:155], v[218:221], v[86:89]
	v_mfma_f32_16x16x32_bf16 v[78:81], v[166:169], v[218:221], v[78:81]
	s_setprio 0
	s_setprio 1
	v_mfma_f32_16x16x32_bf16 v[114:117], v[170:173], v[186:189], v[114:117]
	v_mfma_f32_16x16x32_bf16 v[106:109], v[178:181], v[186:189], v[106:109]
	v_mfma_f32_16x16x32_bf16 v[98:101], v[170:173], v[194:197], v[98:101]
	v_mfma_f32_16x16x32_bf16 v[90:93], v[178:181], v[194:197], v[90:93]
	v_mfma_f32_16x16x32_bf16 v[82:85], v[170:173], v[206:209], v[82:85]
	v_mfma_f32_16x16x32_bf16 v[74:77], v[178:181], v[206:209], v[74:77]
	v_mfma_f32_16x16x32_bf16 v[70:73], v[170:173], v[214:217], v[70:73]
	v_mfma_f32_16x16x32_bf16 v[66:69], v[178:181], v[214:217], v[66:69]
	v_mfma_f32_16x16x32_bf16 v[114:117], v[174:177], v[190:193], v[114:117]
	v_mfma_f32_16x16x32_bf16 v[106:109], v[182:185], v[190:193], v[106:109]
	v_mfma_f32_16x16x32_bf16 v[98:101], v[174:177], v[202:205], v[98:101]
	v_mfma_f32_16x16x32_bf16 v[90:93], v[182:185], v[202:205], v[90:93]
	v_mfma_f32_16x16x32_bf16 v[82:85], v[174:177], v[210:213], v[82:85]
	v_mfma_f32_16x16x32_bf16 v[74:77], v[182:185], v[210:213], v[74:77]
	v_mfma_f32_16x16x32_bf16 v[70:73], v[174:177], v[218:221], v[70:73]
	v_mfma_f32_16x16x32_bf16 v[66:69], v[182:185], v[218:221], v[66:69]
	s_setprio 0
	s_barrier
	s_mov_b32 m0, s87
	v_lshl_add_u64 v[160:161], v[160:161], 0, s[10:11]
	ds_read_b128 v[186:189], v146 offset:49152
	ds_read_b128 v[190:193], v146 offset:50176
	ds_read_b128 v[194:197], v146 offset:51200
	ds_read_b128 v[202:205], v146 offset:52224
	ds_read_b128 v[206:209], v146 offset:53248
	ds_read_b128 v[210:213], v146 offset:54272
	ds_read_b128 v[214:217], v146 offset:55296
	ds_read_b128 v[218:221], v146 offset:56320
	global_load_lds_dwordx4 v[160:161], off
	v_lshl_add_u64 v[160:161], v[198:199], 0, s[10:11]
	s_mov_b32 m0, s85
	s_nop 0
	global_load_lds_dwordx4 v[160:161], off
	v_lshl_add_u64 v[160:161], s[62:63], 0, v[132:133]
	s_mov_b32 m0, s86
	s_nop 0
	global_load_lds_dwordx4 v[160:161], off
	v_lshl_add_u64 v[160:161], s[62:63], 0, v[136:137]
	s_mov_b32 m0, s44
	s_nop 0
	global_load_lds_dwordx4 v[160:161], off
	v_lshl_add_u64 v[160:161], v[222:223], 0, s[10:11]
	s_mov_b32 m0, s76
	s_nop 0
	global_load_lds_dwordx4 v[160:161], off
	v_lshl_add_u64 v[160:161], v[224:225], 0, s[10:11]
	s_mov_b32 m0, s77
	s_nop 0
	global_load_lds_dwordx4 v[160:161], off
	s_waitcnt vmcnt(8)
	s_waitcnt lgkmcnt(0)
	s_barrier
	s_setprio 1
	s_waitcnt lgkmcnt(0)
	v_mfma_f32_16x16x32_bf16 v[62:65], v[148:151], v[186:189], v[62:65]
	v_mfma_f32_16x16x32_bf16 v[58:61], v[156:159], v[186:189], v[58:61]
	v_mfma_f32_16x16x32_bf16 v[54:57], v[148:151], v[194:197], v[54:57]
	v_mfma_f32_16x16x32_bf16 v[46:49], v[156:159], v[194:197], v[46:49]
	v_mfma_f32_16x16x32_bf16 v[38:41], v[148:151], v[206:209], v[38:41]
	v_mfma_f32_16x16x32_bf16 v[30:33], v[156:159], v[206:209], v[30:33]
	v_mfma_f32_16x16x32_bf16 v[22:25], v[148:151], v[214:217], v[22:25]
	v_mfma_f32_16x16x32_bf16 v[14:17], v[156:159], v[214:217], v[14:17]
	v_mfma_f32_16x16x32_bf16 v[62:65], v[152:155], v[190:193], v[62:65]
	v_mfma_f32_16x16x32_bf16 v[58:61], v[166:169], v[190:193], v[58:61]
	v_mfma_f32_16x16x32_bf16 v[54:57], v[152:155], v[202:205], v[54:57]
	v_mfma_f32_16x16x32_bf16 v[46:49], v[166:169], v[202:205], v[46:49]
	v_mfma_f32_16x16x32_bf16 v[38:41], v[152:155], v[210:213], v[38:41]
	v_mfma_f32_16x16x32_bf16 v[30:33], v[166:169], v[210:213], v[30:33]
	v_mfma_f32_16x16x32_bf16 v[22:25], v[152:155], v[218:221], v[22:25]
	v_mfma_f32_16x16x32_bf16 v[14:17], v[166:169], v[218:221], v[14:17]
	s_setprio 0
	s_setprio 1
	v_mfma_f32_16x16x32_bf16 v[50:53], v[170:173], v[186:189], v[50:53]
	v_mfma_f32_16x16x32_bf16 v[42:45], v[178:181], v[186:189], v[42:45]
	v_mfma_f32_16x16x32_bf16 v[34:37], v[170:173], v[194:197], v[34:37]
	v_mfma_f32_16x16x32_bf16 v[26:29], v[178:181], v[194:197], v[26:29]
	v_mfma_f32_16x16x32_bf16 v[18:21], v[170:173], v[206:209], v[18:21]
	v_mfma_f32_16x16x32_bf16 v[10:13], v[178:181], v[206:209], v[10:13]
	v_mfma_f32_16x16x32_bf16 v[6:9], v[170:173], v[214:217], v[6:9]
	v_mfma_f32_16x16x32_bf16 v[2:5], v[178:181], v[214:217], v[2:5]
	v_mfma_f32_16x16x32_bf16 v[50:53], v[174:177], v[190:193], v[50:53]
	v_mfma_f32_16x16x32_bf16 v[42:45], v[182:185], v[190:193], v[42:45]
	v_mfma_f32_16x16x32_bf16 v[34:37], v[174:177], v[202:205], v[34:37]
	v_mfma_f32_16x16x32_bf16 v[26:29], v[182:185], v[202:205], v[26:29]
	v_mfma_f32_16x16x32_bf16 v[18:21], v[174:177], v[210:213], v[18:21]
	v_mfma_f32_16x16x32_bf16 v[10:13], v[182:185], v[210:213], v[10:13]
	v_mfma_f32_16x16x32_bf16 v[6:9], v[174:177], v[218:221], v[6:9]
	v_mfma_f32_16x16x32_bf16 v[2:5], v[182:185], v[218:221], v[2:5]
	s_setprio 0
	s_barrier
	s_movk_i32 s44, 0x100
	s_andn2_b64 vcc, exec, s[60:61]
	s_mov_b64 s[62:63], -1
	s_mov_b64 s[60:61], 0
	s_cbranch_vccz .LBB0_722
	s_and_b64 vcc, exec, s[12:13]
	s_cbranch_vccz .LBB0_725
	s_barrier

.LBB0_1226:
	v_add_u32_e32 v3, s71, v165
	ds_read_b128 v[150:153], v3
	ds_read_b128 v[154:157], v3 offset:1024
	ds_read_b128 v[158:161], v3 offset:2048
	ds_read_b128 v[170:173], v3 offset:3072
	v_add_u32_e32 v3, s72, v165
	ds_read_b128 v[174:177], v3
	ds_read_b128 v[178:181], v3 offset:1024
	ds_read_b128 v[182:185], v3 offset:2048
	ds_read_b128 v[186:189], v3 offset:3072
	s_add_u32 s36, s52, 0xfff80080
	s_addc_u32 s37, s53, -1
	s_cmp_eq_u32 s78, 28
	s_cselect_b32 s59, s21, s37
	s_cselect_b32 s58, s44, s36
	s_cselect_b32 s57, s19, s77
	s_cselect_b32 s56, s55, s76
	v_lshl_add_u64 v[4:5], s[52:53], 0, v[142:143]
	s_add_i32 m0, s63, 0xc000
	ds_read_b128 v[190:193], v169
	ds_read_b128 v[194:197], v169 offset:1024
	ds_read_b128 v[202:205], v169 offset:2048
	ds_read_b128 v[206:209], v169 offset:3072
	ds_read_b128 v[210:213], v169 offset:4096
	ds_read_b128 v[214:217], v169 offset:5120
	ds_read_b128 v[218:221], v169 offset:6144
	ds_read_b128 v[222:225], v169 offset:7168
	global_load_lds_dwordx4 v[4:5], off
	v_lshl_add_u64 v[4:5], s[52:53], 0, v[144:145]
	s_add_i32 m0, s63, 0xe000
	s_nop 0
	global_load_lds_dwordx4 v[4:5], off
	s_waitcnt vmcnt(8)
	s_waitcnt lgkmcnt(0)
	s_barrier
	s_setprio 1
	s_waitcnt lgkmcnt(0)
	v_mfma_f32_16x16x32_bf16 v[130:133], v[150:153], v[190:193], v[130:133]
	v_mfma_f32_16x16x32_bf16 v[126:129], v[158:161], v[190:193], v[126:129]
	v_mfma_f32_16x16x32_bf16 v[122:125], v[150:153], v[202:205], v[122:125]
	v_mfma_f32_16x16x32_bf16 v[118:121], v[158:161], v[202:205], v[118:121]
	v_mfma_f32_16x16x32_bf16 v[114:117], v[150:153], v[210:213], v[114:117]
	v_mfma_f32_16x16x32_bf16 v[110:113], v[158:161], v[210:213], v[110:113]
	v_mfma_f32_16x16x32_bf16 v[106:109], v[150:153], v[218:221], v[106:109]
	v_mfma_f32_16x16x32_bf16 v[102:105], v[158:161], v[218:221], v[102:105]
	v_mfma_f32_16x16x32_bf16 v[130:133], v[154:157], v[194:197], v[130:133]
	v_mfma_f32_16x16x32_bf16 v[126:129], v[170:173], v[194:197], v[126:129]
	v_mfma_f32_16x16x32_bf16 v[122:125], v[154:157], v[206:209], v[122:125]
	v_mfma_f32_16x16x32_bf16 v[118:121], v[170:173], v[206:209], v[118:121]
	v_mfma_f32_16x16x32_bf16 v[114:117], v[154:157], v[214:217], v[114:117]
	v_mfma_f32_16x16x32_bf16 v[110:113], v[170:173], v[214:217], v[110:113]
	v_mfma_f32_16x16x32_bf16 v[106:109], v[154:157], v[222:225], v[106:109]
	v_mfma_f32_16x16x32_bf16 v[102:105], v[170:173], v[222:225], v[102:105]
	s_setprio 0
	s_setprio 1
	v_mfma_f32_16x16x32_bf16 v[98:101], v[174:177], v[190:193], v[98:101]
	v_mfma_f32_16x16x32_bf16 v[94:97], v[182:185], v[190:193], v[94:97]
	v_mfma_f32_16x16x32_bf16 v[90:93], v[174:177], v[202:205], v[90:93]
	v_mfma_f32_16x16x32_bf16 v[86:89], v[182:185], v[202:205], v[86:89]
	v_mfma_f32_16x16x32_bf16 v[82:85], v[174:177], v[210:213], v[82:85]
	v_mfma_f32_16x16x32_bf16 v[78:81], v[182:185], v[210:213], v[78:81]
	v_mfma_f32_16x16x32_bf16 v[74:77], v[174:177], v[218:221], v[74:77]
	v_mfma_f32_16x16x32_bf16 v[70:73], v[182:185], v[218:221], v[70:73]
	v_mfma_f32_16x16x32_bf16 v[98:101], v[178:181], v[194:197], v[98:101]
	v_mfma_f32_16x16x32_bf16 v[94:97], v[186:189], v[194:197], v[94:97]
	v_mfma_f32_16x16x32_bf16 v[90:93], v[178:181], v[206:209], v[90:93]
	v_mfma_f32_16x16x32_bf16 v[86:89], v[186:189], v[206:209], v[86:89]
	v_mfma_f32_16x16x32_bf16 v[82:85], v[178:181], v[214:217], v[82:85]
	v_mfma_f32_16x16x32_bf16 v[78:81], v[186:189], v[214:217], v[78:81]
	v_mfma_f32_16x16x32_bf16 v[74:77], v[178:181], v[222:225], v[74:77]
	v_mfma_f32_16x16x32_bf16 v[70:73], v[186:189], v[222:225], v[70:73]
	s_setprio 0
	s_barrier
	s_add_i32 s36, s71, s43
	v_lshl_add_u64 v[166:167], s[56:57], 0, v[138:139]
	s_mov_b32 m0, s36
	ds_read_b128 v[190:193], v169 offset:16384
	ds_read_b128 v[194:197], v169 offset:17408
	ds_read_b128 v[202:205], v169 offset:18432
	ds_read_b128 v[206:209], v169 offset:19456
	ds_read_b128 v[210:213], v169 offset:20480
	ds_read_b128 v[214:217], v169 offset:21504
	ds_read_b128 v[218:221], v169 offset:22528
	ds_read_b128 v[222:225], v169 offset:23552
	global_load_lds_dwordx4 v[166:167], off
	s_add_i32 m0, s36, 0x2000
	s_add_u32 s80, s56, 0x80000
	v_lshl_add_u64 v[198:199], s[56:57], 0, v[134:135]
	s_addc_u32 s81, s57, 0
	s_add_i32 s36, s72, s43
	global_load_lds_dwordx4 v[198:199], off
	v_lshl_add_u64 v[4:5], s[80:81], 0, v[138:139]
	s_mov_b32 m0, s36
	v_lshl_add_u64 v[226:227], s[58:59], 0, v[140:141]
	global_load_lds_dwordx4 v[4:5], off
	v_lshl_add_u64 v[4:5], s[80:81], 0, v[134:135]
	s_add_i32 m0, s36, 0x2000
	v_lshl_add_u64 v[228:229], s[58:59], 0, v[136:137]
	global_load_lds_dwordx4 v[4:5], off
	s_waitcnt vmcnt(6)
	s_waitcnt lgkmcnt(0)
	s_barrier
	s_setprio 1
	s_waitcnt lgkmcnt(0)
	v_mfma_f32_16x16x32_bf16 v[66:69], v[150:153], v[190:193], v[66:69]
	v_mfma_f32_16x16x32_bf16 v[62:65], v[158:161], v[190:193], v[62:65]
	v_mfma_f32_16x16x32_bf16 v[58:61], v[150:153], v[202:205], v[58:61]
	v_mfma_f32_16x16x32_bf16 v[54:57], v[158:161], v[202:205], v[54:57]
	v_mfma_f32_16x16x32_bf16 v[50:53], v[150:153], v[210:213], v[50:53]
	v_mfma_f32_16x16x32_bf16 v[46:49], v[158:161], v[210:213], v[46:49]
	v_mfma_f32_16x16x32_bf16 v[42:45], v[150:153], v[218:221], v[42:45]
	v_mfma_f32_16x16x32_bf16 v[38:41], v[158:161], v[218:221], v[38:41]
	v_mfma_f32_16x16x32_bf16 v[66:69], v[154:157], v[194:197], v[66:69]
	v_mfma_f32_16x16x32_bf16 v[62:65], v[170:173], v[194:197], v[62:65]
	v_mfma_f32_16x16x32_bf16 v[58:61], v[154:157], v[206:209], v[58:61]
	v_mfma_f32_16x16x32_bf16 v[54:57], v[170:173], v[206:209], v[54:57]
	v_mfma_f32_16x16x32_bf16 v[50:53], v[154:157], v[214:217], v[50:53]
	v_mfma_f32_16x16x32_bf16 v[46:49], v[170:173], v[214:217], v[46:49]
	v_mfma_f32_16x16x32_bf16 v[42:45], v[154:157], v[222:225], v[42:45]
	v_mfma_f32_16x16x32_bf16 v[38:41], v[170:173], v[222:225], v[38:41]
	s_setprio 0
	s_setprio 1
	v_mfma_f32_16x16x32_bf16 v[34:37], v[174:177], v[190:193], v[34:37]
	v_mfma_f32_16x16x32_bf16 v[30:33], v[182:185], v[190:193], v[30:33]
	v_mfma_f32_16x16x32_bf16 v[26:29], v[174:177], v[202:205], v[26:29]
	v_mfma_f32_16x16x32_bf16 v[22:25], v[182:185], v[202:205], v[22:25]
	v_mfma_f32_16x16x32_bf16 v[18:21], v[174:177], v[210:213], v[18:21]
	v_mfma_f32_16x16x32_bf16 v[14:17], v[182:185], v[210:213], v[14:17]
	v_mfma_f32_16x16x32_bf16 v[10:13], v[174:177], v[218:221], v[10:13]
	v_mfma_f32_16x16x32_bf16 v[4:7], v[182:185], v[218:221], v[6:9]
	v_mfma_f32_16x16x32_bf16 v[34:37], v[178:181], v[194:197], v[34:37]
	v_mfma_f32_16x16x32_bf16 v[30:33], v[186:189], v[194:197], v[30:33]
	v_mfma_f32_16x16x32_bf16 v[26:29], v[178:181], v[206:209], v[26:29]
	v_mfma_f32_16x16x32_bf16 v[22:25], v[186:189], v[206:209], v[22:25]
	v_mfma_f32_16x16x32_bf16 v[18:21], v[178:181], v[214:217], v[18:21]
	v_mfma_f32_16x16x32_bf16 v[14:17], v[186:189], v[214:217], v[14:17]
	v_mfma_f32_16x16x32_bf16 v[10:13], v[178:181], v[222:225], v[10:13]
	v_mfma_f32_16x16x32_bf16 v[4:7], v[186:189], v[222:225], v[4:7]
	s_setprio 0
	s_barrier
	s_add_i32 s36, 0, 0x18000
	v_add_u32_e32 v3, s36, v165
	s_add_i32 s37, 0, 0x1c000
	ds_read_b128 v[150:153], v3
	ds_read_b128 v[154:157], v3 offset:1024
	ds_read_b128 v[158:161], v3 offset:2048
	ds_read_b128 v[170:173], v3 offset:3072
	v_add_u32_e32 v3, s37, v165
	ds_read_b128 v[174:177], v3
	ds_read_b128 v[178:181], v3 offset:1024
	ds_read_b128 v[182:185], v3 offset:2048
	ds_read_b128 v[186:189], v3 offset:3072
	s_add_u32 s58, s58, 0x80000
	s_addc_u32 s59, s59, 0
	s_mov_b32 m0, s63
	s_nop 0
	global_load_lds_dwordx4 v[226:227], off
	s_mov_b32 m0, s64
	s_nop 0
	global_load_lds_dwordx4 v[228:229], off
	s_mov_b32 m0, s65
	v_lshl_add_u64 v[8:9], s[58:59], 0, v[140:141]
	ds_read_b128 v[190:193], v169 offset:32768
	ds_read_b128 v[194:197], v169 offset:33792
	ds_read_b128 v[202:205], v169 offset:34816
	ds_read_b128 v[206:209], v169 offset:35840
	ds_read_b128 v[210:213], v169 offset:36864
	ds_read_b128 v[214:217], v169 offset:37888
	ds_read_b128 v[218:221], v169 offset:38912
	ds_read_b128 v[222:225], v169 offset:39936
	global_load_lds_dwordx4 v[8:9], off
	v_lshl_add_u64 v[8:9], s[58:59], 0, v[136:137]
	s_mov_b32 m0, s66
	s_nop 0
	global_load_lds_dwordx4 v[8:9], off
	s_waitcnt vmcnt(8)
	s_waitcnt lgkmcnt(0)
	s_barrier
	s_setprio 1
	s_waitcnt lgkmcnt(0)
	v_mfma_f32_16x16x32_bf16 v[130:133], v[150:153], v[190:193], v[130:133]
	v_mfma_f32_16x16x32_bf16 v[126:129], v[158:161], v[190:193], v[126:129]
	v_mfma_f32_16x16x32_bf16 v[122:125], v[150:153], v[202:205], v[122:125]
	v_mfma_f32_16x16x32_bf16 v[118:121], v[158:161], v[202:205], v[118:121]
	v_mfma_f32_16x16x32_bf16 v[114:117], v[150:153], v[210:213], v[114:117]
	v_mfma_f32_16x16x32_bf16 v[110:113], v[158:161], v[210:213], v[110:113]
	v_mfma_f32_16x16x32_bf16 v[106:109], v[150:153], v[218:221], v[106:109]
	v_mfma_f32_16x16x32_bf16 v[102:105], v[158:161], v[218:221], v[102:105]
	v_mfma_f32_16x16x32_bf16 v[130:133], v[154:157], v[194:197], v[130:133]
	v_mfma_f32_16x16x32_bf16 v[126:129], v[170:173], v[194:197], v[126:129]
	v_mfma_f32_16x16x32_bf16 v[122:125], v[154:157], v[206:209], v[122:125]
	v_mfma_f32_16x16x32_bf16 v[118:121], v[170:173], v[206:209], v[118:121]
	v_mfma_f32_16x16x32_bf16 v[114:117], v[154:157], v[214:217], v[114:117]
	v_mfma_f32_16x16x32_bf16 v[110:113], v[170:173], v[214:217], v[110:113]
	v_mfma_f32_16x16x32_bf16 v[106:109], v[154:157], v[222:225], v[106:109]
	v_mfma_f32_16x16x32_bf16 v[102:105], v[170:173], v[222:225], v[102:105]
	s_setprio 0
	s_setprio 1
	v_mfma_f32_16x16x32_bf16 v[98:101], v[174:177], v[190:193], v[98:101]
	v_mfma_f32_16x16x32_bf16 v[94:97], v[182:185], v[190:193], v[94:97]
	v_mfma_f32_16x16x32_bf16 v[90:93], v[174:177], v[202:205], v[90:93]
	v_mfma_f32_16x16x32_bf16 v[86:89], v[182:185], v[202:205], v[86:89]
	v_mfma_f32_16x16x32_bf16 v[82:85], v[174:177], v[210:213], v[82:85]
	v_mfma_f32_16x16x32_bf16 v[78:81], v[182:185], v[210:213], v[78:81]
	v_mfma_f32_16x16x32_bf16 v[74:77], v[174:177], v[218:221], v[74:77]
	v_mfma_f32_16x16x32_bf16 v[70:73], v[182:185], v[218:221], v[70:73]
	v_mfma_f32_16x16x32_bf16 v[98:101], v[178:181], v[194:197], v[98:101]
	v_mfma_f32_16x16x32_bf16 v[94:97], v[186:189], v[194:197], v[94:97]
	v_mfma_f32_16x16x32_bf16 v[90:93], v[178:181], v[206:209], v[90:93]
	v_mfma_f32_16x16x32_bf16 v[86:89], v[186:189], v[206:209], v[86:89]
	v_mfma_f32_16x16x32_bf16 v[82:85], v[178:181], v[214:217], v[82:85]
	v_mfma_f32_16x16x32_bf16 v[78:81], v[186:189], v[214:217], v[78:81]
	v_mfma_f32_16x16x32_bf16 v[74:77], v[178:181], v[222:225], v[74:77]
	v_mfma_f32_16x16x32_bf16 v[70:73], v[186:189], v[222:225], v[70:73]
	s_setprio 0
	s_barrier
	s_add_i32 s36, s36, s43
	v_lshl_add_u64 v[8:9], v[166:167], 0, s[10:11]
	s_mov_b32 m0, s36
	ds_read_b128 v[190:193], v169 offset:49152
	ds_read_b128 v[194:197], v169 offset:50176
	ds_read_b128 v[202:205], v169 offset:51200
	ds_read_b128 v[206:209], v169 offset:52224
	ds_read_b128 v[210:213], v169 offset:53248
	ds_read_b128 v[214:217], v169 offset:54272
	ds_read_b128 v[218:221], v169 offset:55296
	ds_read_b128 v[222:225], v169 offset:56320
	global_load_lds_dwordx4 v[8:9], off
	s_add_i32 m0, s36, 0x2000
	s_add_u32 s56, s56, 0x80080
	v_lshl_add_u64 v[8:9], v[198:199], 0, s[10:11]
	s_addc_u32 s57, s57, 0
	s_add_i32 s36, s37, s43
	global_load_lds_dwordx4 v[8:9], off
	v_lshl_add_u64 v[8:9], s[56:57], 0, v[138:139]
	s_mov_b32 m0, s36
	s_nop 0
	global_load_lds_dwordx4 v[8:9], off
	v_lshl_add_u64 v[8:9], s[56:57], 0, v[134:135]
	s_add_i32 m0, s36, 0x2000
	s_nop 0
	global_load_lds_dwordx4 v[8:9], off
	v_lshl_add_u64 v[8:9], v[226:227], 0, s[10:11]
	s_mov_b32 m0, s69
	s_nop 0
	global_load_lds_dwordx4 v[8:9], off
	v_lshl_add_u64 v[8:9], v[228:229], 0, s[10:11]
	s_mov_b32 m0, s70
	s_nop 0
	global_load_lds_dwordx4 v[8:9], off
	s_waitcnt vmcnt(8)
	s_waitcnt lgkmcnt(0)
	s_barrier
	s_setprio 1
	s_waitcnt lgkmcnt(0)
	v_mfma_f32_16x16x32_bf16 v[66:69], v[150:153], v[190:193], v[66:69]
	v_mfma_f32_16x16x32_bf16 v[62:65], v[158:161], v[190:193], v[62:65]
	v_mfma_f32_16x16x32_bf16 v[58:61], v[150:153], v[202:205], v[58:61]
	v_mfma_f32_16x16x32_bf16 v[54:57], v[158:161], v[202:205], v[54:57]
	v_mfma_f32_16x16x32_bf16 v[50:53], v[150:153], v[210:213], v[50:53]
	v_mfma_f32_16x16x32_bf16 v[46:49], v[158:161], v[210:213], v[46:49]
	v_mfma_f32_16x16x32_bf16 v[42:45], v[150:153], v[218:221], v[42:45]
	v_mfma_f32_16x16x32_bf16 v[38:41], v[158:161], v[218:221], v[38:41]
	v_mfma_f32_16x16x32_bf16 v[66:69], v[154:157], v[194:197], v[66:69]
	v_mfma_f32_16x16x32_bf16 v[62:65], v[170:173], v[194:197], v[62:65]
	v_mfma_f32_16x16x32_bf16 v[58:61], v[154:157], v[206:209], v[58:61]
	v_mfma_f32_16x16x32_bf16 v[54:57], v[170:173], v[206:209], v[54:57]
	v_mfma_f32_16x16x32_bf16 v[50:53], v[154:157], v[214:217], v[50:53]
	v_mfma_f32_16x16x32_bf16 v[46:49], v[170:173], v[214:217], v[46:49]
	v_mfma_f32_16x16x32_bf16 v[42:45], v[154:157], v[222:225], v[42:45]
	v_mfma_f32_16x16x32_bf16 v[38:41], v[170:173], v[222:225], v[38:41]
	s_setprio 0
	s_setprio 1
	v_mfma_f32_16x16x32_bf16 v[34:37], v[174:177], v[190:193], v[34:37]
	v_mfma_f32_16x16x32_bf16 v[30:33], v[182:185], v[190:193], v[30:33]
	v_mfma_f32_16x16x32_bf16 v[26:29], v[174:177], v[202:205], v[26:29]
	v_mfma_f32_16x16x32_bf16 v[22:25], v[182:185], v[202:205], v[22:25]
	v_mfma_f32_16x16x32_bf16 v[18:21], v[174:177], v[210:213], v[18:21]
	v_mfma_f32_16x16x32_bf16 v[14:17], v[182:185], v[210:213], v[14:17]
	v_mfma_f32_16x16x32_bf16 v[8:11], v[174:177], v[218:221], v[10:13]
	v_mfma_f32_16x16x32_bf16 v[4:7], v[182:185], v[218:221], v[4:7]
	v_mfma_f32_16x16x32_bf16 v[34:37], v[178:181], v[194:197], v[34:37]
	v_mfma_f32_16x16x32_bf16 v[30:33], v[186:189], v[194:197], v[30:33]
	v_mfma_f32_16x16x32_bf16 v[26:29], v[178:181], v[206:209], v[26:29]
	v_mfma_f32_16x16x32_bf16 v[22:25], v[186:189], v[206:209], v[22:25]
	v_mfma_f32_16x16x32_bf16 v[18:21], v[178:181], v[214:217], v[18:21]
	v_mfma_f32_16x16x32_bf16 v[14:17], v[186:189], v[214:217], v[14:17]
	v_mfma_f32_16x16x32_bf16 v[10:13], v[178:181], v[222:225], v[8:11]
	v_mfma_f32_16x16x32_bf16 v[6:9], v[186:189], v[222:225], v[4:7]
	s_setprio 0
	s_barrier
	s_add_i32 s78, s78, 2
	s_add_u32 s52, s52, 0x100
	s_addc_u32 s53, s53, 0
	s_add_u32 s76, s76, 0x100
	s_addc_u32 s77, s77, 0
	s_cmp_gt_u32 s78, 29
	s_cbranch_scc0 .LBB0_1226
	s_and_b64 vcc, exec, s[12:13]
	s_cbranch_vccz .LBB0_1229
	s_barrier

.LBB0_1397:
	ds_read_b128 v[146:149], v154
	ds_read_b128 v[158:161], v154 offset:1024
	ds_read_b128 v[166:169], v154 offset:2048
	ds_read_b128 v[170:173], v154 offset:3072
	ds_read_b128 v[174:177], v155
	ds_read_b128 v[178:181], v155 offset:1024
	ds_read_b128 v[182:185], v155 offset:2048
	ds_read_b128 v[186:189], v155 offset:3072
	s_add_i32 s93, s44, 2
	s_add_u32 s36, s62, 0xfff00080
	s_addc_u32 s37, s63, -1
	s_cmp_eq_u32 s59, s44
	s_cselect_b32 s67, s38, s37
	s_cselect_b32 s66, s39, s36
	s_cselect_b32 s65, s51, s92
	s_cselect_b32 s64, s53, s61
	v_lshl_add_u64 v[150:151], s[62:63], 0, v[140:141]
	s_add_i32 m0, s72, 0xc000
	ds_read_b128 v[190:193], v156
	ds_read_b128 v[194:197], v156 offset:1024
	ds_read_b128 v[202:205], v156 offset:2048
	ds_read_b128 v[206:209], v156 offset:3072
	ds_read_b128 v[210:213], v156 offset:4096
	ds_read_b128 v[214:217], v156 offset:5120
	ds_read_b128 v[218:221], v156 offset:6144
	ds_read_b128 v[222:225], v156 offset:7168
	global_load_lds_dwordx4 v[150:151], off
	v_lshl_add_u64 v[150:151], s[62:63], 0, v[142:143]
	s_add_i32 m0, s72, 0xe000
	s_nop 0
	global_load_lds_dwordx4 v[150:151], off
	s_waitcnt vmcnt(8)
	s_waitcnt lgkmcnt(0)
	s_barrier
	s_setprio 1
	s_waitcnt lgkmcnt(0)
	v_mfma_f32_16x16x32_bf16 v[126:129], v[146:149], v[190:193], v[126:129]
	v_mfma_f32_16x16x32_bf16 v[122:125], v[166:169], v[190:193], v[122:125]
	v_mfma_f32_16x16x32_bf16 v[110:113], v[146:149], v[202:205], v[110:113]
	v_mfma_f32_16x16x32_bf16 v[106:109], v[166:169], v[202:205], v[106:109]
	v_mfma_f32_16x16x32_bf16 v[94:97], v[146:149], v[210:213], v[94:97]
	v_mfma_f32_16x16x32_bf16 v[90:93], v[166:169], v[210:213], v[90:93]
	v_mfma_f32_16x16x32_bf16 v[78:81], v[146:149], v[218:221], v[78:81]
	v_mfma_f32_16x16x32_bf16 v[74:77], v[166:169], v[218:221], v[74:77]
	v_mfma_f32_16x16x32_bf16 v[126:129], v[158:161], v[194:197], v[126:129]
	v_mfma_f32_16x16x32_bf16 v[122:125], v[170:173], v[194:197], v[122:125]
	v_mfma_f32_16x16x32_bf16 v[110:113], v[158:161], v[206:209], v[110:113]
	v_mfma_f32_16x16x32_bf16 v[106:109], v[170:173], v[206:209], v[106:109]
	v_mfma_f32_16x16x32_bf16 v[94:97], v[158:161], v[214:217], v[94:97]
	v_mfma_f32_16x16x32_bf16 v[90:93], v[170:173], v[214:217], v[90:93]
	v_mfma_f32_16x16x32_bf16 v[78:81], v[158:161], v[222:225], v[78:81]
	v_mfma_f32_16x16x32_bf16 v[74:77], v[170:173], v[222:225], v[74:77]
	s_setprio 0
	s_setprio 1
	v_mfma_f32_16x16x32_bf16 v[118:121], v[174:177], v[190:193], v[118:121]
	v_mfma_f32_16x16x32_bf16 v[114:117], v[182:185], v[190:193], v[114:117]
	v_mfma_f32_16x16x32_bf16 v[102:105], v[174:177], v[202:205], v[102:105]
	v_mfma_f32_16x16x32_bf16 v[98:101], v[182:185], v[202:205], v[98:101]
	v_mfma_f32_16x16x32_bf16 v[86:89], v[174:177], v[210:213], v[86:89]
	v_mfma_f32_16x16x32_bf16 v[82:85], v[182:185], v[210:213], v[82:85]
	v_mfma_f32_16x16x32_bf16 v[70:73], v[174:177], v[218:221], v[70:73]
	v_mfma_f32_16x16x32_bf16 v[66:69], v[182:185], v[218:221], v[66:69]
	v_mfma_f32_16x16x32_bf16 v[118:121], v[178:181], v[194:197], v[118:121]
	v_mfma_f32_16x16x32_bf16 v[114:117], v[186:189], v[194:197], v[114:117]
	v_mfma_f32_16x16x32_bf16 v[102:105], v[178:181], v[206:209], v[102:105]
	v_mfma_f32_16x16x32_bf16 v[98:101], v[186:189], v[206:209], v[98:101]
	v_mfma_f32_16x16x32_bf16 v[86:89], v[178:181], v[214:217], v[86:89]
	v_mfma_f32_16x16x32_bf16 v[82:85], v[186:189], v[214:217], v[82:85]
	v_mfma_f32_16x16x32_bf16 v[70:73], v[178:181], v[222:225], v[70:73]
	v_mfma_f32_16x16x32_bf16 v[66:69], v[186:189], v[222:225], v[66:69]
	s_setprio 0
	s_barrier
	s_add_i32 s36, s82, s69
	v_lshl_add_u64 v[150:151], s[64:65], 0, v[132:133]
	s_mov_b32 m0, s36
	ds_read_b128 v[190:193], v156 offset:16384
	ds_read_b128 v[194:197], v156 offset:17408
	ds_read_b128 v[202:205], v156 offset:18432
	ds_read_b128 v[206:209], v156 offset:19456
	ds_read_b128 v[210:213], v156 offset:20480
	ds_read_b128 v[214:217], v156 offset:21504
	ds_read_b128 v[218:221], v156 offset:22528
	ds_read_b128 v[222:225], v156 offset:23552
	global_load_lds_dwordx4 v[150:151], off
	s_add_i32 m0, s36, 0x2000
	s_add_u32 s94, s64, 0x100000
	v_lshl_add_u64 v[198:199], s[64:65], 0, v[136:137]
	s_addc_u32 s95, s65, 0
	s_add_i32 s36, s83, s69
	global_load_lds_dwordx4 v[198:199], off
	v_lshl_add_u64 v[226:227], s[94:95], 0, v[132:133]
	s_mov_b32 m0, s36
	v_lshl_add_u64 v[228:229], s[66:67], 0, v[134:135]
	global_load_lds_dwordx4 v[226:227], off
	v_lshl_add_u64 v[226:227], s[94:95], 0, v[136:137]
	s_add_i32 m0, s36, 0x2000
	s_nop 0
	global_load_lds_dwordx4 v[226:227], off
	s_waitcnt vmcnt(6)
	s_waitcnt lgkmcnt(0)
	s_barrier
	s_setprio 1
	s_waitcnt lgkmcnt(0)
	v_mfma_f32_16x16x32_bf16 v[62:65], v[146:149], v[190:193], v[62:65]
	v_mfma_f32_16x16x32_bf16 v[58:61], v[166:169], v[190:193], v[58:61]
	v_mfma_f32_16x16x32_bf16 v[46:49], v[146:149], v[202:205], v[46:49]
	v_mfma_f32_16x16x32_bf16 v[42:45], v[166:169], v[202:205], v[42:45]
	v_mfma_f32_16x16x32_bf16 v[30:33], v[146:149], v[210:213], v[30:33]
	v_mfma_f32_16x16x32_bf16 v[26:29], v[166:169], v[210:213], v[26:29]
	v_mfma_f32_16x16x32_bf16 v[14:17], v[146:149], v[218:221], v[14:17]
	v_mfma_f32_16x16x32_bf16 v[10:13], v[166:169], v[218:221], v[10:13]
	v_mfma_f32_16x16x32_bf16 v[62:65], v[158:161], v[194:197], v[62:65]
	v_mfma_f32_16x16x32_bf16 v[58:61], v[170:173], v[194:197], v[58:61]
	v_mfma_f32_16x16x32_bf16 v[46:49], v[158:161], v[206:209], v[46:49]
	v_mfma_f32_16x16x32_bf16 v[42:45], v[170:173], v[206:209], v[42:45]
	v_mfma_f32_16x16x32_bf16 v[30:33], v[158:161], v[214:217], v[30:33]
	v_mfma_f32_16x16x32_bf16 v[26:29], v[170:173], v[214:217], v[26:29]
	v_mfma_f32_16x16x32_bf16 v[14:17], v[158:161], v[222:225], v[14:17]
	v_mfma_f32_16x16x32_bf16 v[10:13], v[170:173], v[222:225], v[10:13]
	s_setprio 0
	s_setprio 1
	v_mfma_f32_16x16x32_bf16 v[54:57], v[174:177], v[190:193], v[54:57]
	v_mfma_f32_16x16x32_bf16 v[50:53], v[182:185], v[190:193], v[50:53]
	v_mfma_f32_16x16x32_bf16 v[38:41], v[174:177], v[202:205], v[38:41]
	v_mfma_f32_16x16x32_bf16 v[34:37], v[182:185], v[202:205], v[34:37]
	v_mfma_f32_16x16x32_bf16 v[22:25], v[174:177], v[210:213], v[22:25]
	v_mfma_f32_16x16x32_bf16 v[18:21], v[182:185], v[210:213], v[18:21]
	v_mfma_f32_16x16x32_bf16 v[6:9], v[174:177], v[218:221], v[6:9]
	v_mfma_f32_16x16x32_bf16 v[2:5], v[182:185], v[218:221], v[2:5]
	v_mfma_f32_16x16x32_bf16 v[54:57], v[178:181], v[194:197], v[54:57]
	v_mfma_f32_16x16x32_bf16 v[50:53], v[186:189], v[194:197], v[50:53]
	v_mfma_f32_16x16x32_bf16 v[38:41], v[178:181], v[206:209], v[38:41]
	v_mfma_f32_16x16x32_bf16 v[34:37], v[186:189], v[206:209], v[34:37]
	v_mfma_f32_16x16x32_bf16 v[22:25], v[178:181], v[214:217], v[22:25]
	v_mfma_f32_16x16x32_bf16 v[18:21], v[186:189], v[214:217], v[18:21]
	v_mfma_f32_16x16x32_bf16 v[6:9], v[178:181], v[222:225], v[6:9]
	v_mfma_f32_16x16x32_bf16 v[2:5], v[186:189], v[222:225], v[2:5]
	s_setprio 0
	s_barrier
	s_add_i32 s36, 0, 0x18000
	v_add_u32_e32 v138, s36, v152
	s_add_i32 s37, 0, 0x1c000
	ds_read_b128 v[146:149], v138
	ds_read_b128 v[158:161], v138 offset:1024
	ds_read_b128 v[166:169], v138 offset:2048
	ds_read_b128 v[170:173], v138 offset:3072
	v_add_u32_e32 v138, s37, v152
	ds_read_b128 v[174:177], v138
	ds_read_b128 v[178:181], v138 offset:1024
	ds_read_b128 v[182:185], v138 offset:2048
	ds_read_b128 v[186:189], v138 offset:3072
	v_lshl_add_u64 v[226:227], s[66:67], 0, v[130:131]
	s_mov_b32 m0, s72
	s_nop 0
	global_load_lds_dwordx4 v[226:227], off
	s_mov_b32 m0, s73
	s_nop 0
	global_load_lds_dwordx4 v[228:229], off
	s_add_u32 s66, s66, 0x100000
	s_addc_u32 s67, s67, 0
	s_mov_b32 m0, s74
	v_lshl_add_u64 v[230:231], s[66:67], 0, v[130:131]
	ds_read_b128 v[190:193], v156 offset:32768
	ds_read_b128 v[194:197], v156 offset:33792
	ds_read_b128 v[202:205], v156 offset:34816
	ds_read_b128 v[206:209], v156 offset:35840
	ds_read_b128 v[210:213], v156 offset:36864
	ds_read_b128 v[214:217], v156 offset:37888
	ds_read_b128 v[218:221], v156 offset:38912
	ds_read_b128 v[222:225], v156 offset:39936
	global_load_lds_dwordx4 v[230:231], off
	v_lshl_add_u64 v[230:231], s[66:67], 0, v[134:135]
	s_mov_b32 m0, s75
	s_nop 0
	global_load_lds_dwordx4 v[230:231], off
	s_waitcnt vmcnt(8)
	s_waitcnt lgkmcnt(0)
	s_barrier
	s_setprio 1
	s_waitcnt lgkmcnt(0)
	v_mfma_f32_16x16x32_bf16 v[126:129], v[146:149], v[190:193], v[126:129]
	v_mfma_f32_16x16x32_bf16 v[122:125], v[166:169], v[190:193], v[122:125]
	v_mfma_f32_16x16x32_bf16 v[110:113], v[146:149], v[202:205], v[110:113]
	v_mfma_f32_16x16x32_bf16 v[106:109], v[166:169], v[202:205], v[106:109]
	v_mfma_f32_16x16x32_bf16 v[94:97], v[146:149], v[210:213], v[94:97]
	v_mfma_f32_16x16x32_bf16 v[90:93], v[166:169], v[210:213], v[90:93]
	v_mfma_f32_16x16x32_bf16 v[78:81], v[146:149], v[218:221], v[78:81]
	v_mfma_f32_16x16x32_bf16 v[74:77], v[166:169], v[218:221], v[74:77]
	v_mfma_f32_16x16x32_bf16 v[126:129], v[158:161], v[194:197], v[126:129]
	v_mfma_f32_16x16x32_bf16 v[122:125], v[170:173], v[194:197], v[122:125]
	v_mfma_f32_16x16x32_bf16 v[110:113], v[158:161], v[206:209], v[110:113]
	v_mfma_f32_16x16x32_bf16 v[106:109], v[170:173], v[206:209], v[106:109]
	v_mfma_f32_16x16x32_bf16 v[94:97], v[158:161], v[214:217], v[94:97]
	v_mfma_f32_16x16x32_bf16 v[90:93], v[170:173], v[214:217], v[90:93]
	v_mfma_f32_16x16x32_bf16 v[78:81], v[158:161], v[222:225], v[78:81]
	v_mfma_f32_16x16x32_bf16 v[74:77], v[170:173], v[222:225], v[74:77]
	s_setprio 0
	s_setprio 1
	v_mfma_f32_16x16x32_bf16 v[118:121], v[174:177], v[190:193], v[118:121]
	v_mfma_f32_16x16x32_bf16 v[114:117], v[182:185], v[190:193], v[114:117]
	v_mfma_f32_16x16x32_bf16 v[102:105], v[174:177], v[202:205], v[102:105]
	v_mfma_f32_16x16x32_bf16 v[98:101], v[182:185], v[202:205], v[98:101]
	v_mfma_f32_16x16x32_bf16 v[86:89], v[174:177], v[210:213], v[86:89]
	v_mfma_f32_16x16x32_bf16 v[82:85], v[182:185], v[210:213], v[82:85]
	v_mfma_f32_16x16x32_bf16 v[70:73], v[174:177], v[218:221], v[70:73]
	v_mfma_f32_16x16x32_bf16 v[66:69], v[182:185], v[218:221], v[66:69]
	v_mfma_f32_16x16x32_bf16 v[118:121], v[178:181], v[194:197], v[118:121]
	v_mfma_f32_16x16x32_bf16 v[114:117], v[186:189], v[194:197], v[114:117]
	v_mfma_f32_16x16x32_bf16 v[102:105], v[178:181], v[206:209], v[102:105]
	v_mfma_f32_16x16x32_bf16 v[98:101], v[186:189], v[206:209], v[98:101]
	v_mfma_f32_16x16x32_bf16 v[86:89], v[178:181], v[214:217], v[86:89]
	v_mfma_f32_16x16x32_bf16 v[82:85], v[186:189], v[214:217], v[82:85]
	v_mfma_f32_16x16x32_bf16 v[70:73], v[178:181], v[222:225], v[70:73]
	v_mfma_f32_16x16x32_bf16 v[66:69], v[186:189], v[222:225], v[66:69]
	s_setprio 0
	s_barrier
	s_add_i32 s36, s36, s69
	v_lshl_add_u64 v[150:151], v[150:151], 0, s[16:17]
	s_mov_b32 m0, s36
	ds_read_b128 v[190:193], v156 offset:49152
	ds_read_b128 v[194:197], v156 offset:50176
	ds_read_b128 v[202:205], v156 offset:51200
	ds_read_b128 v[206:209], v156 offset:52224
	ds_read_b128 v[210:213], v156 offset:53248
	ds_read_b128 v[214:217], v156 offset:54272
	ds_read_b128 v[218:221], v156 offset:55296
	ds_read_b128 v[222:225], v156 offset:56320
	global_load_lds_dwordx4 v[150:151], off
	s_add_i32 m0, s36, 0x2000
	s_add_u32 s64, s64, 0x100080
	v_lshl_add_u64 v[150:151], v[198:199], 0, s[16:17]
	s_addc_u32 s65, s65, 0
	s_add_i32 s36, s37, s69
	global_load_lds_dwordx4 v[150:151], off
	v_lshl_add_u64 v[150:151], s[64:65], 0, v[132:133]
	s_mov_b32 m0, s36
	s_nop 0
	global_load_lds_dwordx4 v[150:151], off
	v_lshl_add_u64 v[150:151], s[64:65], 0, v[136:137]
	s_add_i32 m0, s36, 0x2000
	s_nop 0
	global_load_lds_dwordx4 v[150:151], off
	v_lshl_add_u64 v[150:151], v[226:227], 0, s[16:17]
	s_mov_b32 m0, s78
	s_nop 0
	global_load_lds_dwordx4 v[150:151], off
	v_lshl_add_u64 v[150:151], v[228:229], 0, s[16:17]
	s_mov_b32 m0, s79
	s_nop 0
	global_load_lds_dwordx4 v[150:151], off
	s_waitcnt vmcnt(8)
	s_waitcnt lgkmcnt(0)
	s_barrier
	s_setprio 1
	s_waitcnt lgkmcnt(0)
	v_mfma_f32_16x16x32_bf16 v[62:65], v[146:149], v[190:193], v[62:65]
	v_mfma_f32_16x16x32_bf16 v[58:61], v[166:169], v[190:193], v[58:61]
	v_mfma_f32_16x16x32_bf16 v[46:49], v[146:149], v[202:205], v[46:49]
	v_mfma_f32_16x16x32_bf16 v[42:45], v[166:169], v[202:205], v[42:45]
	v_mfma_f32_16x16x32_bf16 v[30:33], v[146:149], v[210:213], v[30:33]
	v_mfma_f32_16x16x32_bf16 v[26:29], v[166:169], v[210:213], v[26:29]
	v_mfma_f32_16x16x32_bf16 v[14:17], v[146:149], v[218:221], v[14:17]
	v_mfma_f32_16x16x32_bf16 v[10:13], v[166:169], v[218:221], v[10:13]
	v_mfma_f32_16x16x32_bf16 v[62:65], v[158:161], v[194:197], v[62:65]
	v_mfma_f32_16x16x32_bf16 v[58:61], v[170:173], v[194:197], v[58:61]
	v_mfma_f32_16x16x32_bf16 v[46:49], v[158:161], v[206:209], v[46:49]
	v_mfma_f32_16x16x32_bf16 v[42:45], v[170:173], v[206:209], v[42:45]
	v_mfma_f32_16x16x32_bf16 v[30:33], v[158:161], v[214:217], v[30:33]
	v_mfma_f32_16x16x32_bf16 v[26:29], v[170:173], v[214:217], v[26:29]
	v_mfma_f32_16x16x32_bf16 v[14:17], v[158:161], v[222:225], v[14:17]
	v_mfma_f32_16x16x32_bf16 v[10:13], v[170:173], v[222:225], v[10:13]
	s_setprio 0
	s_setprio 1
	v_mfma_f32_16x16x32_bf16 v[54:57], v[174:177], v[190:193], v[54:57]
	v_mfma_f32_16x16x32_bf16 v[50:53], v[182:185], v[190:193], v[50:53]
	v_mfma_f32_16x16x32_bf16 v[38:41], v[174:177], v[202:205], v[38:41]
	v_mfma_f32_16x16x32_bf16 v[34:37], v[182:185], v[202:205], v[34:37]
	v_mfma_f32_16x16x32_bf16 v[22:25], v[174:177], v[210:213], v[22:25]
	v_mfma_f32_16x16x32_bf16 v[18:21], v[182:185], v[210:213], v[18:21]
	v_mfma_f32_16x16x32_bf16 v[6:9], v[174:177], v[218:221], v[6:9]
	v_mfma_f32_16x16x32_bf16 v[2:5], v[182:185], v[218:221], v[2:5]
	v_mfma_f32_16x16x32_bf16 v[54:57], v[178:181], v[194:197], v[54:57]
	v_mfma_f32_16x16x32_bf16 v[50:53], v[186:189], v[194:197], v[50:53]
	v_mfma_f32_16x16x32_bf16 v[38:41], v[178:181], v[206:209], v[38:41]
	v_mfma_f32_16x16x32_bf16 v[34:37], v[186:189], v[206:209], v[34:37]
	v_mfma_f32_16x16x32_bf16 v[22:25], v[178:181], v[214:217], v[22:25]
	v_mfma_f32_16x16x32_bf16 v[18:21], v[186:189], v[214:217], v[18:21]
	v_mfma_f32_16x16x32_bf16 v[6:9], v[178:181], v[222:225], v[6:9]
	v_mfma_f32_16x16x32_bf16 v[2:5], v[186:189], v[222:225], v[2:5]
	s_setprio 0
	s_barrier
	s_add_u32 s62, s62, 0x100
	s_addc_u32 s63, s63, 0
	s_add_u32 s61, s61, 0x100
	s_addc_u32 s92, s92, 0
	s_cmp_ge_i32 s93, s11
	s_mov_b32 s44, s93
	s_cbranch_scc0 .LBB0_1397
	s_and_b64 vcc, exec, s[18:19]
	s_cbranch_vccz .LBB0_1400

.LBB0_1631:
	ds_read_b128 v[166:169], v158
	ds_read_b128 v[170:173], v158 offset:1024
	ds_read_b128 v[174:177], v158 offset:2048
	ds_read_b128 v[178:181], v158 offset:3072
	ds_read_b128 v[182:185], v159
	ds_read_b128 v[186:189], v159 offset:1024
	ds_read_b128 v[190:193], v159 offset:2048
	ds_read_b128 v[194:197], v159 offset:3072
	s_add_u32 s36, s54, 0xfff00080
	s_addc_u32 s37, s55, -1
	s_cmp_eq_u32 s78, 60
	s_cselect_b32 s59, s21, s37
	s_cselect_b32 s58, s74, s36
	s_cselect_b32 s57, s19, s77
	s_cselect_b32 s56, s75, s76
	v_lshl_add_u64 v[198:199], s[54:55], 0, v[140:141]
	s_add_i32 m0, s53, 0xc000
	ds_read_b128 v[202:205], v160
	ds_read_b128 v[206:209], v160 offset:1024
	ds_read_b128 v[210:213], v160 offset:2048
	ds_read_b128 v[214:217], v160 offset:3072
	ds_read_b128 v[218:221], v160 offset:4096
	ds_read_b128 v[222:225], v160 offset:5120
	ds_read_b128 v[226:229], v160 offset:6144
	ds_read_b128 v[230:233], v160 offset:7168
	global_load_lds_dwordx4 v[198:199], off
	v_lshl_add_u64 v[198:199], s[54:55], 0, v[142:143]
	s_add_i32 m0, s53, 0xe000
	s_nop 0
	global_load_lds_dwordx4 v[198:199], off
	s_waitcnt vmcnt(8)
	s_waitcnt lgkmcnt(0)
	s_barrier
	s_setprio 1
	s_waitcnt lgkmcnt(0)
	v_mfma_f32_16x16x32_bf16 v[126:129], v[166:169], v[202:205], v[126:129]
	v_mfma_f32_16x16x32_bf16 v[122:125], v[174:177], v[202:205], v[122:125]
	v_mfma_f32_16x16x32_bf16 v[118:121], v[166:169], v[210:213], v[118:121]
	v_mfma_f32_16x16x32_bf16 v[110:113], v[174:177], v[210:213], v[110:113]
	v_mfma_f32_16x16x32_bf16 v[102:105], v[166:169], v[218:221], v[102:105]
	v_mfma_f32_16x16x32_bf16 v[94:97], v[174:177], v[218:221], v[94:97]
	v_mfma_f32_16x16x32_bf16 v[86:89], v[166:169], v[226:229], v[86:89]
	v_mfma_f32_16x16x32_bf16 v[78:81], v[174:177], v[226:229], v[78:81]
	v_mfma_f32_16x16x32_bf16 v[126:129], v[170:173], v[206:209], v[126:129]
	v_mfma_f32_16x16x32_bf16 v[122:125], v[178:181], v[206:209], v[122:125]
	v_mfma_f32_16x16x32_bf16 v[118:121], v[170:173], v[214:217], v[118:121]
	v_mfma_f32_16x16x32_bf16 v[110:113], v[178:181], v[214:217], v[110:113]
	v_mfma_f32_16x16x32_bf16 v[102:105], v[170:173], v[222:225], v[102:105]
	v_mfma_f32_16x16x32_bf16 v[94:97], v[178:181], v[222:225], v[94:97]
	v_mfma_f32_16x16x32_bf16 v[86:89], v[170:173], v[230:233], v[86:89]
	v_mfma_f32_16x16x32_bf16 v[78:81], v[178:181], v[230:233], v[78:81]
	s_setprio 0
	s_setprio 1
	v_mfma_f32_16x16x32_bf16 v[114:117], v[182:185], v[202:205], v[114:117]
	v_mfma_f32_16x16x32_bf16 v[106:109], v[190:193], v[202:205], v[106:109]
	v_mfma_f32_16x16x32_bf16 v[98:101], v[182:185], v[210:213], v[98:101]
	v_mfma_f32_16x16x32_bf16 v[90:93], v[190:193], v[210:213], v[90:93]
	v_mfma_f32_16x16x32_bf16 v[82:85], v[182:185], v[218:221], v[82:85]
	v_mfma_f32_16x16x32_bf16 v[74:77], v[190:193], v[218:221], v[74:77]
	v_mfma_f32_16x16x32_bf16 v[70:73], v[182:185], v[226:229], v[70:73]
	v_mfma_f32_16x16x32_bf16 v[66:69], v[190:193], v[226:229], v[66:69]
	v_mfma_f32_16x16x32_bf16 v[114:117], v[186:189], v[206:209], v[114:117]
	v_mfma_f32_16x16x32_bf16 v[106:109], v[194:197], v[206:209], v[106:109]
	v_mfma_f32_16x16x32_bf16 v[98:101], v[186:189], v[214:217], v[98:101]
	v_mfma_f32_16x16x32_bf16 v[90:93], v[194:197], v[214:217], v[90:93]
	v_mfma_f32_16x16x32_bf16 v[82:85], v[186:189], v[222:225], v[82:85]
	v_mfma_f32_16x16x32_bf16 v[74:77], v[194:197], v[222:225], v[74:77]
	v_mfma_f32_16x16x32_bf16 v[70:73], v[186:189], v[230:233], v[70:73]
	v_mfma_f32_16x16x32_bf16 v[66:69], v[194:197], v[230:233], v[66:69]
	s_setprio 0
	s_barrier
	s_add_i32 s36, s68, s38
	v_lshl_add_u64 v[198:199], s[56:57], 0, v[136:137]
	s_mov_b32 m0, s36
	ds_read_b128 v[202:205], v160 offset:16384
	ds_read_b128 v[206:209], v160 offset:17408
	ds_read_b128 v[210:213], v160 offset:18432
	ds_read_b128 v[214:217], v160 offset:19456
	ds_read_b128 v[218:221], v160 offset:20480
	ds_read_b128 v[222:225], v160 offset:21504
	ds_read_b128 v[226:229], v160 offset:22528
	ds_read_b128 v[230:233], v160 offset:23552
	global_load_lds_dwordx4 v[198:199], off
	s_add_i32 m0, s36, 0x2000
	s_add_u32 s80, s56, 0x100000
	v_lshl_add_u64 v[234:235], s[56:57], 0, v[132:133]
	s_addc_u32 s81, s57, 0
	s_add_i32 s36, s69, s38
	global_load_lds_dwordx4 v[234:235], off
	v_lshl_add_u64 v[236:237], s[80:81], 0, v[136:137]
	s_mov_b32 m0, s36
	v_lshl_add_u64 v[238:239], s[58:59], 0, v[134:135]
	global_load_lds_dwordx4 v[236:237], off
	v_lshl_add_u64 v[236:237], s[80:81], 0, v[132:133]
	s_add_i32 m0, s36, 0x2000
	s_nop 0
	global_load_lds_dwordx4 v[236:237], off
	s_waitcnt vmcnt(6)
	s_waitcnt lgkmcnt(0)
	s_barrier
	s_setprio 1
	s_waitcnt lgkmcnt(0)
	v_mfma_f32_16x16x32_bf16 v[62:65], v[166:169], v[202:205], v[62:65]
	v_mfma_f32_16x16x32_bf16 v[58:61], v[174:177], v[202:205], v[58:61]
	v_mfma_f32_16x16x32_bf16 v[54:57], v[166:169], v[210:213], v[54:57]
	v_mfma_f32_16x16x32_bf16 v[46:49], v[174:177], v[210:213], v[46:49]
	v_mfma_f32_16x16x32_bf16 v[38:41], v[166:169], v[218:221], v[38:41]
	v_mfma_f32_16x16x32_bf16 v[30:33], v[174:177], v[218:221], v[30:33]
	v_mfma_f32_16x16x32_bf16 v[22:25], v[166:169], v[226:229], v[22:25]
	v_mfma_f32_16x16x32_bf16 v[14:17], v[174:177], v[226:229], v[14:17]
	v_mfma_f32_16x16x32_bf16 v[62:65], v[170:173], v[206:209], v[62:65]
	v_mfma_f32_16x16x32_bf16 v[58:61], v[178:181], v[206:209], v[58:61]
	v_mfma_f32_16x16x32_bf16 v[54:57], v[170:173], v[214:217], v[54:57]
	v_mfma_f32_16x16x32_bf16 v[46:49], v[178:181], v[214:217], v[46:49]
	v_mfma_f32_16x16x32_bf16 v[38:41], v[170:173], v[222:225], v[38:41]
	v_mfma_f32_16x16x32_bf16 v[30:33], v[178:181], v[222:225], v[30:33]
	v_mfma_f32_16x16x32_bf16 v[22:25], v[170:173], v[230:233], v[22:25]
	v_mfma_f32_16x16x32_bf16 v[14:17], v[178:181], v[230:233], v[14:17]
	s_setprio 0
	s_setprio 1
	v_mfma_f32_16x16x32_bf16 v[50:53], v[182:185], v[202:205], v[50:53]
	v_mfma_f32_16x16x32_bf16 v[42:45], v[190:193], v[202:205], v[42:45]
	v_mfma_f32_16x16x32_bf16 v[34:37], v[182:185], v[210:213], v[34:37]
	v_mfma_f32_16x16x32_bf16 v[26:29], v[190:193], v[210:213], v[26:29]
	v_mfma_f32_16x16x32_bf16 v[18:21], v[182:185], v[218:221], v[18:21]
	v_mfma_f32_16x16x32_bf16 v[10:13], v[190:193], v[218:221], v[10:13]
	v_mfma_f32_16x16x32_bf16 v[6:9], v[182:185], v[226:229], v[6:9]
	v_mfma_f32_16x16x32_bf16 v[2:5], v[190:193], v[226:229], v[2:5]
	v_mfma_f32_16x16x32_bf16 v[50:53], v[186:189], v[206:209], v[50:53]
	v_mfma_f32_16x16x32_bf16 v[42:45], v[194:197], v[206:209], v[42:45]
	v_mfma_f32_16x16x32_bf16 v[34:37], v[186:189], v[214:217], v[34:37]
	v_mfma_f32_16x16x32_bf16 v[26:29], v[194:197], v[214:217], v[26:29]
	v_mfma_f32_16x16x32_bf16 v[18:21], v[186:189], v[222:225], v[18:21]
	v_mfma_f32_16x16x32_bf16 v[10:13], v[194:197], v[222:225], v[10:13]
	v_mfma_f32_16x16x32_bf16 v[6:9], v[186:189], v[230:233], v[6:9]
	v_mfma_f32_16x16x32_bf16 v[2:5], v[194:197], v[230:233], v[2:5]
	s_setprio 0
	s_barrier
	s_add_i32 s36, 0, 0x18000
	v_add_u32_e32 v161, s36, v156
	s_add_i32 s37, 0, 0x1c000
	ds_read_b128 v[166:169], v161
	ds_read_b128 v[170:173], v161 offset:1024
	ds_read_b128 v[174:177], v161 offset:2048
	ds_read_b128 v[178:181], v161 offset:3072
	v_add_u32_e32 v161, s37, v156
	ds_read_b128 v[182:185], v161
	ds_read_b128 v[186:189], v161 offset:1024
	ds_read_b128 v[190:193], v161 offset:2048
	ds_read_b128 v[194:197], v161 offset:3072
	v_lshl_add_u64 v[236:237], s[58:59], 0, v[138:139]
	s_mov_b32 m0, s53
	s_nop 0
	global_load_lds_dwordx4 v[236:237], off
	s_mov_b32 m0, s61
	s_nop 0
	global_load_lds_dwordx4 v[238:239], off
	s_add_u32 s58, s58, 0x100000
	s_addc_u32 s59, s59, 0
	s_mov_b32 m0, s62
	v_lshl_add_u64 v[240:241], s[58:59], 0, v[138:139]
	ds_read_b128 v[202:205], v160 offset:32768
	ds_read_b128 v[206:209], v160 offset:33792
	ds_read_b128 v[210:213], v160 offset:34816
	ds_read_b128 v[214:217], v160 offset:35840
	ds_read_b128 v[218:221], v160 offset:36864
	ds_read_b128 v[222:225], v160 offset:37888
	ds_read_b128 v[226:229], v160 offset:38912
	ds_read_b128 v[230:233], v160 offset:39936
	global_load_lds_dwordx4 v[240:241], off
	v_lshl_add_u64 v[240:241], s[58:59], 0, v[134:135]
	s_mov_b32 m0, s63
	s_nop 0
	global_load_lds_dwordx4 v[240:241], off
	s_waitcnt vmcnt(8)
	s_waitcnt lgkmcnt(0)
	s_barrier
	s_setprio 1
	s_waitcnt lgkmcnt(0)
	v_mfma_f32_16x16x32_bf16 v[126:129], v[166:169], v[202:205], v[126:129]
	v_mfma_f32_16x16x32_bf16 v[122:125], v[174:177], v[202:205], v[122:125]
	v_mfma_f32_16x16x32_bf16 v[118:121], v[166:169], v[210:213], v[118:121]
	v_mfma_f32_16x16x32_bf16 v[110:113], v[174:177], v[210:213], v[110:113]
	v_mfma_f32_16x16x32_bf16 v[102:105], v[166:169], v[218:221], v[102:105]
	v_mfma_f32_16x16x32_bf16 v[94:97], v[174:177], v[218:221], v[94:97]
	v_mfma_f32_16x16x32_bf16 v[86:89], v[166:169], v[226:229], v[86:89]
	v_mfma_f32_16x16x32_bf16 v[78:81], v[174:177], v[226:229], v[78:81]
	v_mfma_f32_16x16x32_bf16 v[126:129], v[170:173], v[206:209], v[126:129]
	v_mfma_f32_16x16x32_bf16 v[122:125], v[178:181], v[206:209], v[122:125]
	v_mfma_f32_16x16x32_bf16 v[118:121], v[170:173], v[214:217], v[118:121]
	v_mfma_f32_16x16x32_bf16 v[110:113], v[178:181], v[214:217], v[110:113]
	v_mfma_f32_16x16x32_bf16 v[102:105], v[170:173], v[222:225], v[102:105]
	v_mfma_f32_16x16x32_bf16 v[94:97], v[178:181], v[222:225], v[94:97]
	v_mfma_f32_16x16x32_bf16 v[86:89], v[170:173], v[230:233], v[86:89]
	v_mfma_f32_16x16x32_bf16 v[78:81], v[178:181], v[230:233], v[78:81]
	s_setprio 0
	s_setprio 1
	v_mfma_f32_16x16x32_bf16 v[114:117], v[182:185], v[202:205], v[114:117]
	v_mfma_f32_16x16x32_bf16 v[106:109], v[190:193], v[202:205], v[106:109]
	v_mfma_f32_16x16x32_bf16 v[98:101], v[182:185], v[210:213], v[98:101]
	v_mfma_f32_16x16x32_bf16 v[90:93], v[190:193], v[210:213], v[90:93]
	v_mfma_f32_16x16x32_bf16 v[82:85], v[182:185], v[218:221], v[82:85]
	v_mfma_f32_16x16x32_bf16 v[74:77], v[190:193], v[218:221], v[74:77]
	v_mfma_f32_16x16x32_bf16 v[70:73], v[182:185], v[226:229], v[70:73]
	v_mfma_f32_16x16x32_bf16 v[66:69], v[190:193], v[226:229], v[66:69]
	v_mfma_f32_16x16x32_bf16 v[114:117], v[186:189], v[206:209], v[114:117]
	v_mfma_f32_16x16x32_bf16 v[106:109], v[194:197], v[206:209], v[106:109]
	v_mfma_f32_16x16x32_bf16 v[98:101], v[186:189], v[214:217], v[98:101]
	v_mfma_f32_16x16x32_bf16 v[90:93], v[194:197], v[214:217], v[90:93]
	v_mfma_f32_16x16x32_bf16 v[82:85], v[186:189], v[222:225], v[82:85]
	v_mfma_f32_16x16x32_bf16 v[74:77], v[194:197], v[222:225], v[74:77]
	v_mfma_f32_16x16x32_bf16 v[70:73], v[186:189], v[230:233], v[70:73]
	v_mfma_f32_16x16x32_bf16 v[66:69], v[194:197], v[230:233], v[66:69]
	s_setprio 0
	s_barrier
	s_add_i32 s36, s36, s38
	v_lshl_add_u64 v[198:199], v[198:199], 0, s[14:15]
	s_mov_b32 m0, s36
	ds_read_b128 v[202:205], v160 offset:49152
	ds_read_b128 v[206:209], v160 offset:50176
	ds_read_b128 v[210:213], v160 offset:51200
	ds_read_b128 v[214:217], v160 offset:52224
	ds_read_b128 v[218:221], v160 offset:53248
	ds_read_b128 v[222:225], v160 offset:54272
	ds_read_b128 v[226:229], v160 offset:55296
	ds_read_b128 v[230:233], v160 offset:56320
	global_load_lds_dwordx4 v[198:199], off
	s_add_i32 m0, s36, 0x2000
	s_add_u32 s56, s56, 0x100080
	v_lshl_add_u64 v[198:199], v[234:235], 0, s[14:15]
	s_addc_u32 s57, s57, 0
	s_add_i32 s36, s37, s38
	global_load_lds_dwordx4 v[198:199], off
	v_lshl_add_u64 v[198:199], s[56:57], 0, v[136:137]
	s_mov_b32 m0, s36
	s_nop 0
	global_load_lds_dwordx4 v[198:199], off
	v_lshl_add_u64 v[198:199], s[56:57], 0, v[132:133]
	s_add_i32 m0, s36, 0x2000
	s_nop 0
	global_load_lds_dwordx4 v[198:199], off
	v_lshl_add_u64 v[198:199], v[236:237], 0, s[14:15]
	s_mov_b32 m0, s65
	s_nop 0
	global_load_lds_dwordx4 v[198:199], off
	v_lshl_add_u64 v[198:199], v[238:239], 0, s[14:15]
	s_mov_b32 m0, s66
	s_nop 0
	global_load_lds_dwordx4 v[198:199], off
	s_waitcnt vmcnt(8)
	s_waitcnt lgkmcnt(0)
	s_barrier
	s_setprio 1
	s_waitcnt lgkmcnt(0)
	v_mfma_f32_16x16x32_bf16 v[62:65], v[166:169], v[202:205], v[62:65]
	v_mfma_f32_16x16x32_bf16 v[58:61], v[174:177], v[202:205], v[58:61]
	v_mfma_f32_16x16x32_bf16 v[54:57], v[166:169], v[210:213], v[54:57]
	v_mfma_f32_16x16x32_bf16 v[46:49], v[174:177], v[210:213], v[46:49]
	v_mfma_f32_16x16x32_bf16 v[38:41], v[166:169], v[218:221], v[38:41]
	v_mfma_f32_16x16x32_bf16 v[30:33], v[174:177], v[218:221], v[30:33]
	v_mfma_f32_16x16x32_bf16 v[22:25], v[166:169], v[226:229], v[22:25]
	v_mfma_f32_16x16x32_bf16 v[14:17], v[174:177], v[226:229], v[14:17]
	v_mfma_f32_16x16x32_bf16 v[62:65], v[170:173], v[206:209], v[62:65]
	v_mfma_f32_16x16x32_bf16 v[58:61], v[178:181], v[206:209], v[58:61]
	v_mfma_f32_16x16x32_bf16 v[54:57], v[170:173], v[214:217], v[54:57]
	v_mfma_f32_16x16x32_bf16 v[46:49], v[178:181], v[214:217], v[46:49]
	v_mfma_f32_16x16x32_bf16 v[38:41], v[170:173], v[222:225], v[38:41]
	v_mfma_f32_16x16x32_bf16 v[30:33], v[178:181], v[222:225], v[30:33]
	v_mfma_f32_16x16x32_bf16 v[22:25], v[170:173], v[230:233], v[22:25]
	v_mfma_f32_16x16x32_bf16 v[14:17], v[178:181], v[230:233], v[14:17]
	s_setprio 0
	s_setprio 1
	v_mfma_f32_16x16x32_bf16 v[50:53], v[182:185], v[202:205], v[50:53]
	v_mfma_f32_16x16x32_bf16 v[42:45], v[190:193], v[202:205], v[42:45]
	v_mfma_f32_16x16x32_bf16 v[34:37], v[182:185], v[210:213], v[34:37]
	v_mfma_f32_16x16x32_bf16 v[26:29], v[190:193], v[210:213], v[26:29]
	v_mfma_f32_16x16x32_bf16 v[18:21], v[182:185], v[218:221], v[18:21]
	v_mfma_f32_16x16x32_bf16 v[10:13], v[190:193], v[218:221], v[10:13]
	v_mfma_f32_16x16x32_bf16 v[6:9], v[182:185], v[226:229], v[6:9]
	v_mfma_f32_16x16x32_bf16 v[2:5], v[190:193], v[226:229], v[2:5]
	v_mfma_f32_16x16x32_bf16 v[50:53], v[186:189], v[206:209], v[50:53]
	v_mfma_f32_16x16x32_bf16 v[42:45], v[194:197], v[206:209], v[42:45]
	v_mfma_f32_16x16x32_bf16 v[34:37], v[186:189], v[214:217], v[34:37]
	v_mfma_f32_16x16x32_bf16 v[26:29], v[194:197], v[214:217], v[26:29]
	v_mfma_f32_16x16x32_bf16 v[18:21], v[186:189], v[222:225], v[18:21]
	v_mfma_f32_16x16x32_bf16 v[10:13], v[194:197], v[222:225], v[10:13]
	v_mfma_f32_16x16x32_bf16 v[6:9], v[186:189], v[230:233], v[6:9]
	v_mfma_f32_16x16x32_bf16 v[2:5], v[194:197], v[230:233], v[2:5]
	s_setprio 0
	s_barrier
	s_add_i32 s78, s78, 2
	s_add_u32 s54, s54, 0x100
	s_addc_u32 s55, s55, 0
	s_add_u32 s76, s76, 0x100
	s_addc_u32 s77, s77, 0
	s_cmp_gt_u32 s78, 61
	s_cbranch_scc0 .LBB0_1631
	s_and_b64 vcc, exec, s[16:17]
	s_cbranch_vccz .LBB0_1634
	s_barrier

.LBB0_1649:
	s_add_u32 s36, s56, s44
	s_addc_u32 s37, s57, 0
	s_add_u32 s64, s36, 0x100
	s_addc_u32 s65, s37, 0
	s_and_b64 s[62:63], s[60:61], exec
	s_cselect_b32 s65, s21, s65
	s_cselect_b32 s64, s87, s64
	s_add_u32 s44, s54, s44
	s_addc_u32 s62, s55, 0
	s_add_u32 s44, s44, 0x100
	s_addc_u32 s62, s62, 0
	s_and_b64 s[60:61], s[60:61], exec
	s_cselect_b32 s67, s19, s62
	s_cselect_b32 s66, s89, s44
	s_add_u32 s70, s36, 0x10080
	s_addc_u32 s71, s37, 0
	s_add_i32 vcc_lo, s84, s39
	ds_read_b128 v[158:161], v147
	ds_read_b128 v[166:169], v147 offset:1024
	ds_read_b128 v[170:173], v147 offset:2048
	ds_read_b128 v[174:177], v147 offset:3072
	ds_read_b128 v[178:181], v155
	ds_read_b128 v[182:185], v155 offset:1024
	ds_read_b128 v[186:189], v155 offset:2048
	ds_read_b128 v[190:193], v155 offset:3072
	s_add_i32 m0, s53, 0xc000
	s_add_i32 vcc_hi, s53, 0xe000
	s_add_i32 s95, vcc_lo, 0x2000
	s_add_u32 s68, s66, 0x10000
	s_addc_u32 s69, s67, 0
	s_add_i32 s97, s85, s39
	s_add_i32 s96, s97, 0x2000
	s_add_i32 s94, 0, 0x18000
	s_add_i32 s93, 0, 0x1c000
	s_add_u32 s62, s64, 0x10000
	s_addc_u32 s63, s65, 0
	s_add_i32 s92, s94, s39
	s_add_i32 s90, s92, 0x2000
	s_add_u32 s60, s66, 0x10080
	s_addc_u32 s61, s67, 0
	s_add_i32 s91, s93, s39
	s_add_i32 s44, s91, 0x2000
	v_lshl_add_u64 v[198:199], s[70:71], 0, v[138:139]
	ds_read_b128 v[194:197], v156
	ds_read_b128 v[202:205], v156 offset:1024
	ds_read_b128 v[206:209], v156 offset:2048
	ds_read_b128 v[210:213], v156 offset:3072
	ds_read_b128 v[214:217], v156 offset:4096
	ds_read_b128 v[218:221], v156 offset:5120
	ds_read_b128 v[222:225], v156 offset:6144
	ds_read_b128 v[226:229], v156 offset:7168
	global_load_lds_dwordx4 v[198:199], off
	v_lshl_add_u64 v[198:199], s[70:71], 0, v[134:135]
	s_mov_b32 m0, vcc_hi
	s_nop 0
	global_load_lds_dwordx4 v[198:199], off
	s_waitcnt vmcnt(8)
	s_waitcnt lgkmcnt(0)
	s_barrier
	s_setprio 1
	s_waitcnt lgkmcnt(0)
	v_mfma_f32_16x16x32_bf16 v[126:129], v[158:161], v[194:197], v[126:129]
	v_mfma_f32_16x16x32_bf16 v[122:125], v[170:173], v[194:197], v[122:125]
	v_mfma_f32_16x16x32_bf16 v[118:121], v[158:161], v[206:209], v[118:121]
	v_mfma_f32_16x16x32_bf16 v[110:113], v[170:173], v[206:209], v[110:113]
	v_mfma_f32_16x16x32_bf16 v[102:105], v[158:161], v[214:217], v[102:105]
	v_mfma_f32_16x16x32_bf16 v[94:97], v[170:173], v[214:217], v[94:97]
	v_mfma_f32_16x16x32_bf16 v[86:89], v[158:161], v[222:225], v[86:89]
	v_mfma_f32_16x16x32_bf16 v[78:81], v[170:173], v[222:225], v[78:81]
	v_mfma_f32_16x16x32_bf16 v[126:129], v[166:169], v[202:205], v[126:129]
	v_mfma_f32_16x16x32_bf16 v[122:125], v[174:177], v[202:205], v[122:125]
	v_mfma_f32_16x16x32_bf16 v[118:121], v[166:169], v[210:213], v[118:121]
	v_mfma_f32_16x16x32_bf16 v[110:113], v[174:177], v[210:213], v[110:113]
	v_mfma_f32_16x16x32_bf16 v[102:105], v[166:169], v[218:221], v[102:105]
	v_mfma_f32_16x16x32_bf16 v[94:97], v[174:177], v[218:221], v[94:97]
	v_mfma_f32_16x16x32_bf16 v[86:89], v[166:169], v[226:229], v[86:89]
	v_mfma_f32_16x16x32_bf16 v[78:81], v[174:177], v[226:229], v[78:81]
	s_setprio 0
	s_setprio 1
	v_mfma_f32_16x16x32_bf16 v[114:117], v[178:181], v[194:197], v[114:117]
	v_mfma_f32_16x16x32_bf16 v[106:109], v[186:189], v[194:197], v[106:109]
	v_mfma_f32_16x16x32_bf16 v[98:101], v[178:181], v[206:209], v[98:101]
	v_mfma_f32_16x16x32_bf16 v[90:93], v[186:189], v[206:209], v[90:93]
	v_mfma_f32_16x16x32_bf16 v[82:85], v[178:181], v[214:217], v[82:85]
	v_mfma_f32_16x16x32_bf16 v[74:77], v[186:189], v[214:217], v[74:77]
	v_mfma_f32_16x16x32_bf16 v[70:73], v[178:181], v[222:225], v[70:73]
	v_mfma_f32_16x16x32_bf16 v[66:69], v[186:189], v[222:225], v[66:69]
	v_mfma_f32_16x16x32_bf16 v[114:117], v[182:185], v[202:205], v[114:117]
	v_mfma_f32_16x16x32_bf16 v[106:109], v[190:193], v[202:205], v[106:109]
	v_mfma_f32_16x16x32_bf16 v[98:101], v[182:185], v[210:213], v[98:101]
	v_mfma_f32_16x16x32_bf16 v[90:93], v[190:193], v[210:213], v[90:93]
	v_mfma_f32_16x16x32_bf16 v[82:85], v[182:185], v[218:221], v[82:85]
	v_mfma_f32_16x16x32_bf16 v[74:77], v[190:193], v[218:221], v[74:77]
	v_mfma_f32_16x16x32_bf16 v[70:73], v[182:185], v[226:229], v[70:73]
	v_mfma_f32_16x16x32_bf16 v[66:69], v[190:193], v[226:229], v[66:69]
	s_setprio 0
	s_barrier
	s_mov_b32 m0, vcc_lo
	v_lshl_add_u64 v[198:199], s[66:67], 0, v[136:137]
	ds_read_b128 v[194:197], v156 offset:16384
	ds_read_b128 v[202:205], v156 offset:17408
	ds_read_b128 v[206:209], v156 offset:18432
	ds_read_b128 v[210:213], v156 offset:19456
	ds_read_b128 v[214:217], v156 offset:20480
	ds_read_b128 v[218:221], v156 offset:21504
	ds_read_b128 v[222:225], v156 offset:22528
	ds_read_b128 v[226:229], v156 offset:23552
	global_load_lds_dwordx4 v[198:199], off
	v_lshl_add_u64 v[230:231], s[66:67], 0, v[132:133]
	s_mov_b32 m0, s95
	v_lshl_add_u64 v[232:233], s[68:69], 0, v[136:137]
	global_load_lds_dwordx4 v[230:231], off
	s_mov_b32 m0, s97
	v_lshl_add_u64 v[234:235], s[64:65], 0, v[134:135]
	global_load_lds_dwordx4 v[232:233], off
	v_lshl_add_u64 v[232:233], s[68:69], 0, v[132:133]
	s_mov_b32 m0, s96
	s_nop 0
	global_load_lds_dwordx4 v[232:233], off
	s_waitcnt vmcnt(6)
	s_waitcnt lgkmcnt(0)
	s_barrier
	s_setprio 1
	s_waitcnt lgkmcnt(0)
	v_mfma_f32_16x16x32_bf16 v[62:65], v[158:161], v[194:197], v[62:65]
	v_mfma_f32_16x16x32_bf16 v[58:61], v[170:173], v[194:197], v[58:61]
	v_mfma_f32_16x16x32_bf16 v[54:57], v[158:161], v[206:209], v[54:57]
	v_mfma_f32_16x16x32_bf16 v[46:49], v[170:173], v[206:209], v[46:49]
	v_mfma_f32_16x16x32_bf16 v[38:41], v[158:161], v[214:217], v[38:41]
	v_mfma_f32_16x16x32_bf16 v[30:33], v[170:173], v[214:217], v[30:33]
	v_mfma_f32_16x16x32_bf16 v[22:25], v[158:161], v[222:225], v[22:25]
	v_mfma_f32_16x16x32_bf16 v[14:17], v[170:173], v[222:225], v[14:17]
	v_mfma_f32_16x16x32_bf16 v[62:65], v[166:169], v[202:205], v[62:65]
	v_mfma_f32_16x16x32_bf16 v[58:61], v[174:177], v[202:205], v[58:61]
	v_mfma_f32_16x16x32_bf16 v[54:57], v[166:169], v[210:213], v[54:57]
	v_mfma_f32_16x16x32_bf16 v[46:49], v[174:177], v[210:213], v[46:49]
	v_mfma_f32_16x16x32_bf16 v[38:41], v[166:169], v[218:221], v[38:41]
	v_mfma_f32_16x16x32_bf16 v[30:33], v[174:177], v[218:221], v[30:33]
	v_mfma_f32_16x16x32_bf16 v[22:25], v[166:169], v[226:229], v[22:25]
	v_mfma_f32_16x16x32_bf16 v[14:17], v[174:177], v[226:229], v[14:17]
	s_setprio 0
	s_setprio 1
	v_mfma_f32_16x16x32_bf16 v[50:53], v[178:181], v[194:197], v[50:53]
	v_mfma_f32_16x16x32_bf16 v[42:45], v[186:189], v[194:197], v[42:45]
	v_mfma_f32_16x16x32_bf16 v[34:37], v[178:181], v[206:209], v[34:37]
	v_mfma_f32_16x16x32_bf16 v[26:29], v[186:189], v[206:209], v[26:29]
	v_mfma_f32_16x16x32_bf16 v[18:21], v[178:181], v[214:217], v[18:21]
	v_mfma_f32_16x16x32_bf16 v[10:13], v[186:189], v[214:217], v[10:13]
	v_mfma_f32_16x16x32_bf16 v[6:9], v[178:181], v[222:225], v[6:9]
	v_mfma_f32_16x16x32_bf16 v[2:5], v[186:189], v[222:225], v[2:5]
	v_mfma_f32_16x16x32_bf16 v[50:53], v[182:185], v[202:205], v[50:53]
	v_mfma_f32_16x16x32_bf16 v[42:45], v[190:193], v[202:205], v[42:45]
	v_mfma_f32_16x16x32_bf16 v[34:37], v[182:185], v[210:213], v[34:37]
	v_mfma_f32_16x16x32_bf16 v[26:29], v[190:193], v[210:213], v[26:29]
	v_mfma_f32_16x16x32_bf16 v[18:21], v[182:185], v[218:221], v[18:21]
	v_mfma_f32_16x16x32_bf16 v[10:13], v[190:193], v[218:221], v[10:13]
	v_mfma_f32_16x16x32_bf16 v[6:9], v[182:185], v[226:229], v[6:9]
	v_mfma_f32_16x16x32_bf16 v[2:5], v[190:193], v[226:229], v[2:5]
	s_setprio 0
	s_barrier
	v_add_u32_e32 v157, s94, v145
	ds_read_b128 v[158:161], v157
	ds_read_b128 v[166:169], v157 offset:1024
	ds_read_b128 v[170:173], v157 offset:2048
	ds_read_b128 v[174:177], v157 offset:3072
	v_add_u32_e32 v157, s93, v145
	ds_read_b128 v[178:181], v157
	ds_read_b128 v[182:185], v157 offset:1024
	ds_read_b128 v[186:189], v157 offset:2048
	ds_read_b128 v[190:193], v157 offset:3072
	v_lshl_add_u64 v[232:233], s[64:65], 0, v[138:139]
	s_mov_b32 m0, s53
	s_nop 0
	global_load_lds_dwordx4 v[232:233], off
	s_mov_b32 m0, s75
	s_nop 0
	global_load_lds_dwordx4 v[234:235], off
	s_mov_b32 m0, s76
	v_lshl_add_u64 v[236:237], s[62:63], 0, v[138:139]
	ds_read_b128 v[194:197], v156 offset:32768
	ds_read_b128 v[202:205], v156 offset:33792
	ds_read_b128 v[206:209], v156 offset:34816
	ds_read_b128 v[210:213], v156 offset:35840
	ds_read_b128 v[214:217], v156 offset:36864
	ds_read_b128 v[218:221], v156 offset:37888
	ds_read_b128 v[222:225], v156 offset:38912
	ds_read_b128 v[226:229], v156 offset:39936
	global_load_lds_dwordx4 v[236:237], off
	v_lshl_add_u64 v[236:237], s[62:63], 0, v[134:135]
	s_mov_b32 m0, s77
	s_nop 0
	global_load_lds_dwordx4 v[236:237], off
	s_waitcnt vmcnt(8)
	s_waitcnt lgkmcnt(0)
	s_barrier
	s_setprio 1
	s_waitcnt lgkmcnt(0)
	v_mfma_f32_16x16x32_bf16 v[126:129], v[158:161], v[194:197], v[126:129]
	v_mfma_f32_16x16x32_bf16 v[122:125], v[170:173], v[194:197], v[122:125]
	v_mfma_f32_16x16x32_bf16 v[118:121], v[158:161], v[206:209], v[118:121]
	v_mfma_f32_16x16x32_bf16 v[110:113], v[170:173], v[206:209], v[110:113]
	v_mfma_f32_16x16x32_bf16 v[102:105], v[158:161], v[214:217], v[102:105]
	v_mfma_f32_16x16x32_bf16 v[94:97], v[170:173], v[214:217], v[94:97]
	v_mfma_f32_16x16x32_bf16 v[86:89], v[158:161], v[222:225], v[86:89]
	v_mfma_f32_16x16x32_bf16 v[78:81], v[170:173], v[222:225], v[78:81]
	v_mfma_f32_16x16x32_bf16 v[126:129], v[166:169], v[202:205], v[126:129]
	v_mfma_f32_16x16x32_bf16 v[122:125], v[174:177], v[202:205], v[122:125]
	v_mfma_f32_16x16x32_bf16 v[118:121], v[166:169], v[210:213], v[118:121]
	v_mfma_f32_16x16x32_bf16 v[110:113], v[174:177], v[210:213], v[110:113]
	v_mfma_f32_16x16x32_bf16 v[102:105], v[166:169], v[218:221], v[102:105]
	v_mfma_f32_16x16x32_bf16 v[94:97], v[174:177], v[218:221], v[94:97]
	v_mfma_f32_16x16x32_bf16 v[86:89], v[166:169], v[226:229], v[86:89]
	v_mfma_f32_16x16x32_bf16 v[78:81], v[174:177], v[226:229], v[78:81]
	s_setprio 0
	s_setprio 1
	v_mfma_f32_16x16x32_bf16 v[114:117], v[178:181], v[194:197], v[114:117]
	v_mfma_f32_16x16x32_bf16 v[106:109], v[186:189], v[194:197], v[106:109]
	v_mfma_f32_16x16x32_bf16 v[98:101], v[178:181], v[206:209], v[98:101]
	v_mfma_f32_16x16x32_bf16 v[90:93], v[186:189], v[206:209], v[90:93]
	v_mfma_f32_16x16x32_bf16 v[82:85], v[178:181], v[214:217], v[82:85]
	v_mfma_f32_16x16x32_bf16 v[74:77], v[186:189], v[214:217], v[74:77]
	v_mfma_f32_16x16x32_bf16 v[70:73], v[178:181], v[222:225], v[70:73]
	v_mfma_f32_16x16x32_bf16 v[66:69], v[186:189], v[222:225], v[66:69]
	v_mfma_f32_16x16x32_bf16 v[114:117], v[182:185], v[202:205], v[114:117]
	v_mfma_f32_16x16x32_bf16 v[106:109], v[190:193], v[202:205], v[106:109]
	v_mfma_f32_16x16x32_bf16 v[98:101], v[182:185], v[210:213], v[98:101]
	v_mfma_f32_16x16x32_bf16 v[90:93], v[190:193], v[210:213], v[90:93]
	v_mfma_f32_16x16x32_bf16 v[82:85], v[182:185], v[218:221], v[82:85]
	v_mfma_f32_16x16x32_bf16 v[74:77], v[190:193], v[218:221], v[74:77]
	v_mfma_f32_16x16x32_bf16 v[70:73], v[182:185], v[226:229], v[70:73]
	v_mfma_f32_16x16x32_bf16 v[66:69], v[190:193], v[226:229], v[66:69]
	s_setprio 0
	s_barrier
	s_mov_b32 m0, s92
	v_lshl_add_u64 v[198:199], v[198:199], 0, s[14:15]
	ds_read_b128 v[194:197], v156 offset:49152
	ds_read_b128 v[202:205], v156 offset:50176
	ds_read_b128 v[206:209], v156 offset:51200
	ds_read_b128 v[210:213], v156 offset:52224
	ds_read_b128 v[214:217], v156 offset:53248
	ds_read_b128 v[218:221], v156 offset:54272
	ds_read_b128 v[222:225], v156 offset:55296
	ds_read_b128 v[226:229], v156 offset:56320
	global_load_lds_dwordx4 v[198:199], off
	v_lshl_add_u64 v[198:199], v[230:231], 0, s[14:15]
	s_mov_b32 m0, s90
	s_nop 0
	global_load_lds_dwordx4 v[198:199], off
	v_lshl_add_u64 v[198:199], s[60:61], 0, v[136:137]
	s_mov_b32 m0, s91
	s_nop 0
	global_load_lds_dwordx4 v[198:199], off
	v_lshl_add_u64 v[198:199], s[60:61], 0, v[132:133]
	s_mov_b32 m0, s44
	s_nop 0
	global_load_lds_dwordx4 v[198:199], off
	v_lshl_add_u64 v[198:199], v[232:233], 0, s[14:15]
	s_mov_b32 m0, s80
	s_nop 0
	global_load_lds_dwordx4 v[198:199], off
	v_lshl_add_u64 v[198:199], v[234:235], 0, s[14:15]
	s_mov_b32 m0, s81
	s_nop 0
	global_load_lds_dwordx4 v[198:199], off
	s_waitcnt vmcnt(8)
	s_waitcnt lgkmcnt(0)
	s_barrier
	s_setprio 1
	s_waitcnt lgkmcnt(0)
	v_mfma_f32_16x16x32_bf16 v[62:65], v[158:161], v[194:197], v[62:65]
	v_mfma_f32_16x16x32_bf16 v[58:61], v[170:173], v[194:197], v[58:61]
	v_mfma_f32_16x16x32_bf16 v[54:57], v[158:161], v[206:209], v[54:57]
	v_mfma_f32_16x16x32_bf16 v[46:49], v[170:173], v[206:209], v[46:49]
	v_mfma_f32_16x16x32_bf16 v[38:41], v[158:161], v[214:217], v[38:41]
	v_mfma_f32_16x16x32_bf16 v[30:33], v[170:173], v[214:217], v[30:33]
	v_mfma_f32_16x16x32_bf16 v[22:25], v[158:161], v[222:225], v[22:25]
	v_mfma_f32_16x16x32_bf16 v[14:17], v[170:173], v[222:225], v[14:17]
	v_mfma_f32_16x16x32_bf16 v[62:65], v[166:169], v[202:205], v[62:65]
	v_mfma_f32_16x16x32_bf16 v[58:61], v[174:177], v[202:205], v[58:61]
	v_mfma_f32_16x16x32_bf16 v[54:57], v[166:169], v[210:213], v[54:57]
	v_mfma_f32_16x16x32_bf16 v[46:49], v[174:177], v[210:213], v[46:49]
	v_mfma_f32_16x16x32_bf16 v[38:41], v[166:169], v[218:221], v[38:41]
	v_mfma_f32_16x16x32_bf16 v[30:33], v[174:177], v[218:221], v[30:33]
	v_mfma_f32_16x16x32_bf16 v[22:25], v[166:169], v[226:229], v[22:25]
	v_mfma_f32_16x16x32_bf16 v[14:17], v[174:177], v[226:229], v[14:17]
	s_setprio 0
	s_setprio 1
	v_mfma_f32_16x16x32_bf16 v[50:53], v[178:181], v[194:197], v[50:53]
	v_mfma_f32_16x16x32_bf16 v[42:45], v[186:189], v[194:197], v[42:45]
	v_mfma_f32_16x16x32_bf16 v[34:37], v[178:181], v[206:209], v[34:37]
	v_mfma_f32_16x16x32_bf16 v[26:29], v[186:189], v[206:209], v[26:29]
	v_mfma_f32_16x16x32_bf16 v[18:21], v[178:181], v[214:217], v[18:21]
	v_mfma_f32_16x16x32_bf16 v[10:13], v[186:189], v[214:217], v[10:13]
	v_mfma_f32_16x16x32_bf16 v[6:9], v[178:181], v[222:225], v[6:9]
	v_mfma_f32_16x16x32_bf16 v[2:5], v[186:189], v[222:225], v[2:5]
	v_mfma_f32_16x16x32_bf16 v[50:53], v[182:185], v[202:205], v[50:53]
	v_mfma_f32_16x16x32_bf16 v[42:45], v[190:193], v[202:205], v[42:45]
	v_mfma_f32_16x16x32_bf16 v[34:37], v[182:185], v[210:213], v[34:37]
	v_mfma_f32_16x16x32_bf16 v[26:29], v[190:193], v[210:213], v[26:29]
	v_mfma_f32_16x16x32_bf16 v[18:21], v[182:185], v[218:221], v[18:21]
	v_mfma_f32_16x16x32_bf16 v[10:13], v[190:193], v[218:221], v[10:13]
	v_mfma_f32_16x16x32_bf16 v[6:9], v[182:185], v[226:229], v[6:9]
	v_mfma_f32_16x16x32_bf16 v[2:5], v[190:193], v[226:229], v[2:5]
	s_setprio 0
	s_barrier
	s_movk_i32 s44, 0x100
	s_andn2_b64 vcc, exec, s[58:59]
	s_mov_b64 s[60:61], -1
	s_mov_b64 s[58:59], 0
	s_cbranch_vccz .LBB0_1649
	s_and_b64 vcc, exec, s[16:17]
	s_cbranch_vccz .LBB0_1652
	s_barrier

.LBB0_1667:
	s_add_u32 s36, s56, s44
	s_addc_u32 s37, s57, 0
	s_add_u32 s64, s36, 0x100
	s_addc_u32 s65, s37, 0
	s_and_b64 s[62:63], s[60:61], exec
	s_cselect_b32 s65, s21, s65
	s_cselect_b32 s64, s86, s64
	s_add_u32 s44, s54, s44
	s_addc_u32 s62, s55, 0
	s_add_u32 s44, s44, 0x100
	s_addc_u32 s62, s62, 0
	s_and_b64 s[60:61], s[60:61], exec
	s_cselect_b32 s67, s19, s62
	s_cselect_b32 s66, s87, s44
	s_add_u32 s70, s36, 0x10080
	s_addc_u32 s71, s37, 0
	s_add_i32 s97, s82, s38
	ds_read_b128 v[150:153], v146
	ds_read_b128 v[154:157], v146 offset:1024
	ds_read_b128 v[158:161], v146 offset:2048
	ds_read_b128 v[166:169], v146 offset:3072
	ds_read_b128 v[170:173], v147
	ds_read_b128 v[174:177], v147 offset:1024
	ds_read_b128 v[178:181], v147 offset:2048
	ds_read_b128 v[182:185], v147 offset:3072
	s_add_i32 m0, s53, 0xc000
	s_add_i32 vcc_lo, s53, 0xe000
	s_add_i32 s94, s97, 0x2000
	s_add_u32 s68, s66, 0x10000
	s_addc_u32 s69, s67, 0
	s_add_i32 s96, s83, s38
	s_add_i32 s95, s96, 0x2000
	s_add_i32 s93, 0, 0x18000
	s_add_i32 s92, 0, 0x1c000
	s_add_u32 s62, s64, 0x10000
	s_addc_u32 s63, s65, 0
	s_add_i32 s91, s93, s38
	s_add_i32 s89, s91, 0x2000
	s_add_u32 s60, s66, 0x10080
	s_addc_u32 s61, s67, 0
	s_add_i32 s90, s92, s38
	s_add_i32 s44, s90, 0x2000
	v_lshl_add_u64 v[198:199], s[70:71], 0, v[138:139]
	ds_read_b128 v[186:189], v148
	ds_read_b128 v[190:193], v148 offset:1024
	ds_read_b128 v[194:197], v148 offset:2048
	ds_read_b128 v[202:205], v148 offset:3072
	ds_read_b128 v[206:209], v148 offset:4096
	ds_read_b128 v[210:213], v148 offset:5120
	ds_read_b128 v[214:217], v148 offset:6144
	ds_read_b128 v[218:221], v148 offset:7168
	global_load_lds_dwordx4 v[198:199], off
	v_lshl_add_u64 v[198:199], s[70:71], 0, v[134:135]
	s_mov_b32 m0, vcc_lo
	s_nop 0
	global_load_lds_dwordx4 v[198:199], off
	s_waitcnt vmcnt(8)
	s_waitcnt lgkmcnt(0)
	s_barrier
	s_setprio 1
	s_waitcnt lgkmcnt(0)
	v_mfma_f32_16x16x32_bf16 v[126:129], v[150:153], v[186:189], v[126:129]
	v_mfma_f32_16x16x32_bf16 v[122:125], v[158:161], v[186:189], v[122:125]
	v_mfma_f32_16x16x32_bf16 v[118:121], v[150:153], v[194:197], v[118:121]
	v_mfma_f32_16x16x32_bf16 v[110:113], v[158:161], v[194:197], v[110:113]
	v_mfma_f32_16x16x32_bf16 v[102:105], v[150:153], v[206:209], v[102:105]
	v_mfma_f32_16x16x32_bf16 v[94:97], v[158:161], v[206:209], v[94:97]
	v_mfma_f32_16x16x32_bf16 v[86:89], v[150:153], v[214:217], v[86:89]
	v_mfma_f32_16x16x32_bf16 v[78:81], v[158:161], v[214:217], v[78:81]
	v_mfma_f32_16x16x32_bf16 v[126:129], v[154:157], v[190:193], v[126:129]
	v_mfma_f32_16x16x32_bf16 v[122:125], v[166:169], v[190:193], v[122:125]
	v_mfma_f32_16x16x32_bf16 v[118:121], v[154:157], v[202:205], v[118:121]
	v_mfma_f32_16x16x32_bf16 v[110:113], v[166:169], v[202:205], v[110:113]
	v_mfma_f32_16x16x32_bf16 v[102:105], v[154:157], v[210:213], v[102:105]
	v_mfma_f32_16x16x32_bf16 v[94:97], v[166:169], v[210:213], v[94:97]
	v_mfma_f32_16x16x32_bf16 v[86:89], v[154:157], v[218:221], v[86:89]
	v_mfma_f32_16x16x32_bf16 v[78:81], v[166:169], v[218:221], v[78:81]
	s_setprio 0
	s_setprio 1
	v_mfma_f32_16x16x32_bf16 v[114:117], v[170:173], v[186:189], v[114:117]
	v_mfma_f32_16x16x32_bf16 v[106:109], v[178:181], v[186:189], v[106:109]
	v_mfma_f32_16x16x32_bf16 v[98:101], v[170:173], v[194:197], v[98:101]
	v_mfma_f32_16x16x32_bf16 v[90:93], v[178:181], v[194:197], v[90:93]
	v_mfma_f32_16x16x32_bf16 v[82:85], v[170:173], v[206:209], v[82:85]
	v_mfma_f32_16x16x32_bf16 v[74:77], v[178:181], v[206:209], v[74:77]
	v_mfma_f32_16x16x32_bf16 v[70:73], v[170:173], v[214:217], v[70:73]
	v_mfma_f32_16x16x32_bf16 v[66:69], v[178:181], v[214:217], v[66:69]
	v_mfma_f32_16x16x32_bf16 v[114:117], v[174:177], v[190:193], v[114:117]
	v_mfma_f32_16x16x32_bf16 v[106:109], v[182:185], v[190:193], v[106:109]
	v_mfma_f32_16x16x32_bf16 v[98:101], v[174:177], v[202:205], v[98:101]
	v_mfma_f32_16x16x32_bf16 v[90:93], v[182:185], v[202:205], v[90:93]
	v_mfma_f32_16x16x32_bf16 v[82:85], v[174:177], v[210:213], v[82:85]
	v_mfma_f32_16x16x32_bf16 v[74:77], v[182:185], v[210:213], v[74:77]
	v_mfma_f32_16x16x32_bf16 v[70:73], v[174:177], v[218:221], v[70:73]
	v_mfma_f32_16x16x32_bf16 v[66:69], v[182:185], v[218:221], v[66:69]
	s_setprio 0
	s_barrier
	s_mov_b32 m0, s97
	v_lshl_add_u64 v[198:199], s[66:67], 0, v[136:137]
	ds_read_b128 v[186:189], v148 offset:16384
	ds_read_b128 v[190:193], v148 offset:17408
	ds_read_b128 v[194:197], v148 offset:18432
	ds_read_b128 v[202:205], v148 offset:19456
	ds_read_b128 v[206:209], v148 offset:20480
	ds_read_b128 v[210:213], v148 offset:21504
	ds_read_b128 v[214:217], v148 offset:22528
	ds_read_b128 v[218:221], v148 offset:23552
	global_load_lds_dwordx4 v[198:199], off
	v_lshl_add_u64 v[222:223], s[66:67], 0, v[132:133]
	s_mov_b32 m0, s94
	v_lshl_add_u64 v[224:225], s[68:69], 0, v[136:137]
	global_load_lds_dwordx4 v[222:223], off
	s_mov_b32 m0, s96
	v_lshl_add_u64 v[226:227], s[64:65], 0, v[134:135]
	global_load_lds_dwordx4 v[224:225], off
	v_lshl_add_u64 v[224:225], s[68:69], 0, v[132:133]
	s_mov_b32 m0, s95
	s_nop 0
	global_load_lds_dwordx4 v[224:225], off
	s_waitcnt vmcnt(6)
	s_waitcnt lgkmcnt(0)
	s_barrier
	s_setprio 1
	s_waitcnt lgkmcnt(0)
	v_mfma_f32_16x16x32_bf16 v[62:65], v[150:153], v[186:189], v[62:65]
	v_mfma_f32_16x16x32_bf16 v[58:61], v[158:161], v[186:189], v[58:61]
	v_mfma_f32_16x16x32_bf16 v[54:57], v[150:153], v[194:197], v[54:57]
	v_mfma_f32_16x16x32_bf16 v[46:49], v[158:161], v[194:197], v[46:49]
	v_mfma_f32_16x16x32_bf16 v[38:41], v[150:153], v[206:209], v[38:41]
	v_mfma_f32_16x16x32_bf16 v[30:33], v[158:161], v[206:209], v[30:33]
	v_mfma_f32_16x16x32_bf16 v[22:25], v[150:153], v[214:217], v[22:25]
	v_mfma_f32_16x16x32_bf16 v[14:17], v[158:161], v[214:217], v[14:17]
	v_mfma_f32_16x16x32_bf16 v[62:65], v[154:157], v[190:193], v[62:65]
	v_mfma_f32_16x16x32_bf16 v[58:61], v[166:169], v[190:193], v[58:61]
	v_mfma_f32_16x16x32_bf16 v[54:57], v[154:157], v[202:205], v[54:57]
	v_mfma_f32_16x16x32_bf16 v[46:49], v[166:169], v[202:205], v[46:49]
	v_mfma_f32_16x16x32_bf16 v[38:41], v[154:157], v[210:213], v[38:41]
	v_mfma_f32_16x16x32_bf16 v[30:33], v[166:169], v[210:213], v[30:33]
	v_mfma_f32_16x16x32_bf16 v[22:25], v[154:157], v[218:221], v[22:25]
	v_mfma_f32_16x16x32_bf16 v[14:17], v[166:169], v[218:221], v[14:17]
	s_setprio 0
	s_setprio 1
	v_mfma_f32_16x16x32_bf16 v[50:53], v[170:173], v[186:189], v[50:53]
	v_mfma_f32_16x16x32_bf16 v[42:45], v[178:181], v[186:189], v[42:45]
	v_mfma_f32_16x16x32_bf16 v[34:37], v[170:173], v[194:197], v[34:37]
	v_mfma_f32_16x16x32_bf16 v[26:29], v[178:181], v[194:197], v[26:29]
	v_mfma_f32_16x16x32_bf16 v[18:21], v[170:173], v[206:209], v[18:21]
	v_mfma_f32_16x16x32_bf16 v[10:13], v[178:181], v[206:209], v[10:13]
	v_mfma_f32_16x16x32_bf16 v[6:9], v[170:173], v[214:217], v[6:9]
	v_mfma_f32_16x16x32_bf16 v[2:5], v[178:181], v[214:217], v[2:5]
	v_mfma_f32_16x16x32_bf16 v[50:53], v[174:177], v[190:193], v[50:53]
	v_mfma_f32_16x16x32_bf16 v[42:45], v[182:185], v[190:193], v[42:45]
	v_mfma_f32_16x16x32_bf16 v[34:37], v[174:177], v[202:205], v[34:37]
	v_mfma_f32_16x16x32_bf16 v[26:29], v[182:185], v[202:205], v[26:29]
	v_mfma_f32_16x16x32_bf16 v[18:21], v[174:177], v[210:213], v[18:21]
	v_mfma_f32_16x16x32_bf16 v[10:13], v[182:185], v[210:213], v[10:13]
	v_mfma_f32_16x16x32_bf16 v[6:9], v[174:177], v[218:221], v[6:9]
	v_mfma_f32_16x16x32_bf16 v[2:5], v[182:185], v[218:221], v[2:5]
	s_setprio 0
	s_barrier
	v_add_u32_e32 v149, s93, v145
	ds_read_b128 v[150:153], v149
	ds_read_b128 v[154:157], v149 offset:1024
	ds_read_b128 v[158:161], v149 offset:2048
	ds_read_b128 v[166:169], v149 offset:3072
	v_add_u32_e32 v149, s92, v145
	ds_read_b128 v[170:173], v149
	ds_read_b128 v[174:177], v149 offset:1024
	ds_read_b128 v[178:181], v149 offset:2048
	ds_read_b128 v[182:185], v149 offset:3072
	v_lshl_add_u64 v[224:225], s[64:65], 0, v[138:139]
	s_mov_b32 m0, s53
	s_nop 0
	global_load_lds_dwordx4 v[224:225], off
	s_mov_b32 m0, s75
	s_nop 0
	global_load_lds_dwordx4 v[226:227], off
	s_mov_b32 m0, s76
	v_lshl_add_u64 v[228:229], s[62:63], 0, v[138:139]
	ds_read_b128 v[186:189], v148 offset:32768
	ds_read_b128 v[190:193], v148 offset:33792
	ds_read_b128 v[194:197], v148 offset:34816
	ds_read_b128 v[202:205], v148 offset:35840
	ds_read_b128 v[206:209], v148 offset:36864
	ds_read_b128 v[210:213], v148 offset:37888
	ds_read_b128 v[214:217], v148 offset:38912
	ds_read_b128 v[218:221], v148 offset:39936
	global_load_lds_dwordx4 v[228:229], off
	v_lshl_add_u64 v[228:229], s[62:63], 0, v[134:135]
	s_mov_b32 m0, s77
	s_nop 0
	global_load_lds_dwordx4 v[228:229], off
	s_waitcnt vmcnt(8)
	s_waitcnt lgkmcnt(0)
	s_barrier
	s_setprio 1
	s_waitcnt lgkmcnt(0)
	v_mfma_f32_16x16x32_bf16 v[126:129], v[150:153], v[186:189], v[126:129]
	v_mfma_f32_16x16x32_bf16 v[122:125], v[158:161], v[186:189], v[122:125]
	v_mfma_f32_16x16x32_bf16 v[118:121], v[150:153], v[194:197], v[118:121]
	v_mfma_f32_16x16x32_bf16 v[110:113], v[158:161], v[194:197], v[110:113]
	v_mfma_f32_16x16x32_bf16 v[102:105], v[150:153], v[206:209], v[102:105]
	v_mfma_f32_16x16x32_bf16 v[94:97], v[158:161], v[206:209], v[94:97]
	v_mfma_f32_16x16x32_bf16 v[86:89], v[150:153], v[214:217], v[86:89]
	v_mfma_f32_16x16x32_bf16 v[78:81], v[158:161], v[214:217], v[78:81]
	v_mfma_f32_16x16x32_bf16 v[126:129], v[154:157], v[190:193], v[126:129]
	v_mfma_f32_16x16x32_bf16 v[122:125], v[166:169], v[190:193], v[122:125]
	v_mfma_f32_16x16x32_bf16 v[118:121], v[154:157], v[202:205], v[118:121]
	v_mfma_f32_16x16x32_bf16 v[110:113], v[166:169], v[202:205], v[110:113]
	v_mfma_f32_16x16x32_bf16 v[102:105], v[154:157], v[210:213], v[102:105]
	v_mfma_f32_16x16x32_bf16 v[94:97], v[166:169], v[210:213], v[94:97]
	v_mfma_f32_16x16x32_bf16 v[86:89], v[154:157], v[218:221], v[86:89]
	v_mfma_f32_16x16x32_bf16 v[78:81], v[166:169], v[218:221], v[78:81]
	s_setprio 0
	s_setprio 1
	v_mfma_f32_16x16x32_bf16 v[114:117], v[170:173], v[186:189], v[114:117]
	v_mfma_f32_16x16x32_bf16 v[106:109], v[178:181], v[186:189], v[106:109]
	v_mfma_f32_16x16x32_bf16 v[98:101], v[170:173], v[194:197], v[98:101]
	v_mfma_f32_16x16x32_bf16 v[90:93], v[178:181], v[194:197], v[90:93]
	v_mfma_f32_16x16x32_bf16 v[82:85], v[170:173], v[206:209], v[82:85]
	v_mfma_f32_16x16x32_bf16 v[74:77], v[178:181], v[206:209], v[74:77]
	v_mfma_f32_16x16x32_bf16 v[70:73], v[170:173], v[214:217], v[70:73]
	v_mfma_f32_16x16x32_bf16 v[66:69], v[178:181], v[214:217], v[66:69]
	v_mfma_f32_16x16x32_bf16 v[114:117], v[174:177], v[190:193], v[114:117]
	v_mfma_f32_16x16x32_bf16 v[106:109], v[182:185], v[190:193], v[106:109]
	v_mfma_f32_16x16x32_bf16 v[98:101], v[174:177], v[202:205], v[98:101]
	v_mfma_f32_16x16x32_bf16 v[90:93], v[182:185], v[202:205], v[90:93]
	v_mfma_f32_16x16x32_bf16 v[82:85], v[174:177], v[210:213], v[82:85]
	v_mfma_f32_16x16x32_bf16 v[74:77], v[182:185], v[210:213], v[74:77]
	v_mfma_f32_16x16x32_bf16 v[70:73], v[174:177], v[218:221], v[70:73]
	v_mfma_f32_16x16x32_bf16 v[66:69], v[182:185], v[218:221], v[66:69]
	s_setprio 0
	s_barrier
	s_mov_b32 m0, s91
	v_lshl_add_u64 v[198:199], v[198:199], 0, s[14:15]
	ds_read_b128 v[186:189], v148 offset:49152
	ds_read_b128 v[190:193], v148 offset:50176
	ds_read_b128 v[194:197], v148 offset:51200
	ds_read_b128 v[202:205], v148 offset:52224
	ds_read_b128 v[206:209], v148 offset:53248
	ds_read_b128 v[210:213], v148 offset:54272
	ds_read_b128 v[214:217], v148 offset:55296
	ds_read_b128 v[218:221], v148 offset:56320
	global_load_lds_dwordx4 v[198:199], off
	v_lshl_add_u64 v[198:199], v[222:223], 0, s[14:15]
	s_mov_b32 m0, s89
	s_nop 0
	global_load_lds_dwordx4 v[198:199], off
	v_lshl_add_u64 v[198:199], s[60:61], 0, v[136:137]
	s_mov_b32 m0, s90
	s_nop 0
	global_load_lds_dwordx4 v[198:199], off
	v_lshl_add_u64 v[198:199], s[60:61], 0, v[132:133]
	s_mov_b32 m0, s44
	s_nop 0
	global_load_lds_dwordx4 v[198:199], off
	v_lshl_add_u64 v[198:199], v[224:225], 0, s[14:15]
	s_mov_b32 m0, s79
	s_nop 0
	global_load_lds_dwordx4 v[198:199], off
	v_lshl_add_u64 v[198:199], v[226:227], 0, s[14:15]
	s_mov_b32 m0, s80
	s_nop 0
	global_load_lds_dwordx4 v[198:199], off
	s_waitcnt vmcnt(8)
	s_waitcnt lgkmcnt(0)
	s_barrier
	s_setprio 1
	s_waitcnt lgkmcnt(0)
	v_mfma_f32_16x16x32_bf16 v[62:65], v[150:153], v[186:189], v[62:65]
	v_mfma_f32_16x16x32_bf16 v[58:61], v[158:161], v[186:189], v[58:61]
	v_mfma_f32_16x16x32_bf16 v[54:57], v[150:153], v[194:197], v[54:57]
	v_mfma_f32_16x16x32_bf16 v[46:49], v[158:161], v[194:197], v[46:49]
	v_mfma_f32_16x16x32_bf16 v[38:41], v[150:153], v[206:209], v[38:41]
	v_mfma_f32_16x16x32_bf16 v[30:33], v[158:161], v[206:209], v[30:33]
	v_mfma_f32_16x16x32_bf16 v[22:25], v[150:153], v[214:217], v[22:25]
	v_mfma_f32_16x16x32_bf16 v[14:17], v[158:161], v[214:217], v[14:17]
	v_mfma_f32_16x16x32_bf16 v[62:65], v[154:157], v[190:193], v[62:65]
	v_mfma_f32_16x16x32_bf16 v[58:61], v[166:169], v[190:193], v[58:61]
	v_mfma_f32_16x16x32_bf16 v[54:57], v[154:157], v[202:205], v[54:57]
	v_mfma_f32_16x16x32_bf16 v[46:49], v[166:169], v[202:205], v[46:49]
	v_mfma_f32_16x16x32_bf16 v[38:41], v[154:157], v[210:213], v[38:41]
	v_mfma_f32_16x16x32_bf16 v[30:33], v[166:169], v[210:213], v[30:33]
	v_mfma_f32_16x16x32_bf16 v[22:25], v[154:157], v[218:221], v[22:25]
	v_mfma_f32_16x16x32_bf16 v[14:17], v[166:169], v[218:221], v[14:17]
	s_setprio 0
	s_setprio 1
	v_mfma_f32_16x16x32_bf16 v[50:53], v[170:173], v[186:189], v[50:53]
	v_mfma_f32_16x16x32_bf16 v[42:45], v[178:181], v[186:189], v[42:45]
	v_mfma_f32_16x16x32_bf16 v[34:37], v[170:173], v[194:197], v[34:37]
	v_mfma_f32_16x16x32_bf16 v[26:29], v[178:181], v[194:197], v[26:29]
	v_mfma_f32_16x16x32_bf16 v[18:21], v[170:173], v[206:209], v[18:21]
	v_mfma_f32_16x16x32_bf16 v[10:13], v[178:181], v[206:209], v[10:13]
	v_mfma_f32_16x16x32_bf16 v[6:9], v[170:173], v[214:217], v[6:9]
	v_mfma_f32_16x16x32_bf16 v[2:5], v[178:181], v[214:217], v[2:5]
	v_mfma_f32_16x16x32_bf16 v[50:53], v[174:177], v[190:193], v[50:53]
	v_mfma_f32_16x16x32_bf16 v[42:45], v[182:185], v[190:193], v[42:45]
	v_mfma_f32_16x16x32_bf16 v[34:37], v[174:177], v[202:205], v[34:37]
	v_mfma_f32_16x16x32_bf16 v[26:29], v[182:185], v[202:205], v[26:29]
	v_mfma_f32_16x16x32_bf16 v[18:21], v[174:177], v[210:213], v[18:21]
	v_mfma_f32_16x16x32_bf16 v[10:13], v[182:185], v[210:213], v[10:13]
	v_mfma_f32_16x16x32_bf16 v[6:9], v[174:177], v[218:221], v[6:9]
	v_mfma_f32_16x16x32_bf16 v[2:5], v[182:185], v[218:221], v[2:5]
	s_setprio 0
	s_barrier
	s_movk_i32 s44, 0x100
	s_andn2_b64 vcc, exec, s[58:59]
	s_mov_b64 s[60:61], -1
	s_mov_b64 s[58:59], 0
	s_cbranch_vccz .LBB0_1667
	s_and_b64 vcc, exec, s[16:17]
	s_cbranch_vccz .LBB0_1670
	s_barrier

.LBB0_1685:
	ds_read_b128 v[156:159], v153
	ds_read_b128 v[166:169], v153 offset:1024
	ds_read_b128 v[170:173], v153 offset:2048
	ds_read_b128 v[174:177], v153 offset:3072
	ds_read_b128 v[178:181], v154
	ds_read_b128 v[182:185], v154 offset:1024
	ds_read_b128 v[186:189], v154 offset:2048
	ds_read_b128 v[190:193], v154 offset:3072
	s_add_u32 s36, s56, 0xfff00080
	s_addc_u32 s37, s57, -1
	s_cmp_eq_u32 s78, 60
	s_cselect_b32 s61, s25, s37
	s_cselect_b32 s60, s74, s36
	s_cselect_b32 s59, s21, s77
	s_cselect_b32 s58, s75, s76
	v_lshl_add_u64 v[160:161], s[56:57], 0, v[140:141]
	s_add_i32 m0, s55, 0xc000
	ds_read_b128 v[194:197], v155
	ds_read_b128 v[202:205], v155 offset:1024
	ds_read_b128 v[206:209], v155 offset:2048
	ds_read_b128 v[210:213], v155 offset:3072
	ds_read_b128 v[214:217], v155 offset:4096
	ds_read_b128 v[218:221], v155 offset:5120
	ds_read_b128 v[222:225], v155 offset:6144
	ds_read_b128 v[226:229], v155 offset:7168
	global_load_lds_dwordx4 v[160:161], off
	v_lshl_add_u64 v[160:161], s[56:57], 0, v[142:143]
	s_add_i32 m0, s55, 0xe000
	s_nop 0
	global_load_lds_dwordx4 v[160:161], off
	s_waitcnt vmcnt(8)
	s_waitcnt lgkmcnt(0)
	s_barrier
	s_setprio 1
	s_waitcnt lgkmcnt(0)
	v_mfma_f32_16x16x32_bf16 v[126:129], v[156:159], v[194:197], v[126:129]
	v_mfma_f32_16x16x32_bf16 v[122:125], v[170:173], v[194:197], v[122:125]
	v_mfma_f32_16x16x32_bf16 v[118:121], v[156:159], v[206:209], v[118:121]
	v_mfma_f32_16x16x32_bf16 v[110:113], v[170:173], v[206:209], v[110:113]
	v_mfma_f32_16x16x32_bf16 v[102:105], v[156:159], v[214:217], v[102:105]
	v_mfma_f32_16x16x32_bf16 v[94:97], v[170:173], v[214:217], v[94:97]
	v_mfma_f32_16x16x32_bf16 v[86:89], v[156:159], v[222:225], v[86:89]
	v_mfma_f32_16x16x32_bf16 v[78:81], v[170:173], v[222:225], v[78:81]
	v_mfma_f32_16x16x32_bf16 v[126:129], v[166:169], v[202:205], v[126:129]
	v_mfma_f32_16x16x32_bf16 v[122:125], v[174:177], v[202:205], v[122:125]
	v_mfma_f32_16x16x32_bf16 v[118:121], v[166:169], v[210:213], v[118:121]
	v_mfma_f32_16x16x32_bf16 v[110:113], v[174:177], v[210:213], v[110:113]
	v_mfma_f32_16x16x32_bf16 v[102:105], v[166:169], v[218:221], v[102:105]
	v_mfma_f32_16x16x32_bf16 v[94:97], v[174:177], v[218:221], v[94:97]
	v_mfma_f32_16x16x32_bf16 v[86:89], v[166:169], v[226:229], v[86:89]
	v_mfma_f32_16x16x32_bf16 v[78:81], v[174:177], v[226:229], v[78:81]
	s_setprio 0
	s_setprio 1
	v_mfma_f32_16x16x32_bf16 v[114:117], v[178:181], v[194:197], v[114:117]
	v_mfma_f32_16x16x32_bf16 v[106:109], v[186:189], v[194:197], v[106:109]
	v_mfma_f32_16x16x32_bf16 v[98:101], v[178:181], v[206:209], v[98:101]
	v_mfma_f32_16x16x32_bf16 v[90:93], v[186:189], v[206:209], v[90:93]
	v_mfma_f32_16x16x32_bf16 v[82:85], v[178:181], v[214:217], v[82:85]
	v_mfma_f32_16x16x32_bf16 v[74:77], v[186:189], v[214:217], v[74:77]
	v_mfma_f32_16x16x32_bf16 v[70:73], v[178:181], v[222:225], v[70:73]
	v_mfma_f32_16x16x32_bf16 v[66:69], v[186:189], v[222:225], v[66:69]
	v_mfma_f32_16x16x32_bf16 v[114:117], v[182:185], v[202:205], v[114:117]
	v_mfma_f32_16x16x32_bf16 v[106:109], v[190:193], v[202:205], v[106:109]
	v_mfma_f32_16x16x32_bf16 v[98:101], v[182:185], v[210:213], v[98:101]
	v_mfma_f32_16x16x32_bf16 v[90:93], v[190:193], v[210:213], v[90:93]
	v_mfma_f32_16x16x32_bf16 v[82:85], v[182:185], v[218:221], v[82:85]
	v_mfma_f32_16x16x32_bf16 v[74:77], v[190:193], v[218:221], v[74:77]
	v_mfma_f32_16x16x32_bf16 v[70:73], v[182:185], v[226:229], v[70:73]
	v_mfma_f32_16x16x32_bf16 v[66:69], v[190:193], v[226:229], v[66:69]
	s_setprio 0
	s_barrier
	s_add_i32 s36, s68, s38
	v_lshl_add_u64 v[160:161], s[58:59], 0, v[136:137]
	s_mov_b32 m0, s36
	ds_read_b128 v[194:197], v155 offset:16384
	ds_read_b128 v[202:205], v155 offset:17408
	ds_read_b128 v[206:209], v155 offset:18432
	ds_read_b128 v[210:213], v155 offset:19456
	ds_read_b128 v[214:217], v155 offset:20480
	ds_read_b128 v[218:221], v155 offset:21504
	ds_read_b128 v[222:225], v155 offset:22528
	ds_read_b128 v[226:229], v155 offset:23552
	global_load_lds_dwordx4 v[160:161], off
	s_add_i32 m0, s36, 0x2000
	s_add_u32 s80, s58, 0x100000
	v_lshl_add_u64 v[198:199], s[58:59], 0, v[132:133]
	s_addc_u32 s81, s59, 0
	s_add_i32 s36, s69, s38
	global_load_lds_dwordx4 v[198:199], off
	v_lshl_add_u64 v[230:231], s[80:81], 0, v[136:137]
	s_mov_b32 m0, s36
	v_lshl_add_u64 v[232:233], s[60:61], 0, v[134:135]
	global_load_lds_dwordx4 v[230:231], off
	v_lshl_add_u64 v[230:231], s[80:81], 0, v[132:133]
	s_add_i32 m0, s36, 0x2000
	s_nop 0
	global_load_lds_dwordx4 v[230:231], off
	s_waitcnt vmcnt(6)
	s_waitcnt lgkmcnt(0)
	s_barrier
	s_setprio 1
	s_waitcnt lgkmcnt(0)
	v_mfma_f32_16x16x32_bf16 v[62:65], v[156:159], v[194:197], v[62:65]
	v_mfma_f32_16x16x32_bf16 v[58:61], v[170:173], v[194:197], v[58:61]
	v_mfma_f32_16x16x32_bf16 v[54:57], v[156:159], v[206:209], v[54:57]
	v_mfma_f32_16x16x32_bf16 v[46:49], v[170:173], v[206:209], v[46:49]
	v_mfma_f32_16x16x32_bf16 v[38:41], v[156:159], v[214:217], v[38:41]
	v_mfma_f32_16x16x32_bf16 v[30:33], v[170:173], v[214:217], v[30:33]
	v_mfma_f32_16x16x32_bf16 v[22:25], v[156:159], v[222:225], v[22:25]
	v_mfma_f32_16x16x32_bf16 v[14:17], v[170:173], v[222:225], v[14:17]
	v_mfma_f32_16x16x32_bf16 v[62:65], v[166:169], v[202:205], v[62:65]
	v_mfma_f32_16x16x32_bf16 v[58:61], v[174:177], v[202:205], v[58:61]
	v_mfma_f32_16x16x32_bf16 v[54:57], v[166:169], v[210:213], v[54:57]
	v_mfma_f32_16x16x32_bf16 v[46:49], v[174:177], v[210:213], v[46:49]
	v_mfma_f32_16x16x32_bf16 v[38:41], v[166:169], v[218:221], v[38:41]
	v_mfma_f32_16x16x32_bf16 v[30:33], v[174:177], v[218:221], v[30:33]
	v_mfma_f32_16x16x32_bf16 v[22:25], v[166:169], v[226:229], v[22:25]
	v_mfma_f32_16x16x32_bf16 v[14:17], v[174:177], v[226:229], v[14:17]
	s_setprio 0
	s_setprio 1
	v_mfma_f32_16x16x32_bf16 v[50:53], v[178:181], v[194:197], v[50:53]
	v_mfma_f32_16x16x32_bf16 v[42:45], v[186:189], v[194:197], v[42:45]
	v_mfma_f32_16x16x32_bf16 v[34:37], v[178:181], v[206:209], v[34:37]
	v_mfma_f32_16x16x32_bf16 v[26:29], v[186:189], v[206:209], v[26:29]
	v_mfma_f32_16x16x32_bf16 v[18:21], v[178:181], v[214:217], v[18:21]
	v_mfma_f32_16x16x32_bf16 v[10:13], v[186:189], v[214:217], v[10:13]
	v_mfma_f32_16x16x32_bf16 v[6:9], v[178:181], v[222:225], v[6:9]
	v_mfma_f32_16x16x32_bf16 v[2:5], v[186:189], v[222:225], v[2:5]
	v_mfma_f32_16x16x32_bf16 v[50:53], v[182:185], v[202:205], v[50:53]
	v_mfma_f32_16x16x32_bf16 v[42:45], v[190:193], v[202:205], v[42:45]
	v_mfma_f32_16x16x32_bf16 v[34:37], v[182:185], v[210:213], v[34:37]
	v_mfma_f32_16x16x32_bf16 v[26:29], v[190:193], v[210:213], v[26:29]
	v_mfma_f32_16x16x32_bf16 v[18:21], v[182:185], v[218:221], v[18:21]
	v_mfma_f32_16x16x32_bf16 v[10:13], v[190:193], v[218:221], v[10:13]
	v_mfma_f32_16x16x32_bf16 v[6:9], v[182:185], v[226:229], v[6:9]
	v_mfma_f32_16x16x32_bf16 v[2:5], v[190:193], v[226:229], v[2:5]
	s_setprio 0
	s_barrier
	s_add_i32 s36, 0, 0x18000
	v_add_u32_e32 v165, s36, v151
	s_add_i32 s37, 0, 0x1c000
	ds_read_b128 v[156:159], v165
	ds_read_b128 v[166:169], v165 offset:1024
	ds_read_b128 v[170:173], v165 offset:2048
	ds_read_b128 v[174:177], v165 offset:3072
	v_add_u32_e32 v165, s37, v151
	ds_read_b128 v[178:181], v165
	ds_read_b128 v[182:185], v165 offset:1024
	ds_read_b128 v[186:189], v165 offset:2048
	ds_read_b128 v[190:193], v165 offset:3072
	v_lshl_add_u64 v[230:231], s[60:61], 0, v[138:139]
	s_mov_b32 m0, s55
	s_nop 0
	global_load_lds_dwordx4 v[230:231], off
	s_mov_b32 m0, s63
	s_nop 0
	global_load_lds_dwordx4 v[232:233], off
	s_add_u32 s60, s60, 0x100000
	s_addc_u32 s61, s61, 0
	s_mov_b32 m0, s64
	v_lshl_add_u64 v[234:235], s[60:61], 0, v[138:139]
	ds_read_b128 v[194:197], v155 offset:32768
	ds_read_b128 v[202:205], v155 offset:33792
	ds_read_b128 v[206:209], v155 offset:34816
	ds_read_b128 v[210:213], v155 offset:35840
	ds_read_b128 v[214:217], v155 offset:36864
	ds_read_b128 v[218:221], v155 offset:37888
	ds_read_b128 v[222:225], v155 offset:38912
	ds_read_b128 v[226:229], v155 offset:39936
	global_load_lds_dwordx4 v[234:235], off
	v_lshl_add_u64 v[234:235], s[60:61], 0, v[134:135]
	s_mov_b32 m0, s65
	s_nop 0
	global_load_lds_dwordx4 v[234:235], off
	s_waitcnt vmcnt(8)
	s_waitcnt lgkmcnt(0)
	s_barrier
	s_setprio 1
	s_waitcnt lgkmcnt(0)
	v_mfma_f32_16x16x32_bf16 v[126:129], v[156:159], v[194:197], v[126:129]
	v_mfma_f32_16x16x32_bf16 v[122:125], v[170:173], v[194:197], v[122:125]
	v_mfma_f32_16x16x32_bf16 v[118:121], v[156:159], v[206:209], v[118:121]
	v_mfma_f32_16x16x32_bf16 v[110:113], v[170:173], v[206:209], v[110:113]
	v_mfma_f32_16x16x32_bf16 v[102:105], v[156:159], v[214:217], v[102:105]
	v_mfma_f32_16x16x32_bf16 v[94:97], v[170:173], v[214:217], v[94:97]
	v_mfma_f32_16x16x32_bf16 v[86:89], v[156:159], v[222:225], v[86:89]
	v_mfma_f32_16x16x32_bf16 v[78:81], v[170:173], v[222:225], v[78:81]
	v_mfma_f32_16x16x32_bf16 v[126:129], v[166:169], v[202:205], v[126:129]
	v_mfma_f32_16x16x32_bf16 v[122:125], v[174:177], v[202:205], v[122:125]
	v_mfma_f32_16x16x32_bf16 v[118:121], v[166:169], v[210:213], v[118:121]
	v_mfma_f32_16x16x32_bf16 v[110:113], v[174:177], v[210:213], v[110:113]
	v_mfma_f32_16x16x32_bf16 v[102:105], v[166:169], v[218:221], v[102:105]
	v_mfma_f32_16x16x32_bf16 v[94:97], v[174:177], v[218:221], v[94:97]
	v_mfma_f32_16x16x32_bf16 v[86:89], v[166:169], v[226:229], v[86:89]
	v_mfma_f32_16x16x32_bf16 v[78:81], v[174:177], v[226:229], v[78:81]
	s_setprio 0
	s_setprio 1
	v_mfma_f32_16x16x32_bf16 v[114:117], v[178:181], v[194:197], v[114:117]
	v_mfma_f32_16x16x32_bf16 v[106:109], v[186:189], v[194:197], v[106:109]
	v_mfma_f32_16x16x32_bf16 v[98:101], v[178:181], v[206:209], v[98:101]
	v_mfma_f32_16x16x32_bf16 v[90:93], v[186:189], v[206:209], v[90:93]
	v_mfma_f32_16x16x32_bf16 v[82:85], v[178:181], v[214:217], v[82:85]
	v_mfma_f32_16x16x32_bf16 v[74:77], v[186:189], v[214:217], v[74:77]
	v_mfma_f32_16x16x32_bf16 v[70:73], v[178:181], v[222:225], v[70:73]
	v_mfma_f32_16x16x32_bf16 v[66:69], v[186:189], v[222:225], v[66:69]
	v_mfma_f32_16x16x32_bf16 v[114:117], v[182:185], v[202:205], v[114:117]
	v_mfma_f32_16x16x32_bf16 v[106:109], v[190:193], v[202:205], v[106:109]
	v_mfma_f32_16x16x32_bf16 v[98:101], v[182:185], v[210:213], v[98:101]
	v_mfma_f32_16x16x32_bf16 v[90:93], v[190:193], v[210:213], v[90:93]
	v_mfma_f32_16x16x32_bf16 v[82:85], v[182:185], v[218:221], v[82:85]
	v_mfma_f32_16x16x32_bf16 v[74:77], v[190:193], v[218:221], v[74:77]
	v_mfma_f32_16x16x32_bf16 v[70:73], v[182:185], v[226:229], v[70:73]
	v_mfma_f32_16x16x32_bf16 v[66:69], v[190:193], v[226:229], v[66:69]
	s_setprio 0
	s_barrier
	s_add_i32 s36, s36, s38
	v_lshl_add_u64 v[160:161], v[160:161], 0, s[16:17]
	s_mov_b32 m0, s36
	ds_read_b128 v[194:197], v155 offset:49152
	ds_read_b128 v[202:205], v155 offset:50176
	ds_read_b128 v[206:209], v155 offset:51200
	ds_read_b128 v[210:213], v155 offset:52224
	ds_read_b128 v[214:217], v155 offset:53248
	ds_read_b128 v[218:221], v155 offset:54272
	ds_read_b128 v[222:225], v155 offset:55296
	ds_read_b128 v[226:229], v155 offset:56320
	global_load_lds_dwordx4 v[160:161], off
	s_add_i32 m0, s36, 0x2000
	s_add_u32 s58, s58, 0x100080
	v_lshl_add_u64 v[160:161], v[198:199], 0, s[16:17]
	s_addc_u32 s59, s59, 0
	s_add_i32 s36, s37, s38
	global_load_lds_dwordx4 v[160:161], off
	v_lshl_add_u64 v[160:161], s[58:59], 0, v[136:137]
	s_mov_b32 m0, s36
	s_nop 0
	global_load_lds_dwordx4 v[160:161], off
	v_lshl_add_u64 v[160:161], s[58:59], 0, v[132:133]
	s_add_i32 m0, s36, 0x2000
	s_nop 0
	global_load_lds_dwordx4 v[160:161], off
	v_lshl_add_u64 v[160:161], v[230:231], 0, s[16:17]
	s_mov_b32 m0, s66
	s_nop 0
	global_load_lds_dwordx4 v[160:161], off
	v_lshl_add_u64 v[160:161], v[232:233], 0, s[16:17]
	s_mov_b32 m0, s67
	s_nop 0
	global_load_lds_dwordx4 v[160:161], off
	s_waitcnt vmcnt(8)
	s_waitcnt lgkmcnt(0)
	s_barrier
	s_setprio 1
	s_waitcnt lgkmcnt(0)
	v_mfma_f32_16x16x32_bf16 v[62:65], v[156:159], v[194:197], v[62:65]
	v_mfma_f32_16x16x32_bf16 v[58:61], v[170:173], v[194:197], v[58:61]
	v_mfma_f32_16x16x32_bf16 v[54:57], v[156:159], v[206:209], v[54:57]
	v_mfma_f32_16x16x32_bf16 v[46:49], v[170:173], v[206:209], v[46:49]
	v_mfma_f32_16x16x32_bf16 v[38:41], v[156:159], v[214:217], v[38:41]
	v_mfma_f32_16x16x32_bf16 v[30:33], v[170:173], v[214:217], v[30:33]
	v_mfma_f32_16x16x32_bf16 v[22:25], v[156:159], v[222:225], v[22:25]
	v_mfma_f32_16x16x32_bf16 v[14:17], v[170:173], v[222:225], v[14:17]
	v_mfma_f32_16x16x32_bf16 v[62:65], v[166:169], v[202:205], v[62:65]
	v_mfma_f32_16x16x32_bf16 v[58:61], v[174:177], v[202:205], v[58:61]
	v_mfma_f32_16x16x32_bf16 v[54:57], v[166:169], v[210:213], v[54:57]
	v_mfma_f32_16x16x32_bf16 v[46:49], v[174:177], v[210:213], v[46:49]
	v_mfma_f32_16x16x32_bf16 v[38:41], v[166:169], v[218:221], v[38:41]
	v_mfma_f32_16x16x32_bf16 v[30:33], v[174:177], v[218:221], v[30:33]
	v_mfma_f32_16x16x32_bf16 v[22:25], v[166:169], v[226:229], v[22:25]
	v_mfma_f32_16x16x32_bf16 v[14:17], v[174:177], v[226:229], v[14:17]
	s_setprio 0
	s_setprio 1
	v_mfma_f32_16x16x32_bf16 v[50:53], v[178:181], v[194:197], v[50:53]
	v_mfma_f32_16x16x32_bf16 v[42:45], v[186:189], v[194:197], v[42:45]
	v_mfma_f32_16x16x32_bf16 v[34:37], v[178:181], v[206:209], v[34:37]
	v_mfma_f32_16x16x32_bf16 v[26:29], v[186:189], v[206:209], v[26:29]
	v_mfma_f32_16x16x32_bf16 v[18:21], v[178:181], v[214:217], v[18:21]
	v_mfma_f32_16x16x32_bf16 v[10:13], v[186:189], v[214:217], v[10:13]
	v_mfma_f32_16x16x32_bf16 v[6:9], v[178:181], v[222:225], v[6:9]
	v_mfma_f32_16x16x32_bf16 v[2:5], v[186:189], v[222:225], v[2:5]
	v_mfma_f32_16x16x32_bf16 v[50:53], v[182:185], v[202:205], v[50:53]
	v_mfma_f32_16x16x32_bf16 v[42:45], v[190:193], v[202:205], v[42:45]
	v_mfma_f32_16x16x32_bf16 v[34:37], v[182:185], v[210:213], v[34:37]
	v_mfma_f32_16x16x32_bf16 v[26:29], v[190:193], v[210:213], v[26:29]
	v_mfma_f32_16x16x32_bf16 v[18:21], v[182:185], v[218:221], v[18:21]
	v_mfma_f32_16x16x32_bf16 v[10:13], v[190:193], v[218:221], v[10:13]
	v_mfma_f32_16x16x32_bf16 v[6:9], v[182:185], v[226:229], v[6:9]
	v_mfma_f32_16x16x32_bf16 v[2:5], v[190:193], v[226:229], v[2:5]
	s_setprio 0
	s_barrier
	s_add_i32 s78, s78, 2
	s_add_u32 s56, s56, 0x100
	s_addc_u32 s57, s57, 0
	s_add_u32 s76, s76, 0x100
	s_addc_u32 s77, s77, 0
	s_cmp_gt_u32 s78, 61
	s_cbranch_scc0 .LBB0_1685
	s_and_b64 vcc, exec, s[18:19]
	s_cbranch_vccz .LBB0_1688
	s_barrier

.LBB0_1701:
	s_add_u32 s36, s56, s44
	s_addc_u32 s37, s57, 0
	s_add_u32 s64, s36, 0x100
	s_addc_u32 s65, s37, 0
	s_and_b64 s[62:63], s[60:61], exec
	s_cselect_b32 s65, s21, s65
	s_cselect_b32 s64, s86, s64
	s_add_u32 s44, s54, s44
	s_addc_u32 s62, s55, 0
	s_add_u32 s44, s44, 0x100
	s_addc_u32 s62, s62, 0
	s_and_b64 s[60:61], s[60:61], exec
	s_cselect_b32 s67, s25, s62
	s_cselect_b32 s66, s87, s44
	s_add_u32 s70, s36, 0x10080
	s_addc_u32 s71, s37, 0
	s_add_i32 s97, s81, s39
	ds_read_b128 v[152:155], v147
	ds_read_b128 v[156:159], v147 offset:1024
	ds_read_b128 v[166:169], v147 offset:2048
	ds_read_b128 v[170:173], v147 offset:3072
	ds_read_b128 v[174:177], v150
	ds_read_b128 v[178:181], v150 offset:1024
	ds_read_b128 v[182:185], v150 offset:2048
	ds_read_b128 v[186:189], v150 offset:3072
	s_add_i32 m0, s74, 0xc000
	s_add_i32 vcc_lo, s74, 0xe000
	s_add_i32 s94, s97, 0x2000
	s_add_u32 s68, s66, 0x10000
	s_addc_u32 s69, s67, 0
	s_add_i32 s96, s82, s39
	s_add_i32 s95, s96, 0x2000
	s_add_i32 s93, 0, 0x18000
	s_add_i32 s92, 0, 0x1c000
	s_add_u32 s62, s64, 0x10000
	s_addc_u32 s63, s65, 0
	s_add_i32 s91, s93, s39
	s_add_i32 s89, s91, 0x2000
	s_add_u32 s60, s66, 0x10080
	s_addc_u32 s61, s67, 0
	s_add_i32 s90, s92, s39
	s_add_i32 s44, s90, 0x2000
	v_lshl_add_u64 v[160:161], s[70:71], 0, v[138:139]
	ds_read_b128 v[190:193], v151
	ds_read_b128 v[194:197], v151 offset:1024
	ds_read_b128 v[202:205], v151 offset:2048
	ds_read_b128 v[206:209], v151 offset:3072
	ds_read_b128 v[210:213], v151 offset:4096
	ds_read_b128 v[214:217], v151 offset:5120
	ds_read_b128 v[218:221], v151 offset:6144
	ds_read_b128 v[222:225], v151 offset:7168
	global_load_lds_dwordx4 v[160:161], off
	v_lshl_add_u64 v[160:161], s[70:71], 0, v[134:135]
	s_mov_b32 m0, vcc_lo
	s_nop 0
	global_load_lds_dwordx4 v[160:161], off
	s_waitcnt vmcnt(8)
	s_waitcnt lgkmcnt(0)
	s_barrier
	s_setprio 1
	s_waitcnt lgkmcnt(0)
	v_mfma_f32_16x16x32_bf16 v[126:129], v[152:155], v[190:193], v[126:129]
	v_mfma_f32_16x16x32_bf16 v[122:125], v[166:169], v[190:193], v[122:125]
	v_mfma_f32_16x16x32_bf16 v[118:121], v[152:155], v[202:205], v[118:121]
	v_mfma_f32_16x16x32_bf16 v[110:113], v[166:169], v[202:205], v[110:113]
	v_mfma_f32_16x16x32_bf16 v[102:105], v[152:155], v[210:213], v[102:105]
	v_mfma_f32_16x16x32_bf16 v[94:97], v[166:169], v[210:213], v[94:97]
	v_mfma_f32_16x16x32_bf16 v[86:89], v[152:155], v[218:221], v[86:89]
	v_mfma_f32_16x16x32_bf16 v[78:81], v[166:169], v[218:221], v[78:81]
	v_mfma_f32_16x16x32_bf16 v[126:129], v[156:159], v[194:197], v[126:129]
	v_mfma_f32_16x16x32_bf16 v[122:125], v[170:173], v[194:197], v[122:125]
	v_mfma_f32_16x16x32_bf16 v[118:121], v[156:159], v[206:209], v[118:121]
	v_mfma_f32_16x16x32_bf16 v[110:113], v[170:173], v[206:209], v[110:113]
	v_mfma_f32_16x16x32_bf16 v[102:105], v[156:159], v[214:217], v[102:105]
	v_mfma_f32_16x16x32_bf16 v[94:97], v[170:173], v[214:217], v[94:97]
	v_mfma_f32_16x16x32_bf16 v[86:89], v[156:159], v[222:225], v[86:89]
	v_mfma_f32_16x16x32_bf16 v[78:81], v[170:173], v[222:225], v[78:81]
	s_setprio 0
	s_setprio 1
	v_mfma_f32_16x16x32_bf16 v[114:117], v[174:177], v[190:193], v[114:117]
	v_mfma_f32_16x16x32_bf16 v[106:109], v[182:185], v[190:193], v[106:109]
	v_mfma_f32_16x16x32_bf16 v[98:101], v[174:177], v[202:205], v[98:101]
	v_mfma_f32_16x16x32_bf16 v[90:93], v[182:185], v[202:205], v[90:93]
	v_mfma_f32_16x16x32_bf16 v[82:85], v[174:177], v[210:213], v[82:85]
	v_mfma_f32_16x16x32_bf16 v[74:77], v[182:185], v[210:213], v[74:77]
	v_mfma_f32_16x16x32_bf16 v[70:73], v[174:177], v[218:221], v[70:73]
	v_mfma_f32_16x16x32_bf16 v[66:69], v[182:185], v[218:221], v[66:69]
	v_mfma_f32_16x16x32_bf16 v[114:117], v[178:181], v[194:197], v[114:117]
	v_mfma_f32_16x16x32_bf16 v[106:109], v[186:189], v[194:197], v[106:109]
	v_mfma_f32_16x16x32_bf16 v[98:101], v[178:181], v[206:209], v[98:101]
	v_mfma_f32_16x16x32_bf16 v[90:93], v[186:189], v[206:209], v[90:93]
	v_mfma_f32_16x16x32_bf16 v[82:85], v[178:181], v[214:217], v[82:85]
	v_mfma_f32_16x16x32_bf16 v[74:77], v[186:189], v[214:217], v[74:77]
	v_mfma_f32_16x16x32_bf16 v[70:73], v[178:181], v[222:225], v[70:73]
	v_mfma_f32_16x16x32_bf16 v[66:69], v[186:189], v[222:225], v[66:69]
	s_setprio 0
	s_barrier
	s_mov_b32 m0, s97
	v_lshl_add_u64 v[160:161], s[66:67], 0, v[136:137]
	ds_read_b128 v[190:193], v151 offset:16384
	ds_read_b128 v[194:197], v151 offset:17408
	ds_read_b128 v[202:205], v151 offset:18432
	ds_read_b128 v[206:209], v151 offset:19456
	ds_read_b128 v[210:213], v151 offset:20480
	ds_read_b128 v[214:217], v151 offset:21504
	ds_read_b128 v[218:221], v151 offset:22528
	ds_read_b128 v[222:225], v151 offset:23552
	global_load_lds_dwordx4 v[160:161], off
	v_lshl_add_u64 v[198:199], s[66:67], 0, v[132:133]
	s_mov_b32 m0, s94
	v_lshl_add_u64 v[226:227], s[68:69], 0, v[136:137]
	global_load_lds_dwordx4 v[198:199], off
	s_mov_b32 m0, s96
	v_lshl_add_u64 v[228:229], s[64:65], 0, v[134:135]
	global_load_lds_dwordx4 v[226:227], off
	v_lshl_add_u64 v[226:227], s[68:69], 0, v[132:133]
	s_mov_b32 m0, s95
	s_nop 0
	global_load_lds_dwordx4 v[226:227], off
	s_waitcnt vmcnt(6)
	s_waitcnt lgkmcnt(0)
	s_barrier
	s_setprio 1
	s_waitcnt lgkmcnt(0)
	v_mfma_f32_16x16x32_bf16 v[62:65], v[152:155], v[190:193], v[62:65]
	v_mfma_f32_16x16x32_bf16 v[58:61], v[166:169], v[190:193], v[58:61]
	v_mfma_f32_16x16x32_bf16 v[54:57], v[152:155], v[202:205], v[54:57]
	v_mfma_f32_16x16x32_bf16 v[46:49], v[166:169], v[202:205], v[46:49]
	v_mfma_f32_16x16x32_bf16 v[38:41], v[152:155], v[210:213], v[38:41]
	v_mfma_f32_16x16x32_bf16 v[30:33], v[166:169], v[210:213], v[30:33]
	v_mfma_f32_16x16x32_bf16 v[22:25], v[152:155], v[218:221], v[22:25]
	v_mfma_f32_16x16x32_bf16 v[14:17], v[166:169], v[218:221], v[14:17]
	v_mfma_f32_16x16x32_bf16 v[62:65], v[156:159], v[194:197], v[62:65]
	v_mfma_f32_16x16x32_bf16 v[58:61], v[170:173], v[194:197], v[58:61]
	v_mfma_f32_16x16x32_bf16 v[54:57], v[156:159], v[206:209], v[54:57]
	v_mfma_f32_16x16x32_bf16 v[46:49], v[170:173], v[206:209], v[46:49]
	v_mfma_f32_16x16x32_bf16 v[38:41], v[156:159], v[214:217], v[38:41]
	v_mfma_f32_16x16x32_bf16 v[30:33], v[170:173], v[214:217], v[30:33]
	v_mfma_f32_16x16x32_bf16 v[22:25], v[156:159], v[222:225], v[22:25]
	v_mfma_f32_16x16x32_bf16 v[14:17], v[170:173], v[222:225], v[14:17]
	s_setprio 0
	s_setprio 1
	v_mfma_f32_16x16x32_bf16 v[50:53], v[174:177], v[190:193], v[50:53]
	v_mfma_f32_16x16x32_bf16 v[42:45], v[182:185], v[190:193], v[42:45]
	v_mfma_f32_16x16x32_bf16 v[34:37], v[174:177], v[202:205], v[34:37]
	v_mfma_f32_16x16x32_bf16 v[26:29], v[182:185], v[202:205], v[26:29]
	v_mfma_f32_16x16x32_bf16 v[18:21], v[174:177], v[210:213], v[18:21]
	v_mfma_f32_16x16x32_bf16 v[10:13], v[182:185], v[210:213], v[10:13]
	v_mfma_f32_16x16x32_bf16 v[6:9], v[174:177], v[218:221], v[6:9]
	v_mfma_f32_16x16x32_bf16 v[2:5], v[182:185], v[218:221], v[2:5]
	v_mfma_f32_16x16x32_bf16 v[50:53], v[178:181], v[194:197], v[50:53]
	v_mfma_f32_16x16x32_bf16 v[42:45], v[186:189], v[194:197], v[42:45]
	v_mfma_f32_16x16x32_bf16 v[34:37], v[178:181], v[206:209], v[34:37]
	v_mfma_f32_16x16x32_bf16 v[26:29], v[186:189], v[206:209], v[26:29]
	v_mfma_f32_16x16x32_bf16 v[18:21], v[178:181], v[214:217], v[18:21]
	v_mfma_f32_16x16x32_bf16 v[10:13], v[186:189], v[214:217], v[10:13]
	v_mfma_f32_16x16x32_bf16 v[6:9], v[178:181], v[222:225], v[6:9]
	v_mfma_f32_16x16x32_bf16 v[2:5], v[186:189], v[222:225], v[2:5]
	s_setprio 0
	s_barrier
	v_add_u32_e32 v165, s93, v145
	ds_read_b128 v[152:155], v165
	ds_read_b128 v[156:159], v165 offset:1024
	ds_read_b128 v[166:169], v165 offset:2048
	ds_read_b128 v[170:173], v165 offset:3072
	v_add_u32_e32 v165, s92, v145
	ds_read_b128 v[174:177], v165
	ds_read_b128 v[178:181], v165 offset:1024
	ds_read_b128 v[182:185], v165 offset:2048
	ds_read_b128 v[186:189], v165 offset:3072
	v_lshl_add_u64 v[226:227], s[64:65], 0, v[138:139]
	s_mov_b32 m0, s74
	s_nop 0
	global_load_lds_dwordx4 v[226:227], off
	s_mov_b32 m0, s75
	s_nop 0
	global_load_lds_dwordx4 v[228:229], off
	s_mov_b32 m0, s76
	v_lshl_add_u64 v[230:231], s[62:63], 0, v[138:139]
	ds_read_b128 v[190:193], v151 offset:32768
	ds_read_b128 v[194:197], v151 offset:33792
	ds_read_b128 v[202:205], v151 offset:34816
	ds_read_b128 v[206:209], v151 offset:35840
	ds_read_b128 v[210:213], v151 offset:36864
	ds_read_b128 v[214:217], v151 offset:37888
	ds_read_b128 v[218:221], v151 offset:38912
	ds_read_b128 v[222:225], v151 offset:39936
	global_load_lds_dwordx4 v[230:231], off
	v_lshl_add_u64 v[230:231], s[62:63], 0, v[134:135]
	s_mov_b32 m0, s77
	s_nop 0
	global_load_lds_dwordx4 v[230:231], off
	s_waitcnt vmcnt(8)
	s_waitcnt lgkmcnt(0)
	s_barrier
	s_setprio 1
	s_waitcnt lgkmcnt(0)
	v_mfma_f32_16x16x32_bf16 v[126:129], v[152:155], v[190:193], v[126:129]
	v_mfma_f32_16x16x32_bf16 v[122:125], v[166:169], v[190:193], v[122:125]
	v_mfma_f32_16x16x32_bf16 v[118:121], v[152:155], v[202:205], v[118:121]
	v_mfma_f32_16x16x32_bf16 v[110:113], v[166:169], v[202:205], v[110:113]
	v_mfma_f32_16x16x32_bf16 v[102:105], v[152:155], v[210:213], v[102:105]
	v_mfma_f32_16x16x32_bf16 v[94:97], v[166:169], v[210:213], v[94:97]
	v_mfma_f32_16x16x32_bf16 v[86:89], v[152:155], v[218:221], v[86:89]
	v_mfma_f32_16x16x32_bf16 v[78:81], v[166:169], v[218:221], v[78:81]
	v_mfma_f32_16x16x32_bf16 v[126:129], v[156:159], v[194:197], v[126:129]
	v_mfma_f32_16x16x32_bf16 v[122:125], v[170:173], v[194:197], v[122:125]
	v_mfma_f32_16x16x32_bf16 v[118:121], v[156:159], v[206:209], v[118:121]
	v_mfma_f32_16x16x32_bf16 v[110:113], v[170:173], v[206:209], v[110:113]
	v_mfma_f32_16x16x32_bf16 v[102:105], v[156:159], v[214:217], v[102:105]
	v_mfma_f32_16x16x32_bf16 v[94:97], v[170:173], v[214:217], v[94:97]
	v_mfma_f32_16x16x32_bf16 v[86:89], v[156:159], v[222:225], v[86:89]
	v_mfma_f32_16x16x32_bf16 v[78:81], v[170:173], v[222:225], v[78:81]
	s_setprio 0
	s_setprio 1
	v_mfma_f32_16x16x32_bf16 v[114:117], v[174:177], v[190:193], v[114:117]
	v_mfma_f32_16x16x32_bf16 v[106:109], v[182:185], v[190:193], v[106:109]
	v_mfma_f32_16x16x32_bf16 v[98:101], v[174:177], v[202:205], v[98:101]
	v_mfma_f32_16x16x32_bf16 v[90:93], v[182:185], v[202:205], v[90:93]
	v_mfma_f32_16x16x32_bf16 v[82:85], v[174:177], v[210:213], v[82:85]
	v_mfma_f32_16x16x32_bf16 v[74:77], v[182:185], v[210:213], v[74:77]
	v_mfma_f32_16x16x32_bf16 v[70:73], v[174:177], v[218:221], v[70:73]
	v_mfma_f32_16x16x32_bf16 v[66:69], v[182:185], v[218:221], v[66:69]
	v_mfma_f32_16x16x32_bf16 v[114:117], v[178:181], v[194:197], v[114:117]
	v_mfma_f32_16x16x32_bf16 v[106:109], v[186:189], v[194:197], v[106:109]
	v_mfma_f32_16x16x32_bf16 v[98:101], v[178:181], v[206:209], v[98:101]
	v_mfma_f32_16x16x32_bf16 v[90:93], v[186:189], v[206:209], v[90:93]
	v_mfma_f32_16x16x32_bf16 v[82:85], v[178:181], v[214:217], v[82:85]
	v_mfma_f32_16x16x32_bf16 v[74:77], v[186:189], v[214:217], v[74:77]
	v_mfma_f32_16x16x32_bf16 v[70:73], v[178:181], v[222:225], v[70:73]
	v_mfma_f32_16x16x32_bf16 v[66:69], v[186:189], v[222:225], v[66:69]
	s_setprio 0
	s_barrier
	s_mov_b32 m0, s91
	v_lshl_add_u64 v[160:161], v[160:161], 0, s[14:15]
	ds_read_b128 v[190:193], v151 offset:49152
	ds_read_b128 v[194:197], v151 offset:50176
	ds_read_b128 v[202:205], v151 offset:51200
	ds_read_b128 v[206:209], v151 offset:52224
	ds_read_b128 v[210:213], v151 offset:53248
	ds_read_b128 v[214:217], v151 offset:54272
	ds_read_b128 v[218:221], v151 offset:55296
	ds_read_b128 v[222:225], v151 offset:56320
	global_load_lds_dwordx4 v[160:161], off
	v_lshl_add_u64 v[160:161], v[198:199], 0, s[14:15]
	s_mov_b32 m0, s89
	s_nop 0
	global_load_lds_dwordx4 v[160:161], off
	v_lshl_add_u64 v[160:161], s[60:61], 0, v[136:137]
	s_mov_b32 m0, s90
	s_nop 0
	global_load_lds_dwordx4 v[160:161], off
	v_lshl_add_u64 v[160:161], s[60:61], 0, v[132:133]
	s_mov_b32 m0, s44
	s_nop 0
	global_load_lds_dwordx4 v[160:161], off
	v_lshl_add_u64 v[160:161], v[226:227], 0, s[14:15]
	s_mov_b32 m0, s79
	s_nop 0
	global_load_lds_dwordx4 v[160:161], off
	v_lshl_add_u64 v[160:161], v[228:229], 0, s[14:15]
	s_mov_b32 m0, s80
	s_nop 0
	global_load_lds_dwordx4 v[160:161], off
	s_waitcnt vmcnt(8)
	s_waitcnt lgkmcnt(0)
	s_barrier
	s_setprio 1
	s_waitcnt lgkmcnt(0)
	v_mfma_f32_16x16x32_bf16 v[62:65], v[152:155], v[190:193], v[62:65]
	v_mfma_f32_16x16x32_bf16 v[58:61], v[166:169], v[190:193], v[58:61]
	v_mfma_f32_16x16x32_bf16 v[54:57], v[152:155], v[202:205], v[54:57]
	v_mfma_f32_16x16x32_bf16 v[46:49], v[166:169], v[202:205], v[46:49]
	v_mfma_f32_16x16x32_bf16 v[38:41], v[152:155], v[210:213], v[38:41]
	v_mfma_f32_16x16x32_bf16 v[30:33], v[166:169], v[210:213], v[30:33]
	v_mfma_f32_16x16x32_bf16 v[22:25], v[152:155], v[218:221], v[22:25]
	v_mfma_f32_16x16x32_bf16 v[14:17], v[166:169], v[218:221], v[14:17]
	v_mfma_f32_16x16x32_bf16 v[62:65], v[156:159], v[194:197], v[62:65]
	v_mfma_f32_16x16x32_bf16 v[58:61], v[170:173], v[194:197], v[58:61]
	v_mfma_f32_16x16x32_bf16 v[54:57], v[156:159], v[206:209], v[54:57]
	v_mfma_f32_16x16x32_bf16 v[46:49], v[170:173], v[206:209], v[46:49]
	v_mfma_f32_16x16x32_bf16 v[38:41], v[156:159], v[214:217], v[38:41]
	v_mfma_f32_16x16x32_bf16 v[30:33], v[170:173], v[214:217], v[30:33]
	v_mfma_f32_16x16x32_bf16 v[22:25], v[156:159], v[222:225], v[22:25]
	v_mfma_f32_16x16x32_bf16 v[14:17], v[170:173], v[222:225], v[14:17]
	s_setprio 0
	s_setprio 1
	v_mfma_f32_16x16x32_bf16 v[50:53], v[174:177], v[190:193], v[50:53]
	v_mfma_f32_16x16x32_bf16 v[42:45], v[182:185], v[190:193], v[42:45]
	v_mfma_f32_16x16x32_bf16 v[34:37], v[174:177], v[202:205], v[34:37]
	v_mfma_f32_16x16x32_bf16 v[26:29], v[182:185], v[202:205], v[26:29]
	v_mfma_f32_16x16x32_bf16 v[18:21], v[174:177], v[210:213], v[18:21]
	v_mfma_f32_16x16x32_bf16 v[10:13], v[182:185], v[210:213], v[10:13]
	v_mfma_f32_16x16x32_bf16 v[6:9], v[174:177], v[218:221], v[6:9]
	v_mfma_f32_16x16x32_bf16 v[2:5], v[182:185], v[218:221], v[2:5]
	v_mfma_f32_16x16x32_bf16 v[50:53], v[178:181], v[194:197], v[50:53]
	v_mfma_f32_16x16x32_bf16 v[42:45], v[186:189], v[194:197], v[42:45]
	v_mfma_f32_16x16x32_bf16 v[34:37], v[178:181], v[206:209], v[34:37]
	v_mfma_f32_16x16x32_bf16 v[26:29], v[186:189], v[206:209], v[26:29]
	v_mfma_f32_16x16x32_bf16 v[18:21], v[178:181], v[214:217], v[18:21]
	v_mfma_f32_16x16x32_bf16 v[10:13], v[186:189], v[214:217], v[10:13]
	v_mfma_f32_16x16x32_bf16 v[6:9], v[178:181], v[222:225], v[6:9]
	v_mfma_f32_16x16x32_bf16 v[2:5], v[186:189], v[222:225], v[2:5]
	s_setprio 0
	s_barrier
	s_movk_i32 s44, 0x100
	s_andn2_b64 vcc, exec, s[58:59]
	s_mov_b64 s[60:61], -1
	s_mov_b64 s[58:59], 0
	s_cbranch_vccz .LBB0_1701
	s_and_b64 vcc, exec, s[16:17]
	s_cbranch_vccz .LBB0_1704
	s_barrier

.LBB0_1902:
	ds_read_b128 v[148:151], v156
	ds_read_b128 v[166:169], v156 offset:1024
	ds_read_b128 v[170:173], v156 offset:2048
	ds_read_b128 v[174:177], v156 offset:3072
	ds_read_b128 v[178:181], v157
	ds_read_b128 v[182:185], v157 offset:1024
	ds_read_b128 v[186:189], v157 offset:2048
	ds_read_b128 v[190:193], v157 offset:3072
	s_add_i32 s92, s58, 2
	s_add_u32 s36, s56, 0xffd50080
	s_addc_u32 s37, s57, -1
	s_cmp_eq_u32 s89, s58
	s_cselect_b32 s58, s54, s90
	s_cselect_b32 s61, s53, s37
	s_cselect_b32 s60, s52, s36
	s_cselect_b32 s59, s55, s91
	v_lshl_add_u64 v[152:153], s[56:57], 0, v[142:143]
	s_add_i32 m0, s67, 0xc000
	ds_read_b128 v[194:197], v158
	ds_read_b128 v[202:205], v158 offset:1024
	ds_read_b128 v[206:209], v158 offset:2048
	ds_read_b128 v[210:213], v158 offset:3072
	ds_read_b128 v[214:217], v158 offset:4096
	ds_read_b128 v[218:221], v158 offset:5120
	ds_read_b128 v[222:225], v158 offset:6144
	ds_read_b128 v[226:229], v158 offset:7168
	global_load_lds_dwordx4 v[152:153], off
	v_lshl_add_u64 v[152:153], s[56:57], 0, v[144:145]
	s_add_i32 m0, s67, 0xe000
	s_nop 0
	global_load_lds_dwordx4 v[152:153], off
	s_waitcnt vmcnt(8)
	s_waitcnt lgkmcnt(0)
	s_barrier
	s_setprio 1
	s_waitcnt lgkmcnt(0)
	v_mfma_f32_16x16x32_bf16 v[126:129], v[148:151], v[194:197], v[126:129]
	v_mfma_f32_16x16x32_bf16 v[122:125], v[170:173], v[194:197], v[122:125]
	v_mfma_f32_16x16x32_bf16 v[110:113], v[148:151], v[206:209], v[110:113]
	v_mfma_f32_16x16x32_bf16 v[106:109], v[170:173], v[206:209], v[106:109]
	v_mfma_f32_16x16x32_bf16 v[94:97], v[148:151], v[214:217], v[94:97]
	v_mfma_f32_16x16x32_bf16 v[90:93], v[170:173], v[214:217], v[90:93]
	v_mfma_f32_16x16x32_bf16 v[78:81], v[148:151], v[222:225], v[78:81]
	v_mfma_f32_16x16x32_bf16 v[74:77], v[170:173], v[222:225], v[74:77]
	v_mfma_f32_16x16x32_bf16 v[126:129], v[166:169], v[202:205], v[126:129]
	v_mfma_f32_16x16x32_bf16 v[122:125], v[174:177], v[202:205], v[122:125]
	v_mfma_f32_16x16x32_bf16 v[110:113], v[166:169], v[210:213], v[110:113]
	v_mfma_f32_16x16x32_bf16 v[106:109], v[174:177], v[210:213], v[106:109]
	v_mfma_f32_16x16x32_bf16 v[94:97], v[166:169], v[218:221], v[94:97]
	v_mfma_f32_16x16x32_bf16 v[90:93], v[174:177], v[218:221], v[90:93]
	v_mfma_f32_16x16x32_bf16 v[78:81], v[166:169], v[226:229], v[78:81]
	v_mfma_f32_16x16x32_bf16 v[74:77], v[174:177], v[226:229], v[74:77]
	s_setprio 0
	s_setprio 1
	v_mfma_f32_16x16x32_bf16 v[118:121], v[178:181], v[194:197], v[118:121]
	v_mfma_f32_16x16x32_bf16 v[114:117], v[186:189], v[194:197], v[114:117]
	v_mfma_f32_16x16x32_bf16 v[102:105], v[178:181], v[206:209], v[102:105]
	v_mfma_f32_16x16x32_bf16 v[98:101], v[186:189], v[206:209], v[98:101]
	v_mfma_f32_16x16x32_bf16 v[86:89], v[178:181], v[214:217], v[86:89]
	v_mfma_f32_16x16x32_bf16 v[82:85], v[186:189], v[214:217], v[82:85]
	v_mfma_f32_16x16x32_bf16 v[70:73], v[178:181], v[222:225], v[70:73]
	v_mfma_f32_16x16x32_bf16 v[66:69], v[186:189], v[222:225], v[66:69]
	v_mfma_f32_16x16x32_bf16 v[118:121], v[182:185], v[202:205], v[118:121]
	v_mfma_f32_16x16x32_bf16 v[114:117], v[190:193], v[202:205], v[114:117]
	v_mfma_f32_16x16x32_bf16 v[102:105], v[182:185], v[210:213], v[102:105]
	v_mfma_f32_16x16x32_bf16 v[98:101], v[190:193], v[210:213], v[98:101]
	v_mfma_f32_16x16x32_bf16 v[86:89], v[182:185], v[218:221], v[86:89]
	v_mfma_f32_16x16x32_bf16 v[82:85], v[190:193], v[218:221], v[82:85]
	v_mfma_f32_16x16x32_bf16 v[70:73], v[182:185], v[226:229], v[70:73]
	v_mfma_f32_16x16x32_bf16 v[66:69], v[190:193], v[226:229], v[66:69]
	s_setprio 0
	s_barrier
	s_add_i32 s36, s77, s64
	v_lshl_add_u64 v[152:153], s[58:59], 0, v[134:135]
	s_mov_b32 m0, s36
	ds_read_b128 v[194:197], v158 offset:16384
	ds_read_b128 v[202:205], v158 offset:17408
	ds_read_b128 v[206:209], v158 offset:18432
	ds_read_b128 v[210:213], v158 offset:19456
	ds_read_b128 v[214:217], v158 offset:20480
	ds_read_b128 v[218:221], v158 offset:21504
	ds_read_b128 v[222:225], v158 offset:22528
	ds_read_b128 v[226:229], v158 offset:23552
	global_load_lds_dwordx4 v[152:153], off
	s_add_i32 m0, s36, 0x2000
	s_add_u32 s94, s58, 0x2b0000
	v_lshl_add_u64 v[160:161], s[58:59], 0, v[138:139]
	s_addc_u32 s95, s59, 0
	s_add_i32 s36, s78, s64
	global_load_lds_dwordx4 v[160:161], off
	v_lshl_add_u64 v[198:199], s[94:95], 0, v[134:135]
	s_mov_b32 m0, s36
	v_lshl_add_u64 v[230:231], s[60:61], 0, v[136:137]
	global_load_lds_dwordx4 v[198:199], off
	v_lshl_add_u64 v[198:199], s[94:95], 0, v[138:139]
	s_add_i32 m0, s36, 0x2000
	s_nop 0
	global_load_lds_dwordx4 v[198:199], off
	s_waitcnt vmcnt(6)
	s_waitcnt lgkmcnt(0)
	s_barrier
	s_setprio 1
	s_waitcnt lgkmcnt(0)
	v_mfma_f32_16x16x32_bf16 v[62:65], v[148:151], v[194:197], v[62:65]
	v_mfma_f32_16x16x32_bf16 v[58:61], v[170:173], v[194:197], v[58:61]
	v_mfma_f32_16x16x32_bf16 v[46:49], v[148:151], v[206:209], v[46:49]
	v_mfma_f32_16x16x32_bf16 v[42:45], v[170:173], v[206:209], v[42:45]
	v_mfma_f32_16x16x32_bf16 v[30:33], v[148:151], v[214:217], v[30:33]
	v_mfma_f32_16x16x32_bf16 v[26:29], v[170:173], v[214:217], v[26:29]
	v_mfma_f32_16x16x32_bf16 v[14:17], v[148:151], v[222:225], v[14:17]
	v_mfma_f32_16x16x32_bf16 v[10:13], v[170:173], v[222:225], v[10:13]
	v_mfma_f32_16x16x32_bf16 v[62:65], v[166:169], v[202:205], v[62:65]
	v_mfma_f32_16x16x32_bf16 v[58:61], v[174:177], v[202:205], v[58:61]
	v_mfma_f32_16x16x32_bf16 v[46:49], v[166:169], v[210:213], v[46:49]
	v_mfma_f32_16x16x32_bf16 v[42:45], v[174:177], v[210:213], v[42:45]
	v_mfma_f32_16x16x32_bf16 v[30:33], v[166:169], v[218:221], v[30:33]
	v_mfma_f32_16x16x32_bf16 v[26:29], v[174:177], v[218:221], v[26:29]
	v_mfma_f32_16x16x32_bf16 v[14:17], v[166:169], v[226:229], v[14:17]
	v_mfma_f32_16x16x32_bf16 v[10:13], v[174:177], v[226:229], v[10:13]
	s_setprio 0
	s_setprio 1
	v_mfma_f32_16x16x32_bf16 v[54:57], v[178:181], v[194:197], v[54:57]
	v_mfma_f32_16x16x32_bf16 v[50:53], v[186:189], v[194:197], v[50:53]
	v_mfma_f32_16x16x32_bf16 v[38:41], v[178:181], v[206:209], v[38:41]
	v_mfma_f32_16x16x32_bf16 v[34:37], v[186:189], v[206:209], v[34:37]
	v_mfma_f32_16x16x32_bf16 v[22:25], v[178:181], v[214:217], v[22:25]
	v_mfma_f32_16x16x32_bf16 v[18:21], v[186:189], v[214:217], v[18:21]
	v_mfma_f32_16x16x32_bf16 v[6:9], v[178:181], v[222:225], v[6:9]
	v_mfma_f32_16x16x32_bf16 v[2:5], v[186:189], v[222:225], v[2:5]
	v_mfma_f32_16x16x32_bf16 v[54:57], v[182:185], v[202:205], v[54:57]
	v_mfma_f32_16x16x32_bf16 v[50:53], v[190:193], v[202:205], v[50:53]
	v_mfma_f32_16x16x32_bf16 v[38:41], v[182:185], v[210:213], v[38:41]
	v_mfma_f32_16x16x32_bf16 v[34:37], v[190:193], v[210:213], v[34:37]
	v_mfma_f32_16x16x32_bf16 v[22:25], v[182:185], v[218:221], v[22:25]
	v_mfma_f32_16x16x32_bf16 v[18:21], v[190:193], v[218:221], v[18:21]
	v_mfma_f32_16x16x32_bf16 v[6:9], v[182:185], v[226:229], v[6:9]
	v_mfma_f32_16x16x32_bf16 v[2:5], v[190:193], v[226:229], v[2:5]
	s_setprio 0
	s_barrier
	s_add_i32 s36, 0, 0x18000
	v_add_u32_e32 v140, s36, v154
	s_add_i32 s37, 0, 0x1c000
	ds_read_b128 v[148:151], v140
	ds_read_b128 v[166:169], v140 offset:1024
	ds_read_b128 v[170:173], v140 offset:2048
	ds_read_b128 v[174:177], v140 offset:3072
	v_add_u32_e32 v140, s37, v154
	ds_read_b128 v[178:181], v140
	ds_read_b128 v[182:185], v140 offset:1024
	ds_read_b128 v[186:189], v140 offset:2048
	ds_read_b128 v[190:193], v140 offset:3072
	v_lshl_add_u64 v[198:199], s[60:61], 0, v[132:133]
	s_mov_b32 m0, s67
	s_nop 0
	global_load_lds_dwordx4 v[198:199], off
	s_mov_b32 m0, s68
	s_nop 0
	global_load_lds_dwordx4 v[230:231], off
	s_add_u32 s60, s60, 0x2b0000
	s_addc_u32 s61, s61, 0
	s_mov_b32 m0, s69
	v_lshl_add_u64 v[232:233], s[60:61], 0, v[132:133]
	ds_read_b128 v[194:197], v158 offset:32768
	ds_read_b128 v[202:205], v158 offset:33792
	ds_read_b128 v[206:209], v158 offset:34816
	ds_read_b128 v[210:213], v158 offset:35840
	ds_read_b128 v[214:217], v158 offset:36864
	ds_read_b128 v[218:221], v158 offset:37888
	ds_read_b128 v[222:225], v158 offset:38912
	ds_read_b128 v[226:229], v158 offset:39936
	global_load_lds_dwordx4 v[232:233], off
	v_lshl_add_u64 v[232:233], s[60:61], 0, v[136:137]
	s_mov_b32 m0, s70
	s_nop 0
	global_load_lds_dwordx4 v[232:233], off
	s_waitcnt vmcnt(8)
	s_waitcnt lgkmcnt(0)
	s_barrier
	s_setprio 1
	s_waitcnt lgkmcnt(0)
	v_mfma_f32_16x16x32_bf16 v[126:129], v[148:151], v[194:197], v[126:129]
	v_mfma_f32_16x16x32_bf16 v[122:125], v[170:173], v[194:197], v[122:125]
	v_mfma_f32_16x16x32_bf16 v[110:113], v[148:151], v[206:209], v[110:113]
	v_mfma_f32_16x16x32_bf16 v[106:109], v[170:173], v[206:209], v[106:109]
	v_mfma_f32_16x16x32_bf16 v[94:97], v[148:151], v[214:217], v[94:97]
	v_mfma_f32_16x16x32_bf16 v[90:93], v[170:173], v[214:217], v[90:93]
	v_mfma_f32_16x16x32_bf16 v[78:81], v[148:151], v[222:225], v[78:81]
	v_mfma_f32_16x16x32_bf16 v[74:77], v[170:173], v[222:225], v[74:77]
	v_mfma_f32_16x16x32_bf16 v[126:129], v[166:169], v[202:205], v[126:129]
	v_mfma_f32_16x16x32_bf16 v[122:125], v[174:177], v[202:205], v[122:125]
	v_mfma_f32_16x16x32_bf16 v[110:113], v[166:169], v[210:213], v[110:113]
	v_mfma_f32_16x16x32_bf16 v[106:109], v[174:177], v[210:213], v[106:109]
	v_mfma_f32_16x16x32_bf16 v[94:97], v[166:169], v[218:221], v[94:97]
	v_mfma_f32_16x16x32_bf16 v[90:93], v[174:177], v[218:221], v[90:93]
	v_mfma_f32_16x16x32_bf16 v[78:81], v[166:169], v[226:229], v[78:81]
	v_mfma_f32_16x16x32_bf16 v[74:77], v[174:177], v[226:229], v[74:77]
	s_setprio 0
	s_setprio 1
	v_mfma_f32_16x16x32_bf16 v[118:121], v[178:181], v[194:197], v[118:121]
	v_mfma_f32_16x16x32_bf16 v[114:117], v[186:189], v[194:197], v[114:117]
	v_mfma_f32_16x16x32_bf16 v[102:105], v[178:181], v[206:209], v[102:105]
	v_mfma_f32_16x16x32_bf16 v[98:101], v[186:189], v[206:209], v[98:101]
	v_mfma_f32_16x16x32_bf16 v[86:89], v[178:181], v[214:217], v[86:89]
	v_mfma_f32_16x16x32_bf16 v[82:85], v[186:189], v[214:217], v[82:85]
	v_mfma_f32_16x16x32_bf16 v[70:73], v[178:181], v[222:225], v[70:73]
	v_mfma_f32_16x16x32_bf16 v[66:69], v[186:189], v[222:225], v[66:69]
	v_mfma_f32_16x16x32_bf16 v[118:121], v[182:185], v[202:205], v[118:121]
	v_mfma_f32_16x16x32_bf16 v[114:117], v[190:193], v[202:205], v[114:117]
	v_mfma_f32_16x16x32_bf16 v[102:105], v[182:185], v[210:213], v[102:105]
	v_mfma_f32_16x16x32_bf16 v[98:101], v[190:193], v[210:213], v[98:101]
	v_mfma_f32_16x16x32_bf16 v[86:89], v[182:185], v[218:221], v[86:89]
	v_mfma_f32_16x16x32_bf16 v[82:85], v[190:193], v[218:221], v[82:85]
	v_mfma_f32_16x16x32_bf16 v[70:73], v[182:185], v[226:229], v[70:73]
	v_mfma_f32_16x16x32_bf16 v[66:69], v[190:193], v[226:229], v[66:69]
	s_setprio 0
	s_barrier
	s_add_i32 s36, s36, s64
	v_lshl_add_u64 v[152:153], v[152:153], 0, s[20:21]
	s_mov_b32 m0, s36
	ds_read_b128 v[194:197], v158 offset:49152
	ds_read_b128 v[202:205], v158 offset:50176
	ds_read_b128 v[206:209], v158 offset:51200
	ds_read_b128 v[210:213], v158 offset:52224
	ds_read_b128 v[214:217], v158 offset:53248
	ds_read_b128 v[218:221], v158 offset:54272
	ds_read_b128 v[222:225], v158 offset:55296
	ds_read_b128 v[226:229], v158 offset:56320
	global_load_lds_dwordx4 v[152:153], off
	s_add_i32 m0, s36, 0x2000
	s_add_u32 s58, s58, 0x2b0080
	v_lshl_add_u64 v[152:153], v[160:161], 0, s[20:21]
	s_addc_u32 s59, s59, 0
	s_add_i32 s36, s37, s64
	global_load_lds_dwordx4 v[152:153], off
	v_lshl_add_u64 v[152:153], s[58:59], 0, v[134:135]
	s_mov_b32 m0, s36
	s_nop 0
	global_load_lds_dwordx4 v[152:153], off
	v_lshl_add_u64 v[152:153], s[58:59], 0, v[138:139]
	s_add_i32 m0, s36, 0x2000
	s_nop 0
	global_load_lds_dwordx4 v[152:153], off
	v_lshl_add_u64 v[152:153], v[198:199], 0, s[20:21]
	s_mov_b32 m0, s73
	s_nop 0
	global_load_lds_dwordx4 v[152:153], off
	v_lshl_add_u64 v[152:153], v[230:231], 0, s[20:21]
	s_mov_b32 m0, s74
	s_nop 0
	global_load_lds_dwordx4 v[152:153], off
	s_waitcnt vmcnt(8)
	s_waitcnt lgkmcnt(0)
	s_barrier
	s_setprio 1
	s_waitcnt lgkmcnt(0)
	v_mfma_f32_16x16x32_bf16 v[62:65], v[148:151], v[194:197], v[62:65]
	v_mfma_f32_16x16x32_bf16 v[58:61], v[170:173], v[194:197], v[58:61]
	v_mfma_f32_16x16x32_bf16 v[46:49], v[148:151], v[206:209], v[46:49]
	v_mfma_f32_16x16x32_bf16 v[42:45], v[170:173], v[206:209], v[42:45]
	v_mfma_f32_16x16x32_bf16 v[30:33], v[148:151], v[214:217], v[30:33]
	v_mfma_f32_16x16x32_bf16 v[26:29], v[170:173], v[214:217], v[26:29]
	v_mfma_f32_16x16x32_bf16 v[14:17], v[148:151], v[222:225], v[14:17]
	v_mfma_f32_16x16x32_bf16 v[10:13], v[170:173], v[222:225], v[10:13]
	v_mfma_f32_16x16x32_bf16 v[62:65], v[166:169], v[202:205], v[62:65]
	v_mfma_f32_16x16x32_bf16 v[58:61], v[174:177], v[202:205], v[58:61]
	v_mfma_f32_16x16x32_bf16 v[46:49], v[166:169], v[210:213], v[46:49]
	v_mfma_f32_16x16x32_bf16 v[42:45], v[174:177], v[210:213], v[42:45]
	v_mfma_f32_16x16x32_bf16 v[30:33], v[166:169], v[218:221], v[30:33]
	v_mfma_f32_16x16x32_bf16 v[26:29], v[174:177], v[218:221], v[26:29]
	v_mfma_f32_16x16x32_bf16 v[14:17], v[166:169], v[226:229], v[14:17]
	v_mfma_f32_16x16x32_bf16 v[10:13], v[174:177], v[226:229], v[10:13]
	s_setprio 0
	s_setprio 1
	v_mfma_f32_16x16x32_bf16 v[54:57], v[178:181], v[194:197], v[54:57]
	v_mfma_f32_16x16x32_bf16 v[50:53], v[186:189], v[194:197], v[50:53]
	v_mfma_f32_16x16x32_bf16 v[38:41], v[178:181], v[206:209], v[38:41]
	v_mfma_f32_16x16x32_bf16 v[34:37], v[186:189], v[206:209], v[34:37]
	v_mfma_f32_16x16x32_bf16 v[22:25], v[178:181], v[214:217], v[22:25]
	v_mfma_f32_16x16x32_bf16 v[18:21], v[186:189], v[214:217], v[18:21]
	v_mfma_f32_16x16x32_bf16 v[6:9], v[178:181], v[222:225], v[6:9]
	v_mfma_f32_16x16x32_bf16 v[2:5], v[186:189], v[222:225], v[2:5]
	v_mfma_f32_16x16x32_bf16 v[54:57], v[182:185], v[202:205], v[54:57]
	v_mfma_f32_16x16x32_bf16 v[50:53], v[190:193], v[202:205], v[50:53]
	v_mfma_f32_16x16x32_bf16 v[38:41], v[182:185], v[210:213], v[38:41]
	v_mfma_f32_16x16x32_bf16 v[34:37], v[190:193], v[210:213], v[34:37]
	v_mfma_f32_16x16x32_bf16 v[22:25], v[182:185], v[218:221], v[22:25]
	v_mfma_f32_16x16x32_bf16 v[18:21], v[190:193], v[218:221], v[18:21]
	v_mfma_f32_16x16x32_bf16 v[6:9], v[182:185], v[226:229], v[6:9]
	v_mfma_f32_16x16x32_bf16 v[2:5], v[190:193], v[226:229], v[2:5]
	s_setprio 0
	s_barrier
	s_add_u32 s56, s56, 0x100
	s_addc_u32 s57, s57, 0
	s_add_u32 s90, s90, 0x100
	s_addc_u32 s91, s91, 0
	s_cmp_ge_i32 s92, s39
	s_mov_b32 s58, s92
	s_cbranch_scc0 .LBB0_1902
	s_and_b64 vcc, exec, s[24:25]
	s_cbranch_vccz .LBB0_1905

.LBB0_2138:
	ds_read_b128 v[146:149], v157
	ds_read_b128 v[164:167], v157 offset:1024
	ds_read_b128 v[168:171], v157 offset:2048
	ds_read_b128 v[172:175], v157 offset:3072
	ds_read_b128 v[176:179], v158
	ds_read_b128 v[180:183], v158 offset:1024
	ds_read_b128 v[184:187], v158 offset:2048
	ds_read_b128 v[188:191], v158 offset:3072
	s_add_u32 s24, s22, 0xfff00080
	s_addc_u32 s25, s23, -1
	s_cmp_eq_u32 s54, 60
	s_cselect_b32 s35, s15, s25
	s_cselect_b32 s34, s50, s24
	s_cselect_b32 s25, s13, s53
	s_cselect_b32 s24, s51, s52
	v_lshl_add_u64 v[150:151], s[22:23], 0, v[138:139]
	s_add_i32 m0, s21, 0xc000
	ds_read_b128 v[192:195], v159
	ds_read_b128 v[196:199], v159 offset:1024
	ds_read_b128 v[200:203], v159 offset:2048
	ds_read_b128 v[204:207], v159 offset:3072
	ds_read_b128 v[208:211], v159 offset:4096
	ds_read_b128 v[212:215], v159 offset:5120
	ds_read_b128 v[216:219], v159 offset:6144
	ds_read_b128 v[220:223], v159 offset:7168
	global_load_lds_dwordx4 v[150:151], off
	v_lshl_add_u64 v[150:151], s[22:23], 0, v[140:141]
	s_add_i32 m0, s21, 0xe000
	s_nop 0
	global_load_lds_dwordx4 v[150:151], off
	s_waitcnt vmcnt(8)
	s_waitcnt lgkmcnt(0)
	s_barrier
	s_setprio 1
	s_waitcnt lgkmcnt(0)
	v_mfma_f32_16x16x32_bf16 v[126:129], v[146:149], v[192:195], v[126:129]
	v_mfma_f32_16x16x32_bf16 v[122:125], v[168:171], v[192:195], v[122:125]
	v_mfma_f32_16x16x32_bf16 v[110:113], v[146:149], v[200:203], v[110:113]
	v_mfma_f32_16x16x32_bf16 v[106:109], v[168:171], v[200:203], v[106:109]
	v_mfma_f32_16x16x32_bf16 v[94:97], v[146:149], v[208:211], v[94:97]
	v_mfma_f32_16x16x32_bf16 v[90:93], v[168:171], v[208:211], v[90:93]
	v_mfma_f32_16x16x32_bf16 v[78:81], v[146:149], v[216:219], v[78:81]
	v_mfma_f32_16x16x32_bf16 v[74:77], v[168:171], v[216:219], v[74:77]
	v_mfma_f32_16x16x32_bf16 v[126:129], v[164:167], v[196:199], v[126:129]
	v_mfma_f32_16x16x32_bf16 v[122:125], v[172:175], v[196:199], v[122:125]
	v_mfma_f32_16x16x32_bf16 v[110:113], v[164:167], v[204:207], v[110:113]
	v_mfma_f32_16x16x32_bf16 v[106:109], v[172:175], v[204:207], v[106:109]
	v_mfma_f32_16x16x32_bf16 v[94:97], v[164:167], v[212:215], v[94:97]
	v_mfma_f32_16x16x32_bf16 v[90:93], v[172:175], v[212:215], v[90:93]
	v_mfma_f32_16x16x32_bf16 v[78:81], v[164:167], v[220:223], v[78:81]
	v_mfma_f32_16x16x32_bf16 v[74:77], v[172:175], v[220:223], v[74:77]
	s_setprio 0
	s_setprio 1
	v_mfma_f32_16x16x32_bf16 v[118:121], v[176:179], v[192:195], v[118:121]
	v_mfma_f32_16x16x32_bf16 v[114:117], v[184:187], v[192:195], v[114:117]
	v_mfma_f32_16x16x32_bf16 v[102:105], v[176:179], v[200:203], v[102:105]
	v_mfma_f32_16x16x32_bf16 v[98:101], v[184:187], v[200:203], v[98:101]
	v_mfma_f32_16x16x32_bf16 v[86:89], v[176:179], v[208:211], v[86:89]
	v_mfma_f32_16x16x32_bf16 v[82:85], v[184:187], v[208:211], v[82:85]
	v_mfma_f32_16x16x32_bf16 v[70:73], v[176:179], v[216:219], v[70:73]
	v_mfma_f32_16x16x32_bf16 v[66:69], v[184:187], v[216:219], v[66:69]
	v_mfma_f32_16x16x32_bf16 v[118:121], v[180:183], v[196:199], v[118:121]
	v_mfma_f32_16x16x32_bf16 v[114:117], v[188:191], v[196:199], v[114:117]
	v_mfma_f32_16x16x32_bf16 v[102:105], v[180:183], v[204:207], v[102:105]
	v_mfma_f32_16x16x32_bf16 v[98:101], v[188:191], v[204:207], v[98:101]
	v_mfma_f32_16x16x32_bf16 v[86:89], v[180:183], v[212:215], v[86:89]
	v_mfma_f32_16x16x32_bf16 v[82:85], v[188:191], v[212:215], v[82:85]
	v_mfma_f32_16x16x32_bf16 v[70:73], v[180:183], v[220:223], v[70:73]
	v_mfma_f32_16x16x32_bf16 v[66:69], v[188:191], v[220:223], v[66:69]
	s_setprio 0
	s_barrier
	s_add_i32 s55, s47, s27
	v_lshl_add_u64 v[150:151], s[24:25], 0, v[134:135]
	s_mov_b32 m0, s55
	ds_read_b128 v[192:195], v159 offset:16384
	ds_read_b128 v[196:199], v159 offset:17408
	ds_read_b128 v[200:203], v159 offset:18432
	ds_read_b128 v[204:207], v159 offset:19456
	ds_read_b128 v[208:211], v159 offset:20480
	ds_read_b128 v[212:215], v159 offset:21504
	ds_read_b128 v[216:219], v159 offset:22528
	ds_read_b128 v[220:223], v159 offset:23552
	global_load_lds_dwordx4 v[150:151], off
	s_add_i32 m0, s55, 0x2000
	s_add_u32 s56, s24, 0x100000
	v_lshl_add_u64 v[160:161], s[24:25], 0, v[130:131]
	s_addc_u32 s57, s25, 0
	s_add_i32 s55, s48, s27
	global_load_lds_dwordx4 v[160:161], off
	v_lshl_add_u64 v[224:225], s[56:57], 0, v[134:135]
	s_mov_b32 m0, s55
	v_lshl_add_u64 v[226:227], s[34:35], 0, v[132:133]
	global_load_lds_dwordx4 v[224:225], off
	v_lshl_add_u64 v[224:225], s[56:57], 0, v[130:131]
	s_add_i32 m0, s55, 0x2000
	s_nop 0
	global_load_lds_dwordx4 v[224:225], off
	s_waitcnt vmcnt(6)
	s_waitcnt lgkmcnt(0)
	s_barrier
	s_setprio 1
	s_waitcnt lgkmcnt(0)
	v_mfma_f32_16x16x32_bf16 v[62:65], v[146:149], v[192:195], v[62:65]
	v_mfma_f32_16x16x32_bf16 v[58:61], v[168:171], v[192:195], v[58:61]
	v_mfma_f32_16x16x32_bf16 v[46:49], v[146:149], v[200:203], v[46:49]
	v_mfma_f32_16x16x32_bf16 v[42:45], v[168:171], v[200:203], v[42:45]
	v_mfma_f32_16x16x32_bf16 v[30:33], v[146:149], v[208:211], v[30:33]
	v_mfma_f32_16x16x32_bf16 v[26:29], v[168:171], v[208:211], v[26:29]
	v_mfma_f32_16x16x32_bf16 v[14:17], v[146:149], v[216:219], v[14:17]
	v_mfma_f32_16x16x32_bf16 v[10:13], v[168:171], v[216:219], v[10:13]
	v_mfma_f32_16x16x32_bf16 v[62:65], v[164:167], v[196:199], v[62:65]
	v_mfma_f32_16x16x32_bf16 v[58:61], v[172:175], v[196:199], v[58:61]
	v_mfma_f32_16x16x32_bf16 v[46:49], v[164:167], v[204:207], v[46:49]
	v_mfma_f32_16x16x32_bf16 v[42:45], v[172:175], v[204:207], v[42:45]
	v_mfma_f32_16x16x32_bf16 v[30:33], v[164:167], v[212:215], v[30:33]
	v_mfma_f32_16x16x32_bf16 v[26:29], v[172:175], v[212:215], v[26:29]
	v_mfma_f32_16x16x32_bf16 v[14:17], v[164:167], v[220:223], v[14:17]
	v_mfma_f32_16x16x32_bf16 v[10:13], v[172:175], v[220:223], v[10:13]
	s_setprio 0
	s_setprio 1
	v_mfma_f32_16x16x32_bf16 v[54:57], v[176:179], v[192:195], v[54:57]
	v_mfma_f32_16x16x32_bf16 v[50:53], v[184:187], v[192:195], v[50:53]
	v_mfma_f32_16x16x32_bf16 v[38:41], v[176:179], v[200:203], v[38:41]
	v_mfma_f32_16x16x32_bf16 v[34:37], v[184:187], v[200:203], v[34:37]
	v_mfma_f32_16x16x32_bf16 v[22:25], v[176:179], v[208:211], v[22:25]
	v_mfma_f32_16x16x32_bf16 v[18:21], v[184:187], v[208:211], v[18:21]
	v_mfma_f32_16x16x32_bf16 v[6:9], v[176:179], v[216:219], v[6:9]
	v_mfma_f32_16x16x32_bf16 v[2:5], v[184:187], v[216:219], v[2:5]
	v_mfma_f32_16x16x32_bf16 v[54:57], v[180:183], v[196:199], v[54:57]
	v_mfma_f32_16x16x32_bf16 v[50:53], v[188:191], v[196:199], v[50:53]
	v_mfma_f32_16x16x32_bf16 v[38:41], v[180:183], v[204:207], v[38:41]
	v_mfma_f32_16x16x32_bf16 v[34:37], v[188:191], v[204:207], v[34:37]
	v_mfma_f32_16x16x32_bf16 v[22:25], v[180:183], v[212:215], v[22:25]
	v_mfma_f32_16x16x32_bf16 v[18:21], v[188:191], v[212:215], v[18:21]
	v_mfma_f32_16x16x32_bf16 v[6:9], v[180:183], v[220:223], v[6:9]
	v_mfma_f32_16x16x32_bf16 v[2:5], v[188:191], v[220:223], v[2:5]
	s_setprio 0
	s_barrier
	s_add_i32 s55, 0, 0x18000
	v_add_u32_e32 v162, s55, v155
	s_add_i32 s56, 0, 0x1c000
	ds_read_b128 v[146:149], v162
	ds_read_b128 v[164:167], v162 offset:1024
	ds_read_b128 v[168:171], v162 offset:2048
	ds_read_b128 v[172:175], v162 offset:3072
	v_add_u32_e32 v162, s56, v155
	ds_read_b128 v[176:179], v162
	ds_read_b128 v[180:183], v162 offset:1024
	ds_read_b128 v[184:187], v162 offset:2048
	ds_read_b128 v[188:191], v162 offset:3072
	v_lshl_add_u64 v[224:225], s[34:35], 0, v[136:137]
	s_mov_b32 m0, s21
	s_nop 0
	global_load_lds_dwordx4 v[224:225], off
	s_mov_b32 m0, s40
	s_nop 0
	global_load_lds_dwordx4 v[226:227], off
	s_add_u32 s34, s34, 0x100000
	s_addc_u32 s35, s35, 0
	s_mov_b32 m0, s41
	v_lshl_add_u64 v[228:229], s[34:35], 0, v[136:137]
	ds_read_b128 v[192:195], v159 offset:32768
	ds_read_b128 v[196:199], v159 offset:33792
	ds_read_b128 v[200:203], v159 offset:34816
	ds_read_b128 v[204:207], v159 offset:35840
	ds_read_b128 v[208:211], v159 offset:36864
	ds_read_b128 v[212:215], v159 offset:37888
	ds_read_b128 v[216:219], v159 offset:38912
	ds_read_b128 v[220:223], v159 offset:39936
	global_load_lds_dwordx4 v[228:229], off
	v_lshl_add_u64 v[228:229], s[34:35], 0, v[132:133]
	s_mov_b32 m0, s42
	s_nop 0
	global_load_lds_dwordx4 v[228:229], off
	s_waitcnt vmcnt(8)
	s_waitcnt lgkmcnt(0)
	s_barrier
	s_setprio 1
	s_waitcnt lgkmcnt(0)
	v_mfma_f32_16x16x32_bf16 v[126:129], v[146:149], v[192:195], v[126:129]
	v_mfma_f32_16x16x32_bf16 v[122:125], v[168:171], v[192:195], v[122:125]
	v_mfma_f32_16x16x32_bf16 v[110:113], v[146:149], v[200:203], v[110:113]
	v_mfma_f32_16x16x32_bf16 v[106:109], v[168:171], v[200:203], v[106:109]
	v_mfma_f32_16x16x32_bf16 v[94:97], v[146:149], v[208:211], v[94:97]
	v_mfma_f32_16x16x32_bf16 v[90:93], v[168:171], v[208:211], v[90:93]
	v_mfma_f32_16x16x32_bf16 v[78:81], v[146:149], v[216:219], v[78:81]
	v_mfma_f32_16x16x32_bf16 v[74:77], v[168:171], v[216:219], v[74:77]
	v_mfma_f32_16x16x32_bf16 v[126:129], v[164:167], v[196:199], v[126:129]
	v_mfma_f32_16x16x32_bf16 v[122:125], v[172:175], v[196:199], v[122:125]
	v_mfma_f32_16x16x32_bf16 v[110:113], v[164:167], v[204:207], v[110:113]
	v_mfma_f32_16x16x32_bf16 v[106:109], v[172:175], v[204:207], v[106:109]
	v_mfma_f32_16x16x32_bf16 v[94:97], v[164:167], v[212:215], v[94:97]
	v_mfma_f32_16x16x32_bf16 v[90:93], v[172:175], v[212:215], v[90:93]
	v_mfma_f32_16x16x32_bf16 v[78:81], v[164:167], v[220:223], v[78:81]
	v_mfma_f32_16x16x32_bf16 v[74:77], v[172:175], v[220:223], v[74:77]
	s_setprio 0
	s_setprio 1
	v_mfma_f32_16x16x32_bf16 v[118:121], v[176:179], v[192:195], v[118:121]
	v_mfma_f32_16x16x32_bf16 v[114:117], v[184:187], v[192:195], v[114:117]
	v_mfma_f32_16x16x32_bf16 v[102:105], v[176:179], v[200:203], v[102:105]
	v_mfma_f32_16x16x32_bf16 v[98:101], v[184:187], v[200:203], v[98:101]
	v_mfma_f32_16x16x32_bf16 v[86:89], v[176:179], v[208:211], v[86:89]
	v_mfma_f32_16x16x32_bf16 v[82:85], v[184:187], v[208:211], v[82:85]
	v_mfma_f32_16x16x32_bf16 v[70:73], v[176:179], v[216:219], v[70:73]
	v_mfma_f32_16x16x32_bf16 v[66:69], v[184:187], v[216:219], v[66:69]
	v_mfma_f32_16x16x32_bf16 v[118:121], v[180:183], v[196:199], v[118:121]
	v_mfma_f32_16x16x32_bf16 v[114:117], v[188:191], v[196:199], v[114:117]
	v_mfma_f32_16x16x32_bf16 v[102:105], v[180:183], v[204:207], v[102:105]
	v_mfma_f32_16x16x32_bf16 v[98:101], v[188:191], v[204:207], v[98:101]
	v_mfma_f32_16x16x32_bf16 v[86:89], v[180:183], v[212:215], v[86:89]
	v_mfma_f32_16x16x32_bf16 v[82:85], v[188:191], v[212:215], v[82:85]
	v_mfma_f32_16x16x32_bf16 v[70:73], v[180:183], v[220:223], v[70:73]
	v_mfma_f32_16x16x32_bf16 v[66:69], v[188:191], v[220:223], v[66:69]
	s_setprio 0
	s_barrier
	s_add_i32 s34, s55, s27
	v_lshl_add_u64 v[150:151], v[150:151], 0, s[8:9]
	s_mov_b32 m0, s34
	ds_read_b128 v[192:195], v159 offset:49152
	ds_read_b128 v[196:199], v159 offset:50176
	ds_read_b128 v[200:203], v159 offset:51200
	ds_read_b128 v[204:207], v159 offset:52224
	ds_read_b128 v[208:211], v159 offset:53248
	ds_read_b128 v[212:215], v159 offset:54272
	ds_read_b128 v[216:219], v159 offset:55296
	ds_read_b128 v[220:223], v159 offset:56320
	global_load_lds_dwordx4 v[150:151], off
	s_add_i32 m0, s34, 0x2000
	s_add_u32 s24, s24, 0x100080
	v_lshl_add_u64 v[150:151], v[160:161], 0, s[8:9]
	s_addc_u32 s25, s25, 0
	s_add_i32 s34, s56, s27
	global_load_lds_dwordx4 v[150:151], off
	v_lshl_add_u64 v[150:151], s[24:25], 0, v[134:135]
	s_mov_b32 m0, s34
	s_nop 0
	global_load_lds_dwordx4 v[150:151], off
	v_lshl_add_u64 v[150:151], s[24:25], 0, v[130:131]
	s_add_i32 m0, s34, 0x2000
	s_nop 0
	global_load_lds_dwordx4 v[150:151], off
	v_lshl_add_u64 v[150:151], v[224:225], 0, s[8:9]
	s_mov_b32 m0, s44
	s_nop 0
	global_load_lds_dwordx4 v[150:151], off
	v_lshl_add_u64 v[150:151], v[226:227], 0, s[8:9]
	s_mov_b32 m0, s45
	s_nop 0
	global_load_lds_dwordx4 v[150:151], off
	s_waitcnt vmcnt(8)
	s_waitcnt lgkmcnt(0)
	s_barrier
	s_setprio 1
	s_waitcnt lgkmcnt(0)
	v_mfma_f32_16x16x32_bf16 v[62:65], v[146:149], v[192:195], v[62:65]
	v_mfma_f32_16x16x32_bf16 v[58:61], v[168:171], v[192:195], v[58:61]
	v_mfma_f32_16x16x32_bf16 v[46:49], v[146:149], v[200:203], v[46:49]
	v_mfma_f32_16x16x32_bf16 v[42:45], v[168:171], v[200:203], v[42:45]
	v_mfma_f32_16x16x32_bf16 v[30:33], v[146:149], v[208:211], v[30:33]
	v_mfma_f32_16x16x32_bf16 v[26:29], v[168:171], v[208:211], v[26:29]
	v_mfma_f32_16x16x32_bf16 v[14:17], v[146:149], v[216:219], v[14:17]
	v_mfma_f32_16x16x32_bf16 v[10:13], v[168:171], v[216:219], v[10:13]
	v_mfma_f32_16x16x32_bf16 v[62:65], v[164:167], v[196:199], v[62:65]
	v_mfma_f32_16x16x32_bf16 v[58:61], v[172:175], v[196:199], v[58:61]
	v_mfma_f32_16x16x32_bf16 v[46:49], v[164:167], v[204:207], v[46:49]
	v_mfma_f32_16x16x32_bf16 v[42:45], v[172:175], v[204:207], v[42:45]
	v_mfma_f32_16x16x32_bf16 v[30:33], v[164:167], v[212:215], v[30:33]
	v_mfma_f32_16x16x32_bf16 v[26:29], v[172:175], v[212:215], v[26:29]
	v_mfma_f32_16x16x32_bf16 v[14:17], v[164:167], v[220:223], v[14:17]
	v_mfma_f32_16x16x32_bf16 v[10:13], v[172:175], v[220:223], v[10:13]
	s_setprio 0
	s_setprio 1
	v_mfma_f32_16x16x32_bf16 v[54:57], v[176:179], v[192:195], v[54:57]
	v_mfma_f32_16x16x32_bf16 v[50:53], v[184:187], v[192:195], v[50:53]
	v_mfma_f32_16x16x32_bf16 v[38:41], v[176:179], v[200:203], v[38:41]
	v_mfma_f32_16x16x32_bf16 v[34:37], v[184:187], v[200:203], v[34:37]
	v_mfma_f32_16x16x32_bf16 v[22:25], v[176:179], v[208:211], v[22:25]
	v_mfma_f32_16x16x32_bf16 v[18:21], v[184:187], v[208:211], v[18:21]
	v_mfma_f32_16x16x32_bf16 v[6:9], v[176:179], v[216:219], v[6:9]
	v_mfma_f32_16x16x32_bf16 v[2:5], v[184:187], v[216:219], v[2:5]
	v_mfma_f32_16x16x32_bf16 v[54:57], v[180:183], v[196:199], v[54:57]
	v_mfma_f32_16x16x32_bf16 v[50:53], v[188:191], v[196:199], v[50:53]
	v_mfma_f32_16x16x32_bf16 v[38:41], v[180:183], v[204:207], v[38:41]
	v_mfma_f32_16x16x32_bf16 v[34:37], v[188:191], v[204:207], v[34:37]
	v_mfma_f32_16x16x32_bf16 v[22:25], v[180:183], v[212:215], v[22:25]
	v_mfma_f32_16x16x32_bf16 v[18:21], v[188:191], v[212:215], v[18:21]
	v_mfma_f32_16x16x32_bf16 v[6:9], v[180:183], v[220:223], v[6:9]
	v_mfma_f32_16x16x32_bf16 v[2:5], v[188:191], v[220:223], v[2:5]
	s_setprio 0
	s_barrier
	s_add_i32 s54, s54, 2
	s_add_u32 s22, s22, 0x100
	s_addc_u32 s23, s23, 0
	s_add_u32 s52, s52, 0x100
	s_addc_u32 s53, s53, 0
	s_cmp_gt_u32 s54, 61
	s_cbranch_scc0 .LBB0_2138
	s_and_b64 vcc, exec, s[10:11]
	s_cbranch_vccz .LBB0_2141
	s_barrier

.LBB0_2158:
	ds_read_b128 v[146:149], v157
	ds_read_b128 v[164:167], v157 offset:1024
	ds_read_b128 v[168:171], v157 offset:2048
	ds_read_b128 v[172:175], v157 offset:3072
	ds_read_b128 v[176:179], v158
	ds_read_b128 v[180:183], v158 offset:1024
	ds_read_b128 v[184:187], v158 offset:2048
	ds_read_b128 v[188:191], v158 offset:3072
	s_add_u32 s26, s24, 0xfff00080
	s_addc_u32 s27, s25, -1
	s_cmp_eq_u32 s52, 60
	s_cselect_b32 s35, s17, s27
	s_cselect_b32 s34, s48, s26
	s_cselect_b32 s27, s15, s51
	s_cselect_b32 s26, s49, s50
	v_lshl_add_u64 v[150:151], s[24:25], 0, v[138:139]
	s_add_i32 m0, s23, 0xc000
	ds_read_b128 v[192:195], v159
	ds_read_b128 v[196:199], v159 offset:1024
	ds_read_b128 v[200:203], v159 offset:2048
	ds_read_b128 v[204:207], v159 offset:3072
	ds_read_b128 v[208:211], v159 offset:4096
	ds_read_b128 v[212:215], v159 offset:5120
	ds_read_b128 v[216:219], v159 offset:6144
	ds_read_b128 v[220:223], v159 offset:7168
	global_load_lds_dwordx4 v[150:151], off
	v_lshl_add_u64 v[150:151], s[24:25], 0, v[140:141]
	s_add_i32 m0, s23, 0xe000
	s_nop 0
	global_load_lds_dwordx4 v[150:151], off
	s_waitcnt vmcnt(8)
	s_waitcnt lgkmcnt(0)
	s_barrier
	s_setprio 1
	s_waitcnt lgkmcnt(0)
	v_mfma_f32_16x16x32_bf16 v[126:129], v[146:149], v[192:195], v[126:129]
	v_mfma_f32_16x16x32_bf16 v[122:125], v[168:171], v[192:195], v[122:125]
	v_mfma_f32_16x16x32_bf16 v[110:113], v[146:149], v[200:203], v[110:113]
	v_mfma_f32_16x16x32_bf16 v[106:109], v[168:171], v[200:203], v[106:109]
	v_mfma_f32_16x16x32_bf16 v[94:97], v[146:149], v[208:211], v[94:97]
	v_mfma_f32_16x16x32_bf16 v[90:93], v[168:171], v[208:211], v[90:93]
	v_mfma_f32_16x16x32_bf16 v[78:81], v[146:149], v[216:219], v[78:81]
	v_mfma_f32_16x16x32_bf16 v[74:77], v[168:171], v[216:219], v[74:77]
	v_mfma_f32_16x16x32_bf16 v[126:129], v[164:167], v[196:199], v[126:129]
	v_mfma_f32_16x16x32_bf16 v[122:125], v[172:175], v[196:199], v[122:125]
	v_mfma_f32_16x16x32_bf16 v[110:113], v[164:167], v[204:207], v[110:113]
	v_mfma_f32_16x16x32_bf16 v[106:109], v[172:175], v[204:207], v[106:109]
	v_mfma_f32_16x16x32_bf16 v[94:97], v[164:167], v[212:215], v[94:97]
	v_mfma_f32_16x16x32_bf16 v[90:93], v[172:175], v[212:215], v[90:93]
	v_mfma_f32_16x16x32_bf16 v[78:81], v[164:167], v[220:223], v[78:81]
	v_mfma_f32_16x16x32_bf16 v[74:77], v[172:175], v[220:223], v[74:77]
	s_setprio 0
	s_setprio 1
	v_mfma_f32_16x16x32_bf16 v[118:121], v[176:179], v[192:195], v[118:121]
	v_mfma_f32_16x16x32_bf16 v[114:117], v[184:187], v[192:195], v[114:117]
	v_mfma_f32_16x16x32_bf16 v[102:105], v[176:179], v[200:203], v[102:105]
	v_mfma_f32_16x16x32_bf16 v[98:101], v[184:187], v[200:203], v[98:101]
	v_mfma_f32_16x16x32_bf16 v[86:89], v[176:179], v[208:211], v[86:89]
	v_mfma_f32_16x16x32_bf16 v[82:85], v[184:187], v[208:211], v[82:85]
	v_mfma_f32_16x16x32_bf16 v[70:73], v[176:179], v[216:219], v[70:73]
	v_mfma_f32_16x16x32_bf16 v[66:69], v[184:187], v[216:219], v[66:69]
	v_mfma_f32_16x16x32_bf16 v[118:121], v[180:183], v[196:199], v[118:121]
	v_mfma_f32_16x16x32_bf16 v[114:117], v[188:191], v[196:199], v[114:117]
	v_mfma_f32_16x16x32_bf16 v[102:105], v[180:183], v[204:207], v[102:105]
	v_mfma_f32_16x16x32_bf16 v[98:101], v[188:191], v[204:207], v[98:101]
	v_mfma_f32_16x16x32_bf16 v[86:89], v[180:183], v[212:215], v[86:89]
	v_mfma_f32_16x16x32_bf16 v[82:85], v[188:191], v[212:215], v[82:85]
	v_mfma_f32_16x16x32_bf16 v[70:73], v[180:183], v[220:223], v[70:73]
	v_mfma_f32_16x16x32_bf16 v[66:69], v[188:191], v[220:223], v[66:69]
	s_setprio 0
	s_barrier
	s_add_i32 s53, s45, s38
	v_lshl_add_u64 v[150:151], s[26:27], 0, v[132:133]
	s_mov_b32 m0, s53
	ds_read_b128 v[192:195], v159 offset:16384
	ds_read_b128 v[196:199], v159 offset:17408
	ds_read_b128 v[200:203], v159 offset:18432
	ds_read_b128 v[204:207], v159 offset:19456
	ds_read_b128 v[208:211], v159 offset:20480
	ds_read_b128 v[212:215], v159 offset:21504
	ds_read_b128 v[216:219], v159 offset:22528
	ds_read_b128 v[220:223], v159 offset:23552
	global_load_lds_dwordx4 v[150:151], off
	s_add_i32 m0, s53, 0x2000
	s_add_u32 s54, s26, 0x100000
	v_lshl_add_u64 v[160:161], s[26:27], 0, v[134:135]
	s_addc_u32 s55, s27, 0
	s_add_i32 s53, s46, s38
	global_load_lds_dwordx4 v[160:161], off
	v_lshl_add_u64 v[224:225], s[54:55], 0, v[132:133]
	s_mov_b32 m0, s53
	v_lshl_add_u64 v[226:227], s[34:35], 0, v[136:137]
	global_load_lds_dwordx4 v[224:225], off
	v_lshl_add_u64 v[224:225], s[54:55], 0, v[134:135]
	s_add_i32 m0, s53, 0x2000
	s_nop 0
	global_load_lds_dwordx4 v[224:225], off
	s_waitcnt vmcnt(6)
	s_waitcnt lgkmcnt(0)
	s_barrier
	s_setprio 1
	s_waitcnt lgkmcnt(0)
	v_mfma_f32_16x16x32_bf16 v[62:65], v[146:149], v[192:195], v[62:65]
	v_mfma_f32_16x16x32_bf16 v[58:61], v[168:171], v[192:195], v[58:61]
	v_mfma_f32_16x16x32_bf16 v[46:49], v[146:149], v[200:203], v[46:49]
	v_mfma_f32_16x16x32_bf16 v[42:45], v[168:171], v[200:203], v[42:45]
	v_mfma_f32_16x16x32_bf16 v[30:33], v[146:149], v[208:211], v[30:33]
	v_mfma_f32_16x16x32_bf16 v[26:29], v[168:171], v[208:211], v[26:29]
	v_mfma_f32_16x16x32_bf16 v[14:17], v[146:149], v[216:219], v[14:17]
	v_mfma_f32_16x16x32_bf16 v[10:13], v[168:171], v[216:219], v[10:13]
	v_mfma_f32_16x16x32_bf16 v[62:65], v[164:167], v[196:199], v[62:65]
	v_mfma_f32_16x16x32_bf16 v[58:61], v[172:175], v[196:199], v[58:61]
	v_mfma_f32_16x16x32_bf16 v[46:49], v[164:167], v[204:207], v[46:49]
	v_mfma_f32_16x16x32_bf16 v[42:45], v[172:175], v[204:207], v[42:45]
	v_mfma_f32_16x16x32_bf16 v[30:33], v[164:167], v[212:215], v[30:33]
	v_mfma_f32_16x16x32_bf16 v[26:29], v[172:175], v[212:215], v[26:29]
	v_mfma_f32_16x16x32_bf16 v[14:17], v[164:167], v[220:223], v[14:17]
	v_mfma_f32_16x16x32_bf16 v[10:13], v[172:175], v[220:223], v[10:13]
	s_setprio 0
	s_setprio 1
	v_mfma_f32_16x16x32_bf16 v[54:57], v[176:179], v[192:195], v[54:57]
	v_mfma_f32_16x16x32_bf16 v[50:53], v[184:187], v[192:195], v[50:53]
	v_mfma_f32_16x16x32_bf16 v[38:41], v[176:179], v[200:203], v[38:41]
	v_mfma_f32_16x16x32_bf16 v[34:37], v[184:187], v[200:203], v[34:37]
	v_mfma_f32_16x16x32_bf16 v[22:25], v[176:179], v[208:211], v[22:25]
	v_mfma_f32_16x16x32_bf16 v[18:21], v[184:187], v[208:211], v[18:21]
	v_mfma_f32_16x16x32_bf16 v[6:9], v[176:179], v[216:219], v[6:9]
	v_mfma_f32_16x16x32_bf16 v[2:5], v[184:187], v[216:219], v[2:5]
	v_mfma_f32_16x16x32_bf16 v[54:57], v[180:183], v[196:199], v[54:57]
	v_mfma_f32_16x16x32_bf16 v[50:53], v[188:191], v[196:199], v[50:53]
	v_mfma_f32_16x16x32_bf16 v[38:41], v[180:183], v[204:207], v[38:41]
	v_mfma_f32_16x16x32_bf16 v[34:37], v[188:191], v[204:207], v[34:37]
	v_mfma_f32_16x16x32_bf16 v[22:25], v[180:183], v[212:215], v[22:25]
	v_mfma_f32_16x16x32_bf16 v[18:21], v[188:191], v[212:215], v[18:21]
	v_mfma_f32_16x16x32_bf16 v[6:9], v[180:183], v[220:223], v[6:9]
	v_mfma_f32_16x16x32_bf16 v[2:5], v[188:191], v[220:223], v[2:5]
	s_setprio 0
	s_barrier
	s_add_i32 s53, 0, 0x18000
	v_add_u32_e32 v162, s53, v155
	s_add_i32 s54, 0, 0x1c000
	ds_read_b128 v[146:149], v162
	ds_read_b128 v[164:167], v162 offset:1024
	ds_read_b128 v[168:171], v162 offset:2048
	ds_read_b128 v[172:175], v162 offset:3072
	v_add_u32_e32 v162, s54, v155
	ds_read_b128 v[176:179], v162
	ds_read_b128 v[180:183], v162 offset:1024
	ds_read_b128 v[184:187], v162 offset:2048
	ds_read_b128 v[188:191], v162 offset:3072
	v_lshl_add_u64 v[224:225], s[34:35], 0, v[130:131]
	s_mov_b32 m0, s23
	s_nop 0
	global_load_lds_dwordx4 v[224:225], off
	s_mov_b32 m0, s40
	s_nop 0
	global_load_lds_dwordx4 v[226:227], off
	s_add_u32 s34, s34, 0x100000
	s_addc_u32 s35, s35, 0
	s_mov_b32 m0, s41
	v_lshl_add_u64 v[228:229], s[34:35], 0, v[130:131]
	ds_read_b128 v[192:195], v159 offset:32768
	ds_read_b128 v[196:199], v159 offset:33792
	ds_read_b128 v[200:203], v159 offset:34816
	ds_read_b128 v[204:207], v159 offset:35840
	ds_read_b128 v[208:211], v159 offset:36864
	ds_read_b128 v[212:215], v159 offset:37888
	ds_read_b128 v[216:219], v159 offset:38912
	ds_read_b128 v[220:223], v159 offset:39936
	global_load_lds_dwordx4 v[228:229], off
	v_lshl_add_u64 v[228:229], s[34:35], 0, v[136:137]
	s_mov_b32 m0, s42
	s_nop 0
	global_load_lds_dwordx4 v[228:229], off
	s_waitcnt vmcnt(8)
	s_waitcnt lgkmcnt(0)
	s_barrier
	s_setprio 1
	s_waitcnt lgkmcnt(0)
	v_mfma_f32_16x16x32_bf16 v[126:129], v[146:149], v[192:195], v[126:129]
	v_mfma_f32_16x16x32_bf16 v[122:125], v[168:171], v[192:195], v[122:125]
	v_mfma_f32_16x16x32_bf16 v[110:113], v[146:149], v[200:203], v[110:113]
	v_mfma_f32_16x16x32_bf16 v[106:109], v[168:171], v[200:203], v[106:109]
	v_mfma_f32_16x16x32_bf16 v[94:97], v[146:149], v[208:211], v[94:97]
	v_mfma_f32_16x16x32_bf16 v[90:93], v[168:171], v[208:211], v[90:93]
	v_mfma_f32_16x16x32_bf16 v[78:81], v[146:149], v[216:219], v[78:81]
	v_mfma_f32_16x16x32_bf16 v[74:77], v[168:171], v[216:219], v[74:77]
	v_mfma_f32_16x16x32_bf16 v[126:129], v[164:167], v[196:199], v[126:129]
	v_mfma_f32_16x16x32_bf16 v[122:125], v[172:175], v[196:199], v[122:125]
	v_mfma_f32_16x16x32_bf16 v[110:113], v[164:167], v[204:207], v[110:113]
	v_mfma_f32_16x16x32_bf16 v[106:109], v[172:175], v[204:207], v[106:109]
	v_mfma_f32_16x16x32_bf16 v[94:97], v[164:167], v[212:215], v[94:97]
	v_mfma_f32_16x16x32_bf16 v[90:93], v[172:175], v[212:215], v[90:93]
	v_mfma_f32_16x16x32_bf16 v[78:81], v[164:167], v[220:223], v[78:81]
	v_mfma_f32_16x16x32_bf16 v[74:77], v[172:175], v[220:223], v[74:77]
	s_setprio 0
	s_setprio 1
	v_mfma_f32_16x16x32_bf16 v[118:121], v[176:179], v[192:195], v[118:121]
	v_mfma_f32_16x16x32_bf16 v[114:117], v[184:187], v[192:195], v[114:117]
	v_mfma_f32_16x16x32_bf16 v[102:105], v[176:179], v[200:203], v[102:105]
	v_mfma_f32_16x16x32_bf16 v[98:101], v[184:187], v[200:203], v[98:101]
	v_mfma_f32_16x16x32_bf16 v[86:89], v[176:179], v[208:211], v[86:89]
	v_mfma_f32_16x16x32_bf16 v[82:85], v[184:187], v[208:211], v[82:85]
	v_mfma_f32_16x16x32_bf16 v[70:73], v[176:179], v[216:219], v[70:73]
	v_mfma_f32_16x16x32_bf16 v[66:69], v[184:187], v[216:219], v[66:69]
	v_mfma_f32_16x16x32_bf16 v[118:121], v[180:183], v[196:199], v[118:121]
	v_mfma_f32_16x16x32_bf16 v[114:117], v[188:191], v[196:199], v[114:117]
	v_mfma_f32_16x16x32_bf16 v[102:105], v[180:183], v[204:207], v[102:105]
	v_mfma_f32_16x16x32_bf16 v[98:101], v[188:191], v[204:207], v[98:101]
	v_mfma_f32_16x16x32_bf16 v[86:89], v[180:183], v[212:215], v[86:89]
	v_mfma_f32_16x16x32_bf16 v[82:85], v[188:191], v[212:215], v[82:85]
	v_mfma_f32_16x16x32_bf16 v[70:73], v[180:183], v[220:223], v[70:73]
	v_mfma_f32_16x16x32_bf16 v[66:69], v[188:191], v[220:223], v[66:69]
	s_setprio 0
	s_barrier
	s_add_i32 s34, s53, s38
	v_lshl_add_u64 v[150:151], v[150:151], 0, s[10:11]
	s_mov_b32 m0, s34
	ds_read_b128 v[192:195], v159 offset:49152
	ds_read_b128 v[196:199], v159 offset:50176
	ds_read_b128 v[200:203], v159 offset:51200
	ds_read_b128 v[204:207], v159 offset:52224
	ds_read_b128 v[208:211], v159 offset:53248
	ds_read_b128 v[212:215], v159 offset:54272
	ds_read_b128 v[216:219], v159 offset:55296
	ds_read_b128 v[220:223], v159 offset:56320
	global_load_lds_dwordx4 v[150:151], off
	s_add_i32 m0, s34, 0x2000
	s_add_u32 s26, s26, 0x100080
	v_lshl_add_u64 v[150:151], v[160:161], 0, s[10:11]
	s_addc_u32 s27, s27, 0
	s_add_i32 s34, s54, s38
	global_load_lds_dwordx4 v[150:151], off
	v_lshl_add_u64 v[150:151], s[26:27], 0, v[132:133]
	s_mov_b32 m0, s34
	s_nop 0
	global_load_lds_dwordx4 v[150:151], off
	v_lshl_add_u64 v[150:151], s[26:27], 0, v[134:135]
	s_add_i32 m0, s34, 0x2000
	s_nop 0
	global_load_lds_dwordx4 v[150:151], off
	v_lshl_add_u64 v[150:151], v[224:225], 0, s[10:11]
	s_mov_b32 m0, s43
	s_nop 0
	global_load_lds_dwordx4 v[150:151], off
	v_lshl_add_u64 v[150:151], v[226:227], 0, s[10:11]
	s_mov_b32 m0, s44
	s_nop 0
	global_load_lds_dwordx4 v[150:151], off
	s_waitcnt vmcnt(8)
	s_waitcnt lgkmcnt(0)
	s_barrier
	s_setprio 1
	s_waitcnt lgkmcnt(0)
	v_mfma_f32_16x16x32_bf16 v[62:65], v[146:149], v[192:195], v[62:65]
	v_mfma_f32_16x16x32_bf16 v[58:61], v[168:171], v[192:195], v[58:61]
	v_mfma_f32_16x16x32_bf16 v[46:49], v[146:149], v[200:203], v[46:49]
	v_mfma_f32_16x16x32_bf16 v[42:45], v[168:171], v[200:203], v[42:45]
	v_mfma_f32_16x16x32_bf16 v[30:33], v[146:149], v[208:211], v[30:33]
	v_mfma_f32_16x16x32_bf16 v[26:29], v[168:171], v[208:211], v[26:29]
	v_mfma_f32_16x16x32_bf16 v[14:17], v[146:149], v[216:219], v[14:17]
	v_mfma_f32_16x16x32_bf16 v[10:13], v[168:171], v[216:219], v[10:13]
	v_mfma_f32_16x16x32_bf16 v[62:65], v[164:167], v[196:199], v[62:65]
	v_mfma_f32_16x16x32_bf16 v[58:61], v[172:175], v[196:199], v[58:61]
	v_mfma_f32_16x16x32_bf16 v[46:49], v[164:167], v[204:207], v[46:49]
	v_mfma_f32_16x16x32_bf16 v[42:45], v[172:175], v[204:207], v[42:45]
	v_mfma_f32_16x16x32_bf16 v[30:33], v[164:167], v[212:215], v[30:33]
	v_mfma_f32_16x16x32_bf16 v[26:29], v[172:175], v[212:215], v[26:29]
	v_mfma_f32_16x16x32_bf16 v[14:17], v[164:167], v[220:223], v[14:17]
	v_mfma_f32_16x16x32_bf16 v[10:13], v[172:175], v[220:223], v[10:13]
	s_setprio 0
	s_setprio 1
	v_mfma_f32_16x16x32_bf16 v[54:57], v[176:179], v[192:195], v[54:57]
	v_mfma_f32_16x16x32_bf16 v[50:53], v[184:187], v[192:195], v[50:53]
	v_mfma_f32_16x16x32_bf16 v[38:41], v[176:179], v[200:203], v[38:41]
	v_mfma_f32_16x16x32_bf16 v[34:37], v[184:187], v[200:203], v[34:37]
	v_mfma_f32_16x16x32_bf16 v[22:25], v[176:179], v[208:211], v[22:25]
	v_mfma_f32_16x16x32_bf16 v[18:21], v[184:187], v[208:211], v[18:21]
	v_mfma_f32_16x16x32_bf16 v[6:9], v[176:179], v[216:219], v[6:9]
	v_mfma_f32_16x16x32_bf16 v[2:5], v[184:187], v[216:219], v[2:5]
	v_mfma_f32_16x16x32_bf16 v[54:57], v[180:183], v[196:199], v[54:57]
	v_mfma_f32_16x16x32_bf16 v[50:53], v[188:191], v[196:199], v[50:53]
	v_mfma_f32_16x16x32_bf16 v[38:41], v[180:183], v[204:207], v[38:41]
	v_mfma_f32_16x16x32_bf16 v[34:37], v[188:191], v[204:207], v[34:37]
	v_mfma_f32_16x16x32_bf16 v[22:25], v[180:183], v[212:215], v[22:25]
	v_mfma_f32_16x16x32_bf16 v[18:21], v[188:191], v[212:215], v[18:21]
	v_mfma_f32_16x16x32_bf16 v[6:9], v[180:183], v[220:223], v[6:9]
	v_mfma_f32_16x16x32_bf16 v[2:5], v[188:191], v[220:223], v[2:5]
	s_setprio 0
	s_barrier
	s_add_i32 s52, s52, 2
	s_add_u32 s24, s24, 0x100
	s_addc_u32 s25, s25, 0
	s_add_u32 s50, s50, 0x100
	s_addc_u32 s51, s51, 0
	s_cmp_gt_u32 s52, 61
	s_cbranch_scc0 .LBB0_2158
	s_and_b64 vcc, exec, s[12:13]
	s_cbranch_vccz .LBB0_2161
	s_barrier
